# gemv17 (modulation and shift-bias GEMVs) rewritten by hand: all 64 weight-row loads and 17 input loads of a half in flight together instead of one round trip per row
# speedup vs baseline: 1.0372x; 1.0372x over previous
; DI int get_tid() { int t = threadIdx.x; asm volatile("" : "+v"(t)); return t; }
; DI int get_bid() { int t = blockIdx.x; asm volatile("" : "+s"(t)); return t; }
; DI void gemv17(const float* in16, int istride, const float* in1, bool do_silu, const float* W, int ldw, int n0,
;                const float* bvec, float* out, int ostride, char* lds) {
;   const int tid = get_tid(), col = tid & 63, kp = tid >> 6;
;   float* sc = (float*)lds;
;   float* red = (float*)(lds + 34816);
;   float acc[17];
; #pragma unroll
;   for (int j = 0; j < 17; ++j) acc[j] = 0.f;
;   for (int kh = 0; kh < 2; ++kh) {
;     __syncthreads();
;     for (int e = tid; e < 17 * 512; e += NTHREADS) {
;       const int j = e >> 9, k = e & 511;
;       float v = (j < 16) ? in16[(size_t)j * istride + kh * 512 + k] : in1[kh * 512 + k];
;       if (do_silu) v = v / (1.f + expf(-v));
;       sc[e] = v;
;     }
;     __syncthreads();
;     const float* wp = W + (size_t)(kh * 512 + kp * 64) * ldw + n0 + col;
; DI void phase0b(const Params& p, char* lds) {
;     ...
;   for (int it = get_bid(); it < total; it += gridDim.x) {
;     if (it < N_B) {
;       const int l = it / 44, nc = it % 44;
;       gemv17(p.mod + (size_t)l * 17 * 3072, 3072, p.mod + (size_t)(l * 17 + 16) * 3072, false,
;              p.w_in + (size_t)l * DM * INW, INW, nc * 64, nullptr, p.bias + (size_t)l * 17 * INW, INW, lds);
.LBB0_34:
	s_and_b64 vcc, exec, s[2:3]
	s_cbranch_vccz .LBB0_15
	s_mul_i32 s0, s24, 1490
	s_lshr_b32 s0, s0, 16
	s_mul_i32 s2, s0, 44
	s_sub_i32 s2, s24, s2
	s_lshl_b32 s2, s2, 8
	v_readlane_b32 s36, v254, 59
	v_readlane_b32 s37, v254, 60
	v_readlane_b32 s40, v254, 23
	v_readlane_b32 s41, v254, 24
	v_readlane_b32 s44, v254, 61
	v_readlane_b32 s45, v254, 62
	s_nop 3
	s_mul_i32 s3, s0, 0x33000
	s_add_u32 s36, s36, s3
	s_addc_u32 s37, s37, 0
	s_mul_i32 s3, s0, 0xb00000
	s_add_u32 s40, s40, s3
	s_addc_u32 s41, s41, 0
	s_mul_i32 s3, s0, 0x2ec00
	s_add_u32 s44, s44, s3
	s_addc_u32 s45, s45, 0
	s_add_u32 s40, s40, s2
	s_addc_u32 s41, s41, 0
	s_add_u32 s44, s44, s2
	s_addc_u32 s45, s45, 0
	v_lshrrev_b32_e32 v0, 6, v251
	s_nop 0
	v_readfirstlane_b32 s46, v0
	s_nop 3
	s_mul_i32 s3, s46, 720896
	s_add_u32 s40, s40, s3
	s_addc_u32 s41, s41, 0
	v_mov_b32_e32 v66, 0
	v_mov_b32_e32 v67, 0
	v_mov_b32_e32 v68, 0
	v_mov_b32_e32 v69, 0
	v_mov_b32_e32 v70, 0
	v_mov_b32_e32 v71, 0
	v_mov_b32_e32 v72, 0
	v_mov_b32_e32 v73, 0
	v_mov_b32_e32 v74, 0
	v_mov_b32_e32 v75, 0
	v_mov_b32_e32 v76, 0
	v_mov_b32_e32 v77, 0
	v_mov_b32_e32 v78, 0
	v_mov_b32_e32 v79, 0
	v_mov_b32_e32 v80, 0
	v_mov_b32_e32 v81, 0
	v_mov_b32_e32 v89, 0
	s_mov_b32 s47, 0
.Lgv_bias_kh:
	v_and_b32_e32 v111, 63, v251
	v_lshlrev_b32_e32 v111, 2, v111
	v_lshlrev_b32_e32 v112, 2, v251
	s_mov_b64 s[48:49], s[36:37]
	global_load_dword v90, v112, s[48:49]
	s_add_u32 s48, s48, 12288
	s_addc_u32 s49, s49, 0
	global_load_dword v91, v112, s[48:49]
	s_add_u32 s48, s48, 12288
	s_addc_u32 s49, s49, 0
	global_load_dword v92, v112, s[48:49]
	s_add_u32 s48, s48, 12288
	s_addc_u32 s49, s49, 0
	global_load_dword v93, v112, s[48:49]
	s_add_u32 s48, s48, 12288
	s_addc_u32 s49, s49, 0
	global_load_dword v94, v112, s[48:49]
	s_add_u32 s48, s48, 12288
	s_addc_u32 s49, s49, 0
	global_load_dword v95, v112, s[48:49]
	s_add_u32 s48, s48, 12288
	s_addc_u32 s49, s49, 0
	global_load_dword v96, v112, s[48:49]
	s_add_u32 s48, s48, 12288
	s_addc_u32 s49, s49, 0
	global_load_dword v97, v112, s[48:49]
	s_add_u32 s48, s48, 12288
	s_addc_u32 s49, s49, 0
	global_load_dword v98, v112, s[48:49]
	s_add_u32 s48, s48, 12288
	s_addc_u32 s49, s49, 0
	global_load_dword v99, v112, s[48:49]
	s_add_u32 s48, s48, 12288
	s_addc_u32 s49, s49, 0
	global_load_dword v100, v112, s[48:49]
	s_add_u32 s48, s48, 12288
	s_addc_u32 s49, s49, 0
	global_load_dword v101, v112, s[48:49]
	s_add_u32 s48, s48, 12288
	s_addc_u32 s49, s49, 0
	global_load_dword v102, v112, s[48:49]
	s_add_u32 s48, s48, 12288
	s_addc_u32 s49, s49, 0
	global_load_dword v103, v112, s[48:49]
	s_add_u32 s48, s48, 12288
	s_addc_u32 s49, s49, 0
	global_load_dword v108, v112, s[48:49]
	s_add_u32 s48, s48, 12288
	s_addc_u32 s49, s49, 0
	global_load_dword v109, v112, s[48:49]
	s_add_u32 s48, s48, 12288
	s_addc_u32 s49, s49, 0
	global_load_dword v110, v112, s[48:49]
	s_mov_b64 s[50:51], s[40:41]
	global_load_dword v2, v111, s[50:51]
	s_add_u32 s50, s50, 11264
	s_addc_u32 s51, s51, 0
	global_load_dword v3, v111, s[50:51]
	s_add_u32 s50, s50, 11264
	s_addc_u32 s51, s51, 0
	global_load_dword v4, v111, s[50:51]
	s_add_u32 s50, s50, 11264
	s_addc_u32 s51, s51, 0
	global_load_dword v5, v111, s[50:51]
	s_add_u32 s50, s50, 11264
	s_addc_u32 s51, s51, 0
	global_load_dword v6, v111, s[50:51]
	s_add_u32 s50, s50, 11264
	s_addc_u32 s51, s51, 0
	global_load_dword v7, v111, s[50:51]
	s_add_u32 s50, s50, 11264
	s_addc_u32 s51, s51, 0
	global_load_dword v8, v111, s[50:51]
	s_add_u32 s50, s50, 11264
	s_addc_u32 s51, s51, 0
	global_load_dword v9, v111, s[50:51]
	s_add_u32 s50, s50, 11264
	s_addc_u32 s51, s51, 0
	global_load_dword v10, v111, s[50:51]
	s_add_u32 s50, s50, 11264
	s_addc_u32 s51, s51, 0
	global_load_dword v11, v111, s[50:51]
	s_add_u32 s50, s50, 11264
	s_addc_u32 s51, s51, 0
	global_load_dword v12, v111, s[50:51]
	s_add_u32 s50, s50, 11264
	s_addc_u32 s51, s51, 0
	global_load_dword v13, v111, s[50:51]
	s_add_u32 s50, s50, 11264
	s_addc_u32 s51, s51, 0
	global_load_dword v14, v111, s[50:51]
	s_add_u32 s50, s50, 11264
	s_addc_u32 s51, s51, 0
	global_load_dword v15, v111, s[50:51]
	s_add_u32 s50, s50, 11264
	s_addc_u32 s51, s51, 0
	global_load_dword v16, v111, s[50:51]
	s_add_u32 s50, s50, 11264
	s_addc_u32 s51, s51, 0
	global_load_dword v17, v111, s[50:51]
	s_add_u32 s50, s50, 11264
	s_addc_u32 s51, s51, 0
	global_load_dword v18, v111, s[50:51]
	s_add_u32 s50, s50, 11264
	s_addc_u32 s51, s51, 0
	global_load_dword v19, v111, s[50:51]
	s_add_u32 s50, s50, 11264
	s_addc_u32 s51, s51, 0
	global_load_dword v20, v111, s[50:51]
	s_add_u32 s50, s50, 11264
	s_addc_u32 s51, s51, 0
	global_load_dword v21, v111, s[50:51]
	s_add_u32 s50, s50, 11264
	s_addc_u32 s51, s51, 0
	global_load_dword v22, v111, s[50:51]
	s_add_u32 s50, s50, 11264
	s_addc_u32 s51, s51, 0
	global_load_dword v23, v111, s[50:51]
	s_add_u32 s50, s50, 11264
	s_addc_u32 s51, s51, 0
	global_load_dword v24, v111, s[50:51]
	s_add_u32 s50, s50, 11264
	s_addc_u32 s51, s51, 0
	global_load_dword v25, v111, s[50:51]
	s_add_u32 s50, s50, 11264
	s_addc_u32 s51, s51, 0
	global_load_dword v26, v111, s[50:51]
	s_add_u32 s50, s50, 11264
	s_addc_u32 s51, s51, 0
	global_load_dword v27, v111, s[50:51]
	s_add_u32 s50, s50, 11264
	s_addc_u32 s51, s51, 0
	global_load_dword v28, v111, s[50:51]
	s_add_u32 s50, s50, 11264
	s_addc_u32 s51, s51, 0
	global_load_dword v29, v111, s[50:51]
	s_add_u32 s50, s50, 11264
	s_addc_u32 s51, s51, 0
	global_load_dword v30, v111, s[50:51]
	s_add_u32 s50, s50, 11264
	s_addc_u32 s51, s51, 0
	global_load_dword v31, v111, s[50:51]
	s_add_u32 s50, s50, 11264
	s_addc_u32 s51, s51, 0
	global_load_dword v32, v111, s[50:51]
	s_add_u32 s50, s50, 11264
	s_addc_u32 s51, s51, 0
	global_load_dword v33, v111, s[50:51]
	s_add_u32 s50, s50, 11264
	s_addc_u32 s51, s51, 0
	s_waitcnt vmcnt(32)
	s_barrier
; DI void gemv17(const float* in16, int istride, const float* in1, bool do_silu, const float* W, int ldw, int n0,
;                const float* bvec, float* out, int ostride, char* lds) {
;     ...
;     __syncthreads();
;     for (int e = tid; e < 17 * 512; e += NTHREADS) {
;       const int j = e >> 9, k = e & 511;
;       float v = (j < 16) ? in16[(size_t)j * istride + kh * 512 + k] : in1[kh * 512 + k];
;       if (do_silu) v = v / (1.f + expf(-v));
;       sc[e] = v;
;     }
;     __syncthreads();
;     const float* wp = W + (size_t)(kh * 512 + kp * 64) * ldw + n0 + col;
; #pragma unroll 16
;     for (int kk = 0; kk < 64; ++kk) {
;       const float wv = wp[(size_t)kk * ldw];
;       const float* sp = sc + kp * 64 + kk;
; #pragma unroll
;       for (int j = 0; j < 17; ++j) acc[j] += sp[j * 512] * wv;
	ds_write_b32 v112, v90
	ds_write_b32 v112, v91 offset:2048
	ds_write_b32 v112, v92 offset:4096
	ds_write_b32 v112, v93 offset:6144
	ds_write_b32 v112, v94 offset:8192
	ds_write_b32 v112, v95 offset:10240
	ds_write_b32 v112, v96 offset:12288
	ds_write_b32 v112, v97 offset:14336
	ds_write_b32 v112, v98 offset:16384
	ds_write_b32 v112, v99 offset:18432
	ds_write_b32 v112, v100 offset:20480
	ds_write_b32 v112, v101 offset:22528
	ds_write_b32 v112, v102 offset:24576
	ds_write_b32 v112, v103 offset:26624
	ds_write_b32 v112, v108 offset:28672
	ds_write_b32 v112, v109 offset:30720
	ds_write_b32 v112, v110 offset:32768
	global_load_dword v34, v111, s[50:51]
	s_add_u32 s50, s50, 11264
	s_addc_u32 s51, s51, 0
	global_load_dword v35, v111, s[50:51]
	s_add_u32 s50, s50, 11264
	s_addc_u32 s51, s51, 0
	global_load_dword v36, v111, s[50:51]
	s_add_u32 s50, s50, 11264
	s_addc_u32 s51, s51, 0
	global_load_dword v37, v111, s[50:51]
	s_add_u32 s50, s50, 11264
	s_addc_u32 s51, s51, 0
	global_load_dword v38, v111, s[50:51]
	s_add_u32 s50, s50, 11264
	s_addc_u32 s51, s51, 0
	global_load_dword v39, v111, s[50:51]
	s_add_u32 s50, s50, 11264
	s_addc_u32 s51, s51, 0
	global_load_dword v40, v111, s[50:51]
	s_add_u32 s50, s50, 11264
	s_addc_u32 s51, s51, 0
	global_load_dword v41, v111, s[50:51]
	s_add_u32 s50, s50, 11264
	s_addc_u32 s51, s51, 0
	global_load_dword v42, v111, s[50:51]
	s_add_u32 s50, s50, 11264
	s_addc_u32 s51, s51, 0
	global_load_dword v43, v111, s[50:51]
	s_add_u32 s50, s50, 11264
	s_addc_u32 s51, s51, 0
	global_load_dword v44, v111, s[50:51]
	s_add_u32 s50, s50, 11264
	s_addc_u32 s51, s51, 0
	global_load_dword v45, v111, s[50:51]
	s_add_u32 s50, s50, 11264
	s_addc_u32 s51, s51, 0
	global_load_dword v46, v111, s[50:51]
	s_add_u32 s50, s50, 11264
	s_addc_u32 s51, s51, 0
	global_load_dword v47, v111, s[50:51]
	s_add_u32 s50, s50, 11264
	s_addc_u32 s51, s51, 0
	global_load_dword v48, v111, s[50:51]
	s_add_u32 s50, s50, 11264
	s_addc_u32 s51, s51, 0
	global_load_dword v49, v111, s[50:51]
	s_add_u32 s50, s50, 11264
	s_addc_u32 s51, s51, 0
	global_load_dword v50, v111, s[50:51]
	s_add_u32 s50, s50, 11264
	s_addc_u32 s51, s51, 0
	global_load_dword v51, v111, s[50:51]
	s_add_u32 s50, s50, 11264
	s_addc_u32 s51, s51, 0
	global_load_dword v52, v111, s[50:51]
	s_add_u32 s50, s50, 11264
	s_addc_u32 s51, s51, 0
	global_load_dword v53, v111, s[50:51]
	s_add_u32 s50, s50, 11264
	s_addc_u32 s51, s51, 0
	global_load_dword v54, v111, s[50:51]
	s_add_u32 s50, s50, 11264
	s_addc_u32 s51, s51, 0
	global_load_dword v55, v111, s[50:51]
	s_add_u32 s50, s50, 11264
	s_addc_u32 s51, s51, 0
	global_load_dword v56, v111, s[50:51]
	s_add_u32 s50, s50, 11264
	s_addc_u32 s51, s51, 0
	global_load_dword v57, v111, s[50:51]
	s_add_u32 s50, s50, 11264
	s_addc_u32 s51, s51, 0
	global_load_dword v58, v111, s[50:51]
	s_add_u32 s50, s50, 11264
	s_addc_u32 s51, s51, 0
	global_load_dword v59, v111, s[50:51]
	s_add_u32 s50, s50, 11264
	s_addc_u32 s51, s51, 0
	global_load_dword v60, v111, s[50:51]
	s_add_u32 s50, s50, 11264
	s_addc_u32 s51, s51, 0
	global_load_dword v61, v111, s[50:51]
	s_add_u32 s50, s50, 11264
	s_addc_u32 s51, s51, 0
	global_load_dword v62, v111, s[50:51]
	s_add_u32 s50, s50, 11264
	s_addc_u32 s51, s51, 0
	global_load_dword v63, v111, s[50:51]
	s_add_u32 s50, s50, 11264
	s_addc_u32 s51, s51, 0
	global_load_dword v64, v111, s[50:51]
	s_add_u32 s50, s50, 11264
	s_addc_u32 s51, s51, 0
	global_load_dword v65, v111, s[50:51]
	v_lshrrev_b32_e32 v0, 6, v251
	v_lshlrev_b32_e32 v113, 8, v0
	s_waitcnt lgkmcnt(0)
	s_barrier
	ds_read_b128 v[90:93], v113 offset:0
	ds_read_b128 v[94:97], v113 offset:2048
	ds_read_b128 v[98:101], v113 offset:4096
	ds_read_b128 v[108:111], v113 offset:6144
	s_waitcnt vmcnt(60)
	s_waitcnt lgkmcnt(3)
	v_fmac_f32_e32 v66, v90, v2
	v_fmac_f32_e32 v66, v91, v3
	v_fmac_f32_e32 v66, v92, v4
	v_fmac_f32_e32 v66, v93, v5
	ds_read_b128 v[90:93], v113 offset:8192
	s_waitcnt lgkmcnt(3)
	v_fmac_f32_e32 v67, v94, v2
	v_fmac_f32_e32 v67, v95, v3
	v_fmac_f32_e32 v67, v96, v4
	v_fmac_f32_e32 v67, v97, v5
	ds_read_b128 v[94:97], v113 offset:10240
	s_waitcnt lgkmcnt(3)
	v_fmac_f32_e32 v68, v98, v2
	v_fmac_f32_e32 v68, v99, v3
	v_fmac_f32_e32 v68, v100, v4
	v_fmac_f32_e32 v68, v101, v5
	ds_read_b128 v[98:101], v113 offset:12288
	s_waitcnt lgkmcnt(3)
	v_fmac_f32_e32 v69, v108, v2
	v_fmac_f32_e32 v69, v109, v3
	v_fmac_f32_e32 v69, v110, v4
	v_fmac_f32_e32 v69, v111, v5
	ds_read_b128 v[108:111], v113 offset:14336
	s_waitcnt lgkmcnt(3)
	v_fmac_f32_e32 v70, v90, v2
	v_fmac_f32_e32 v70, v91, v3
	v_fmac_f32_e32 v70, v92, v4
	v_fmac_f32_e32 v70, v93, v5
	ds_read_b128 v[90:93], v113 offset:16384
	s_waitcnt lgkmcnt(3)
	v_fmac_f32_e32 v71, v94, v2
	v_fmac_f32_e32 v71, v95, v3
	v_fmac_f32_e32 v71, v96, v4
	v_fmac_f32_e32 v71, v97, v5
	ds_read_b128 v[94:97], v113 offset:18432
	s_waitcnt lgkmcnt(3)
	v_fmac_f32_e32 v72, v98, v2
	v_fmac_f32_e32 v72, v99, v3
	v_fmac_f32_e32 v72, v100, v4
	v_fmac_f32_e32 v72, v101, v5
	ds_read_b128 v[98:101], v113 offset:20480
	s_waitcnt lgkmcnt(3)
	v_fmac_f32_e32 v73, v108, v2
	v_fmac_f32_e32 v73, v109, v3
	v_fmac_f32_e32 v73, v110, v4
	v_fmac_f32_e32 v73, v111, v5
	ds_read_b128 v[108:111], v113 offset:22528
	s_waitcnt lgkmcnt(3)
	v_fmac_f32_e32 v74, v90, v2
	v_fmac_f32_e32 v74, v91, v3
	v_fmac_f32_e32 v74, v92, v4
	v_fmac_f32_e32 v74, v93, v5
	ds_read_b128 v[90:93], v113 offset:24576
	s_waitcnt lgkmcnt(3)
	v_fmac_f32_e32 v75, v94, v2
	v_fmac_f32_e32 v75, v95, v3
	v_fmac_f32_e32 v75, v96, v4
	v_fmac_f32_e32 v75, v97, v5
	ds_read_b128 v[94:97], v113 offset:26624
	s_waitcnt lgkmcnt(3)
; DI void gemv17(const float* in16, int istride, const float* in1, bool do_silu, const float* W, int ldw, int n0,
;                const float* bvec, float* out, int ostride, char* lds) {
;     ...
;     __syncthreads();
;     const float* wp = W + (size_t)(kh * 512 + kp * 64) * ldw + n0 + col;
; #pragma unroll 16
;     for (int kk = 0; kk < 64; ++kk) {
;       const float wv = wp[(size_t)kk * ldw];
;       const float* sp = sc + kp * 64 + kk;
; #pragma unroll
;       for (int j = 0; j < 17; ++j) acc[j] += sp[j * 512] * wv;
	v_fmac_f32_e32 v76, v98, v2
	v_fmac_f32_e32 v76, v99, v3
	v_fmac_f32_e32 v76, v100, v4
	v_fmac_f32_e32 v76, v101, v5
	ds_read_b128 v[98:101], v113 offset:28672
	s_waitcnt lgkmcnt(3)
	v_fmac_f32_e32 v77, v108, v2
	v_fmac_f32_e32 v77, v109, v3
	v_fmac_f32_e32 v77, v110, v4
	v_fmac_f32_e32 v77, v111, v5
	ds_read_b128 v[108:111], v113 offset:30720
	s_waitcnt lgkmcnt(3)
	v_fmac_f32_e32 v78, v90, v2
	v_fmac_f32_e32 v78, v91, v3
	v_fmac_f32_e32 v78, v92, v4
	v_fmac_f32_e32 v78, v93, v5
	ds_read_b128 v[90:93], v113 offset:32768
	s_waitcnt lgkmcnt(3)
	v_fmac_f32_e32 v79, v94, v2
	v_fmac_f32_e32 v79, v95, v3
	v_fmac_f32_e32 v79, v96, v4
	v_fmac_f32_e32 v79, v97, v5
	ds_read_b128 v[94:97], v113 offset:16
	s_waitcnt lgkmcnt(3)
	v_fmac_f32_e32 v80, v98, v2
	v_fmac_f32_e32 v80, v99, v3
	v_fmac_f32_e32 v80, v100, v4
	v_fmac_f32_e32 v80, v101, v5
	ds_read_b128 v[98:101], v113 offset:2064
	s_waitcnt lgkmcnt(3)
	v_fmac_f32_e32 v81, v108, v2
	v_fmac_f32_e32 v81, v109, v3
	v_fmac_f32_e32 v81, v110, v4
	v_fmac_f32_e32 v81, v111, v5
	ds_read_b128 v[108:111], v113 offset:4112
	s_waitcnt lgkmcnt(3)
	v_fmac_f32_e32 v89, v90, v2
	v_fmac_f32_e32 v89, v91, v3
	v_fmac_f32_e32 v89, v92, v4
	v_fmac_f32_e32 v89, v93, v5
	ds_read_b128 v[90:93], v113 offset:6160
	s_waitcnt vmcnt(56)
	s_waitcnt lgkmcnt(3)
	v_fmac_f32_e32 v66, v94, v6
	v_fmac_f32_e32 v66, v95, v7
	v_fmac_f32_e32 v66, v96, v8
	v_fmac_f32_e32 v66, v97, v9
	ds_read_b128 v[94:97], v113 offset:8208
	s_waitcnt lgkmcnt(3)
	v_fmac_f32_e32 v67, v98, v6
	v_fmac_f32_e32 v67, v99, v7
	v_fmac_f32_e32 v67, v100, v8
	v_fmac_f32_e32 v67, v101, v9
	ds_read_b128 v[98:101], v113 offset:10256
	s_waitcnt lgkmcnt(3)
	v_fmac_f32_e32 v68, v108, v6
	v_fmac_f32_e32 v68, v109, v7
	v_fmac_f32_e32 v68, v110, v8
	v_fmac_f32_e32 v68, v111, v9
	ds_read_b128 v[108:111], v113 offset:12304
	s_waitcnt lgkmcnt(3)
	v_fmac_f32_e32 v69, v90, v6
	v_fmac_f32_e32 v69, v91, v7
	v_fmac_f32_e32 v69, v92, v8
	v_fmac_f32_e32 v69, v93, v9
	ds_read_b128 v[90:93], v113 offset:14352
	s_waitcnt lgkmcnt(3)
	v_fmac_f32_e32 v70, v94, v6
	v_fmac_f32_e32 v70, v95, v7
	v_fmac_f32_e32 v70, v96, v8
	v_fmac_f32_e32 v70, v97, v9
	ds_read_b128 v[94:97], v113 offset:16400
	s_waitcnt lgkmcnt(3)
	v_fmac_f32_e32 v71, v98, v6
	v_fmac_f32_e32 v71, v99, v7
	v_fmac_f32_e32 v71, v100, v8
	v_fmac_f32_e32 v71, v101, v9
	ds_read_b128 v[98:101], v113 offset:18448
	s_waitcnt lgkmcnt(3)
	v_fmac_f32_e32 v72, v108, v6
	v_fmac_f32_e32 v72, v109, v7
	v_fmac_f32_e32 v72, v110, v8
	v_fmac_f32_e32 v72, v111, v9
	ds_read_b128 v[108:111], v113 offset:20496
	s_waitcnt lgkmcnt(3)
	v_fmac_f32_e32 v73, v90, v6
	v_fmac_f32_e32 v73, v91, v7
	v_fmac_f32_e32 v73, v92, v8
	v_fmac_f32_e32 v73, v93, v9
	ds_read_b128 v[90:93], v113 offset:22544
	s_waitcnt lgkmcnt(3)
	v_fmac_f32_e32 v74, v94, v6
	v_fmac_f32_e32 v74, v95, v7
	v_fmac_f32_e32 v74, v96, v8
	v_fmac_f32_e32 v74, v97, v9
	ds_read_b128 v[94:97], v113 offset:24592
	s_waitcnt lgkmcnt(3)
	v_fmac_f32_e32 v75, v98, v6
	v_fmac_f32_e32 v75, v99, v7
	v_fmac_f32_e32 v75, v100, v8
	v_fmac_f32_e32 v75, v101, v9
	ds_read_b128 v[98:101], v113 offset:26640
	s_waitcnt lgkmcnt(3)
	v_fmac_f32_e32 v76, v108, v6
	v_fmac_f32_e32 v76, v109, v7
	v_fmac_f32_e32 v76, v110, v8
	v_fmac_f32_e32 v76, v111, v9
	ds_read_b128 v[108:111], v113 offset:28688
	s_waitcnt lgkmcnt(3)
	v_fmac_f32_e32 v77, v90, v6
	v_fmac_f32_e32 v77, v91, v7
	v_fmac_f32_e32 v77, v92, v8
	v_fmac_f32_e32 v77, v93, v9
	ds_read_b128 v[90:93], v113 offset:30736
	s_waitcnt lgkmcnt(3)
	v_fmac_f32_e32 v78, v94, v6
	v_fmac_f32_e32 v78, v95, v7
	v_fmac_f32_e32 v78, v96, v8
	v_fmac_f32_e32 v78, v97, v9
	ds_read_b128 v[94:97], v113 offset:32784
	s_waitcnt lgkmcnt(3)
	v_fmac_f32_e32 v79, v98, v6
	v_fmac_f32_e32 v79, v99, v7
	v_fmac_f32_e32 v79, v100, v8
	v_fmac_f32_e32 v79, v101, v9
	ds_read_b128 v[98:101], v113 offset:32
	s_waitcnt lgkmcnt(3)
	v_fmac_f32_e32 v80, v108, v6
	v_fmac_f32_e32 v80, v109, v7
	v_fmac_f32_e32 v80, v110, v8
	v_fmac_f32_e32 v80, v111, v9
	ds_read_b128 v[108:111], v113 offset:2080
	s_waitcnt lgkmcnt(3)
	v_fmac_f32_e32 v81, v90, v6
	v_fmac_f32_e32 v81, v91, v7
	v_fmac_f32_e32 v81, v92, v8
	v_fmac_f32_e32 v81, v93, v9
	ds_read_b128 v[90:93], v113 offset:4128
	s_waitcnt lgkmcnt(3)
	v_fmac_f32_e32 v89, v94, v6
	v_fmac_f32_e32 v89, v95, v7
	v_fmac_f32_e32 v89, v96, v8
	v_fmac_f32_e32 v89, v97, v9
	ds_read_b128 v[94:97], v113 offset:6176
	s_waitcnt vmcnt(52)
	s_waitcnt lgkmcnt(3)
	v_fmac_f32_e32 v66, v98, v10
	v_fmac_f32_e32 v66, v99, v11
	v_fmac_f32_e32 v66, v100, v12
	v_fmac_f32_e32 v66, v101, v13
	ds_read_b128 v[98:101], v113 offset:8224
	s_waitcnt lgkmcnt(3)
	v_fmac_f32_e32 v67, v108, v10
	v_fmac_f32_e32 v67, v109, v11
	v_fmac_f32_e32 v67, v110, v12
	v_fmac_f32_e32 v67, v111, v13
	ds_read_b128 v[108:111], v113 offset:10272
	s_waitcnt lgkmcnt(3)
	v_fmac_f32_e32 v68, v90, v10
	v_fmac_f32_e32 v68, v91, v11
	v_fmac_f32_e32 v68, v92, v12
	v_fmac_f32_e32 v68, v93, v13
	ds_read_b128 v[90:93], v113 offset:12320
	s_waitcnt lgkmcnt(3)
	v_fmac_f32_e32 v69, v94, v10
	v_fmac_f32_e32 v69, v95, v11
	v_fmac_f32_e32 v69, v96, v12
	v_fmac_f32_e32 v69, v97, v13
	ds_read_b128 v[94:97], v113 offset:14368
	s_waitcnt lgkmcnt(3)
	v_fmac_f32_e32 v70, v98, v10
	v_fmac_f32_e32 v70, v99, v11
	v_fmac_f32_e32 v70, v100, v12
	v_fmac_f32_e32 v70, v101, v13
	ds_read_b128 v[98:101], v113 offset:16416
	s_waitcnt lgkmcnt(3)
	v_fmac_f32_e32 v71, v108, v10
	v_fmac_f32_e32 v71, v109, v11
	v_fmac_f32_e32 v71, v110, v12
	v_fmac_f32_e32 v71, v111, v13
	ds_read_b128 v[108:111], v113 offset:18464
	s_waitcnt lgkmcnt(3)
	v_fmac_f32_e32 v72, v90, v10
	v_fmac_f32_e32 v72, v91, v11
	v_fmac_f32_e32 v72, v92, v12
	v_fmac_f32_e32 v72, v93, v13
	ds_read_b128 v[90:93], v113 offset:20512
	s_waitcnt lgkmcnt(3)
; DI void gemv17(const float* in16, int istride, const float* in1, bool do_silu, const float* W, int ldw, int n0,
;                const float* bvec, float* out, int ostride, char* lds) {
;     ...
;     __syncthreads();
;     const float* wp = W + (size_t)(kh * 512 + kp * 64) * ldw + n0 + col;
; #pragma unroll 16
;     for (int kk = 0; kk < 64; ++kk) {
;       const float wv = wp[(size_t)kk * ldw];
;       const float* sp = sc + kp * 64 + kk;
; #pragma unroll
;       for (int j = 0; j < 17; ++j) acc[j] += sp[j * 512] * wv;
	v_fmac_f32_e32 v73, v94, v10
	v_fmac_f32_e32 v73, v95, v11
	v_fmac_f32_e32 v73, v96, v12
	v_fmac_f32_e32 v73, v97, v13
	ds_read_b128 v[94:97], v113 offset:22560
	s_waitcnt lgkmcnt(3)
	v_fmac_f32_e32 v74, v98, v10
	v_fmac_f32_e32 v74, v99, v11
	v_fmac_f32_e32 v74, v100, v12
	v_fmac_f32_e32 v74, v101, v13
	ds_read_b128 v[98:101], v113 offset:24608
	s_waitcnt lgkmcnt(3)
	v_fmac_f32_e32 v75, v108, v10
	v_fmac_f32_e32 v75, v109, v11
	v_fmac_f32_e32 v75, v110, v12
	v_fmac_f32_e32 v75, v111, v13
	ds_read_b128 v[108:111], v113 offset:26656
	s_waitcnt lgkmcnt(3)
	v_fmac_f32_e32 v76, v90, v10
	v_fmac_f32_e32 v76, v91, v11
	v_fmac_f32_e32 v76, v92, v12
	v_fmac_f32_e32 v76, v93, v13
	ds_read_b128 v[90:93], v113 offset:28704
	s_waitcnt lgkmcnt(3)
	v_fmac_f32_e32 v77, v94, v10
	v_fmac_f32_e32 v77, v95, v11
	v_fmac_f32_e32 v77, v96, v12
	v_fmac_f32_e32 v77, v97, v13
	ds_read_b128 v[94:97], v113 offset:30752
	s_waitcnt lgkmcnt(3)
	v_fmac_f32_e32 v78, v98, v10
	v_fmac_f32_e32 v78, v99, v11
	v_fmac_f32_e32 v78, v100, v12
	v_fmac_f32_e32 v78, v101, v13
	ds_read_b128 v[98:101], v113 offset:32800
	s_waitcnt lgkmcnt(3)
	v_fmac_f32_e32 v79, v108, v10
	v_fmac_f32_e32 v79, v109, v11
	v_fmac_f32_e32 v79, v110, v12
	v_fmac_f32_e32 v79, v111, v13
	ds_read_b128 v[108:111], v113 offset:48
	s_waitcnt lgkmcnt(3)
	v_fmac_f32_e32 v80, v90, v10
	v_fmac_f32_e32 v80, v91, v11
	v_fmac_f32_e32 v80, v92, v12
	v_fmac_f32_e32 v80, v93, v13
	ds_read_b128 v[90:93], v113 offset:2096
	s_waitcnt lgkmcnt(3)
	v_fmac_f32_e32 v81, v94, v10
	v_fmac_f32_e32 v81, v95, v11
	v_fmac_f32_e32 v81, v96, v12
	v_fmac_f32_e32 v81, v97, v13
	ds_read_b128 v[94:97], v113 offset:4144
	s_waitcnt lgkmcnt(3)
	v_fmac_f32_e32 v89, v98, v10
	v_fmac_f32_e32 v89, v99, v11
	v_fmac_f32_e32 v89, v100, v12
	v_fmac_f32_e32 v89, v101, v13
	ds_read_b128 v[98:101], v113 offset:6192
	s_waitcnt vmcnt(48)
	s_waitcnt lgkmcnt(3)
	v_fmac_f32_e32 v66, v108, v14
	v_fmac_f32_e32 v66, v109, v15
	v_fmac_f32_e32 v66, v110, v16
	v_fmac_f32_e32 v66, v111, v17
	ds_read_b128 v[108:111], v113 offset:8240
	s_waitcnt lgkmcnt(3)
	v_fmac_f32_e32 v67, v90, v14
	v_fmac_f32_e32 v67, v91, v15
	v_fmac_f32_e32 v67, v92, v16
	v_fmac_f32_e32 v67, v93, v17
	ds_read_b128 v[90:93], v113 offset:10288
	s_waitcnt lgkmcnt(3)
	v_fmac_f32_e32 v68, v94, v14
	v_fmac_f32_e32 v68, v95, v15
	v_fmac_f32_e32 v68, v96, v16
	v_fmac_f32_e32 v68, v97, v17
	ds_read_b128 v[94:97], v113 offset:12336
	s_waitcnt lgkmcnt(3)
	v_fmac_f32_e32 v69, v98, v14
	v_fmac_f32_e32 v69, v99, v15
	v_fmac_f32_e32 v69, v100, v16
	v_fmac_f32_e32 v69, v101, v17
	ds_read_b128 v[98:101], v113 offset:14384
	s_waitcnt lgkmcnt(3)
	v_fmac_f32_e32 v70, v108, v14
	v_fmac_f32_e32 v70, v109, v15
	v_fmac_f32_e32 v70, v110, v16
	v_fmac_f32_e32 v70, v111, v17
	ds_read_b128 v[108:111], v113 offset:16432
	s_waitcnt lgkmcnt(3)
	v_fmac_f32_e32 v71, v90, v14
	v_fmac_f32_e32 v71, v91, v15
	v_fmac_f32_e32 v71, v92, v16
	v_fmac_f32_e32 v71, v93, v17
	ds_read_b128 v[90:93], v113 offset:18480
	s_waitcnt lgkmcnt(3)
	v_fmac_f32_e32 v72, v94, v14
	v_fmac_f32_e32 v72, v95, v15
	v_fmac_f32_e32 v72, v96, v16
	v_fmac_f32_e32 v72, v97, v17
	ds_read_b128 v[94:97], v113 offset:20528
	s_waitcnt lgkmcnt(3)
	v_fmac_f32_e32 v73, v98, v14
	v_fmac_f32_e32 v73, v99, v15
	v_fmac_f32_e32 v73, v100, v16
	v_fmac_f32_e32 v73, v101, v17
	ds_read_b128 v[98:101], v113 offset:22576
	s_waitcnt lgkmcnt(3)
	v_fmac_f32_e32 v74, v108, v14
	v_fmac_f32_e32 v74, v109, v15
	v_fmac_f32_e32 v74, v110, v16
	v_fmac_f32_e32 v74, v111, v17
	ds_read_b128 v[108:111], v113 offset:24624
	s_waitcnt lgkmcnt(3)
	v_fmac_f32_e32 v75, v90, v14
	v_fmac_f32_e32 v75, v91, v15
	v_fmac_f32_e32 v75, v92, v16
	v_fmac_f32_e32 v75, v93, v17
	ds_read_b128 v[90:93], v113 offset:26672
	s_waitcnt lgkmcnt(3)
	v_fmac_f32_e32 v76, v94, v14
	v_fmac_f32_e32 v76, v95, v15
	v_fmac_f32_e32 v76, v96, v16
	v_fmac_f32_e32 v76, v97, v17
	ds_read_b128 v[94:97], v113 offset:28720
	s_waitcnt lgkmcnt(3)
	v_fmac_f32_e32 v77, v98, v14
	v_fmac_f32_e32 v77, v99, v15
	v_fmac_f32_e32 v77, v100, v16
	v_fmac_f32_e32 v77, v101, v17
	ds_read_b128 v[98:101], v113 offset:30768
	s_waitcnt lgkmcnt(3)
	v_fmac_f32_e32 v78, v108, v14
	v_fmac_f32_e32 v78, v109, v15
	v_fmac_f32_e32 v78, v110, v16
	v_fmac_f32_e32 v78, v111, v17
	ds_read_b128 v[108:111], v113 offset:32816
	s_waitcnt lgkmcnt(3)
	v_fmac_f32_e32 v79, v90, v14
	v_fmac_f32_e32 v79, v91, v15
	v_fmac_f32_e32 v79, v92, v16
	v_fmac_f32_e32 v79, v93, v17
	ds_read_b128 v[90:93], v113 offset:64
	s_waitcnt lgkmcnt(3)
	v_fmac_f32_e32 v80, v94, v14
	v_fmac_f32_e32 v80, v95, v15
	v_fmac_f32_e32 v80, v96, v16
	v_fmac_f32_e32 v80, v97, v17
	ds_read_b128 v[94:97], v113 offset:2112
	s_waitcnt lgkmcnt(3)
	v_fmac_f32_e32 v81, v98, v14
	v_fmac_f32_e32 v81, v99, v15
	v_fmac_f32_e32 v81, v100, v16
	v_fmac_f32_e32 v81, v101, v17
	ds_read_b128 v[98:101], v113 offset:4160
	s_waitcnt lgkmcnt(3)
	v_fmac_f32_e32 v89, v108, v14
	v_fmac_f32_e32 v89, v109, v15
	v_fmac_f32_e32 v89, v110, v16
	v_fmac_f32_e32 v89, v111, v17
	ds_read_b128 v[108:111], v113 offset:6208
	s_waitcnt vmcnt(44)
	s_waitcnt lgkmcnt(3)
	v_fmac_f32_e32 v66, v90, v18
	v_fmac_f32_e32 v66, v91, v19
	v_fmac_f32_e32 v66, v92, v20
	v_fmac_f32_e32 v66, v93, v21
	ds_read_b128 v[90:93], v113 offset:8256
	s_waitcnt lgkmcnt(3)
	v_fmac_f32_e32 v67, v94, v18
	v_fmac_f32_e32 v67, v95, v19
	v_fmac_f32_e32 v67, v96, v20
	v_fmac_f32_e32 v67, v97, v21
	ds_read_b128 v[94:97], v113 offset:10304
	s_waitcnt lgkmcnt(3)
	v_fmac_f32_e32 v68, v98, v18
	v_fmac_f32_e32 v68, v99, v19
	v_fmac_f32_e32 v68, v100, v20
	v_fmac_f32_e32 v68, v101, v21
	ds_read_b128 v[98:101], v113 offset:12352
	s_waitcnt lgkmcnt(3)
; DI void gemv17(const float* in16, int istride, const float* in1, bool do_silu, const float* W, int ldw, int n0,
;                const float* bvec, float* out, int ostride, char* lds) {
;     ...
;     __syncthreads();
;     const float* wp = W + (size_t)(kh * 512 + kp * 64) * ldw + n0 + col;
; #pragma unroll 16
;     for (int kk = 0; kk < 64; ++kk) {
;       const float wv = wp[(size_t)kk * ldw];
;       const float* sp = sc + kp * 64 + kk;
; #pragma unroll
;       for (int j = 0; j < 17; ++j) acc[j] += sp[j * 512] * wv;
	v_fmac_f32_e32 v69, v108, v18
	v_fmac_f32_e32 v69, v109, v19
	v_fmac_f32_e32 v69, v110, v20
	v_fmac_f32_e32 v69, v111, v21
	ds_read_b128 v[108:111], v113 offset:14400
	s_waitcnt lgkmcnt(3)
	v_fmac_f32_e32 v70, v90, v18
	v_fmac_f32_e32 v70, v91, v19
	v_fmac_f32_e32 v70, v92, v20
	v_fmac_f32_e32 v70, v93, v21
	ds_read_b128 v[90:93], v113 offset:16448
	s_waitcnt lgkmcnt(3)
	v_fmac_f32_e32 v71, v94, v18
	v_fmac_f32_e32 v71, v95, v19
	v_fmac_f32_e32 v71, v96, v20
	v_fmac_f32_e32 v71, v97, v21
	ds_read_b128 v[94:97], v113 offset:18496
	s_waitcnt lgkmcnt(3)
	v_fmac_f32_e32 v72, v98, v18
	v_fmac_f32_e32 v72, v99, v19
	v_fmac_f32_e32 v72, v100, v20
	v_fmac_f32_e32 v72, v101, v21
	ds_read_b128 v[98:101], v113 offset:20544
	s_waitcnt lgkmcnt(3)
	v_fmac_f32_e32 v73, v108, v18
	v_fmac_f32_e32 v73, v109, v19
	v_fmac_f32_e32 v73, v110, v20
	v_fmac_f32_e32 v73, v111, v21
	ds_read_b128 v[108:111], v113 offset:22592
	s_waitcnt lgkmcnt(3)
	v_fmac_f32_e32 v74, v90, v18
	v_fmac_f32_e32 v74, v91, v19
	v_fmac_f32_e32 v74, v92, v20
	v_fmac_f32_e32 v74, v93, v21
	ds_read_b128 v[90:93], v113 offset:24640
	s_waitcnt lgkmcnt(3)
	v_fmac_f32_e32 v75, v94, v18
	v_fmac_f32_e32 v75, v95, v19
	v_fmac_f32_e32 v75, v96, v20
	v_fmac_f32_e32 v75, v97, v21
	ds_read_b128 v[94:97], v113 offset:26688
	s_waitcnt lgkmcnt(3)
	v_fmac_f32_e32 v76, v98, v18
	v_fmac_f32_e32 v76, v99, v19
	v_fmac_f32_e32 v76, v100, v20
	v_fmac_f32_e32 v76, v101, v21
	ds_read_b128 v[98:101], v113 offset:28736
	s_waitcnt lgkmcnt(3)
	v_fmac_f32_e32 v77, v108, v18
	v_fmac_f32_e32 v77, v109, v19
	v_fmac_f32_e32 v77, v110, v20
	v_fmac_f32_e32 v77, v111, v21
	ds_read_b128 v[108:111], v113 offset:30784
	s_waitcnt lgkmcnt(3)
	v_fmac_f32_e32 v78, v90, v18
	v_fmac_f32_e32 v78, v91, v19
	v_fmac_f32_e32 v78, v92, v20
	v_fmac_f32_e32 v78, v93, v21
	ds_read_b128 v[90:93], v113 offset:32832
	s_waitcnt lgkmcnt(3)
	v_fmac_f32_e32 v79, v94, v18
	v_fmac_f32_e32 v79, v95, v19
	v_fmac_f32_e32 v79, v96, v20
	v_fmac_f32_e32 v79, v97, v21
	ds_read_b128 v[94:97], v113 offset:80
	s_waitcnt lgkmcnt(3)
	v_fmac_f32_e32 v80, v98, v18
	v_fmac_f32_e32 v80, v99, v19
	v_fmac_f32_e32 v80, v100, v20
	v_fmac_f32_e32 v80, v101, v21
	ds_read_b128 v[98:101], v113 offset:2128
	s_waitcnt lgkmcnt(3)
	v_fmac_f32_e32 v81, v108, v18
	v_fmac_f32_e32 v81, v109, v19
	v_fmac_f32_e32 v81, v110, v20
	v_fmac_f32_e32 v81, v111, v21
	ds_read_b128 v[108:111], v113 offset:4176
	s_waitcnt lgkmcnt(3)
	v_fmac_f32_e32 v89, v90, v18
	v_fmac_f32_e32 v89, v91, v19
	v_fmac_f32_e32 v89, v92, v20
	v_fmac_f32_e32 v89, v93, v21
	ds_read_b128 v[90:93], v113 offset:6224
	s_waitcnt vmcnt(40)
	s_waitcnt lgkmcnt(3)
	v_fmac_f32_e32 v66, v94, v22
	v_fmac_f32_e32 v66, v95, v23
	v_fmac_f32_e32 v66, v96, v24
	v_fmac_f32_e32 v66, v97, v25
	ds_read_b128 v[94:97], v113 offset:8272
	s_waitcnt lgkmcnt(3)
	v_fmac_f32_e32 v67, v98, v22
	v_fmac_f32_e32 v67, v99, v23
	v_fmac_f32_e32 v67, v100, v24
	v_fmac_f32_e32 v67, v101, v25
	ds_read_b128 v[98:101], v113 offset:10320
	s_waitcnt lgkmcnt(3)
	v_fmac_f32_e32 v68, v108, v22
	v_fmac_f32_e32 v68, v109, v23
	v_fmac_f32_e32 v68, v110, v24
	v_fmac_f32_e32 v68, v111, v25
	ds_read_b128 v[108:111], v113 offset:12368
	s_waitcnt lgkmcnt(3)
	v_fmac_f32_e32 v69, v90, v22
	v_fmac_f32_e32 v69, v91, v23
	v_fmac_f32_e32 v69, v92, v24
	v_fmac_f32_e32 v69, v93, v25
	ds_read_b128 v[90:93], v113 offset:14416
	s_waitcnt lgkmcnt(3)
	v_fmac_f32_e32 v70, v94, v22
	v_fmac_f32_e32 v70, v95, v23
	v_fmac_f32_e32 v70, v96, v24
	v_fmac_f32_e32 v70, v97, v25
	ds_read_b128 v[94:97], v113 offset:16464
	s_waitcnt lgkmcnt(3)
	v_fmac_f32_e32 v71, v98, v22
	v_fmac_f32_e32 v71, v99, v23
	v_fmac_f32_e32 v71, v100, v24
	v_fmac_f32_e32 v71, v101, v25
	ds_read_b128 v[98:101], v113 offset:18512
	s_waitcnt lgkmcnt(3)
	v_fmac_f32_e32 v72, v108, v22
	v_fmac_f32_e32 v72, v109, v23
	v_fmac_f32_e32 v72, v110, v24
	v_fmac_f32_e32 v72, v111, v25
	ds_read_b128 v[108:111], v113 offset:20560
	s_waitcnt lgkmcnt(3)
	v_fmac_f32_e32 v73, v90, v22
	v_fmac_f32_e32 v73, v91, v23
	v_fmac_f32_e32 v73, v92, v24
	v_fmac_f32_e32 v73, v93, v25
	ds_read_b128 v[90:93], v113 offset:22608
	s_waitcnt lgkmcnt(3)
	v_fmac_f32_e32 v74, v94, v22
	v_fmac_f32_e32 v74, v95, v23
	v_fmac_f32_e32 v74, v96, v24
	v_fmac_f32_e32 v74, v97, v25
	ds_read_b128 v[94:97], v113 offset:24656
	s_waitcnt lgkmcnt(3)
	v_fmac_f32_e32 v75, v98, v22
	v_fmac_f32_e32 v75, v99, v23
	v_fmac_f32_e32 v75, v100, v24
	v_fmac_f32_e32 v75, v101, v25
	ds_read_b128 v[98:101], v113 offset:26704
	s_waitcnt lgkmcnt(3)
	v_fmac_f32_e32 v76, v108, v22
	v_fmac_f32_e32 v76, v109, v23
	v_fmac_f32_e32 v76, v110, v24
	v_fmac_f32_e32 v76, v111, v25
	ds_read_b128 v[108:111], v113 offset:28752
	s_waitcnt lgkmcnt(3)
	v_fmac_f32_e32 v77, v90, v22
	v_fmac_f32_e32 v77, v91, v23
	v_fmac_f32_e32 v77, v92, v24
	v_fmac_f32_e32 v77, v93, v25
	ds_read_b128 v[90:93], v113 offset:30800
	s_waitcnt lgkmcnt(3)
	v_fmac_f32_e32 v78, v94, v22
	v_fmac_f32_e32 v78, v95, v23
	v_fmac_f32_e32 v78, v96, v24
	v_fmac_f32_e32 v78, v97, v25
	ds_read_b128 v[94:97], v113 offset:32848
	s_waitcnt lgkmcnt(3)
	v_fmac_f32_e32 v79, v98, v22
	v_fmac_f32_e32 v79, v99, v23
	v_fmac_f32_e32 v79, v100, v24
	v_fmac_f32_e32 v79, v101, v25
	ds_read_b128 v[98:101], v113 offset:96
	s_waitcnt lgkmcnt(3)
	v_fmac_f32_e32 v80, v108, v22
	v_fmac_f32_e32 v80, v109, v23
	v_fmac_f32_e32 v80, v110, v24
	v_fmac_f32_e32 v80, v111, v25
	ds_read_b128 v[108:111], v113 offset:2144
	s_waitcnt lgkmcnt(3)
	v_fmac_f32_e32 v81, v90, v22
	v_fmac_f32_e32 v81, v91, v23
	v_fmac_f32_e32 v81, v92, v24
	v_fmac_f32_e32 v81, v93, v25
	ds_read_b128 v[90:93], v113 offset:4192
	s_waitcnt lgkmcnt(3)
; DI void gemv17(const float* in16, int istride, const float* in1, bool do_silu, const float* W, int ldw, int n0,
;                const float* bvec, float* out, int ostride, char* lds) {
;     ...
;     __syncthreads();
;     const float* wp = W + (size_t)(kh * 512 + kp * 64) * ldw + n0 + col;
; #pragma unroll 16
;     for (int kk = 0; kk < 64; ++kk) {
;       const float wv = wp[(size_t)kk * ldw];
;       const float* sp = sc + kp * 64 + kk;
; #pragma unroll
;       for (int j = 0; j < 17; ++j) acc[j] += sp[j * 512] * wv;
	v_fmac_f32_e32 v89, v94, v22
	v_fmac_f32_e32 v89, v95, v23
	v_fmac_f32_e32 v89, v96, v24
	v_fmac_f32_e32 v89, v97, v25
	ds_read_b128 v[94:97], v113 offset:6240
	s_waitcnt vmcnt(36)
	s_waitcnt lgkmcnt(3)
	v_fmac_f32_e32 v66, v98, v26
	v_fmac_f32_e32 v66, v99, v27
	v_fmac_f32_e32 v66, v100, v28
	v_fmac_f32_e32 v66, v101, v29
	ds_read_b128 v[98:101], v113 offset:8288
	s_waitcnt lgkmcnt(3)
	v_fmac_f32_e32 v67, v108, v26
	v_fmac_f32_e32 v67, v109, v27
	v_fmac_f32_e32 v67, v110, v28
	v_fmac_f32_e32 v67, v111, v29
	ds_read_b128 v[108:111], v113 offset:10336
	s_waitcnt lgkmcnt(3)
	v_fmac_f32_e32 v68, v90, v26
	v_fmac_f32_e32 v68, v91, v27
	v_fmac_f32_e32 v68, v92, v28
	v_fmac_f32_e32 v68, v93, v29
	ds_read_b128 v[90:93], v113 offset:12384
	s_waitcnt lgkmcnt(3)
	v_fmac_f32_e32 v69, v94, v26
	v_fmac_f32_e32 v69, v95, v27
	v_fmac_f32_e32 v69, v96, v28
	v_fmac_f32_e32 v69, v97, v29
	ds_read_b128 v[94:97], v113 offset:14432
	s_waitcnt lgkmcnt(3)
	v_fmac_f32_e32 v70, v98, v26
	v_fmac_f32_e32 v70, v99, v27
	v_fmac_f32_e32 v70, v100, v28
	v_fmac_f32_e32 v70, v101, v29
	ds_read_b128 v[98:101], v113 offset:16480
	s_waitcnt lgkmcnt(3)
	v_fmac_f32_e32 v71, v108, v26
	v_fmac_f32_e32 v71, v109, v27
	v_fmac_f32_e32 v71, v110, v28
	v_fmac_f32_e32 v71, v111, v29
	ds_read_b128 v[108:111], v113 offset:18528
	s_waitcnt lgkmcnt(3)
	v_fmac_f32_e32 v72, v90, v26
	v_fmac_f32_e32 v72, v91, v27
	v_fmac_f32_e32 v72, v92, v28
	v_fmac_f32_e32 v72, v93, v29
	ds_read_b128 v[90:93], v113 offset:20576
	s_waitcnt lgkmcnt(3)
	v_fmac_f32_e32 v73, v94, v26
	v_fmac_f32_e32 v73, v95, v27
	v_fmac_f32_e32 v73, v96, v28
	v_fmac_f32_e32 v73, v97, v29
	ds_read_b128 v[94:97], v113 offset:22624
	s_waitcnt lgkmcnt(3)
	v_fmac_f32_e32 v74, v98, v26
	v_fmac_f32_e32 v74, v99, v27
	v_fmac_f32_e32 v74, v100, v28
	v_fmac_f32_e32 v74, v101, v29
	ds_read_b128 v[98:101], v113 offset:24672
	s_waitcnt lgkmcnt(3)
	v_fmac_f32_e32 v75, v108, v26
	v_fmac_f32_e32 v75, v109, v27
	v_fmac_f32_e32 v75, v110, v28
	v_fmac_f32_e32 v75, v111, v29
	ds_read_b128 v[108:111], v113 offset:26720
	s_waitcnt lgkmcnt(3)
	v_fmac_f32_e32 v76, v90, v26
	v_fmac_f32_e32 v76, v91, v27
	v_fmac_f32_e32 v76, v92, v28
	v_fmac_f32_e32 v76, v93, v29
	ds_read_b128 v[90:93], v113 offset:28768
	s_waitcnt lgkmcnt(3)
	v_fmac_f32_e32 v77, v94, v26
	v_fmac_f32_e32 v77, v95, v27
	v_fmac_f32_e32 v77, v96, v28
	v_fmac_f32_e32 v77, v97, v29
	ds_read_b128 v[94:97], v113 offset:30816
	s_waitcnt lgkmcnt(3)
	v_fmac_f32_e32 v78, v98, v26
	v_fmac_f32_e32 v78, v99, v27
	v_fmac_f32_e32 v78, v100, v28
	v_fmac_f32_e32 v78, v101, v29
	ds_read_b128 v[98:101], v113 offset:32864
	s_waitcnt lgkmcnt(3)
	v_fmac_f32_e32 v79, v108, v26
	v_fmac_f32_e32 v79, v109, v27
	v_fmac_f32_e32 v79, v110, v28
	v_fmac_f32_e32 v79, v111, v29
	ds_read_b128 v[108:111], v113 offset:112
	s_waitcnt lgkmcnt(3)
	v_fmac_f32_e32 v80, v90, v26
	v_fmac_f32_e32 v80, v91, v27
	v_fmac_f32_e32 v80, v92, v28
	v_fmac_f32_e32 v80, v93, v29
	ds_read_b128 v[90:93], v113 offset:2160
	s_waitcnt lgkmcnt(3)
	v_fmac_f32_e32 v81, v94, v26
	v_fmac_f32_e32 v81, v95, v27
	v_fmac_f32_e32 v81, v96, v28
	v_fmac_f32_e32 v81, v97, v29
	ds_read_b128 v[94:97], v113 offset:4208
	s_waitcnt lgkmcnt(3)
	v_fmac_f32_e32 v89, v98, v26
	v_fmac_f32_e32 v89, v99, v27
	v_fmac_f32_e32 v89, v100, v28
	v_fmac_f32_e32 v89, v101, v29
	ds_read_b128 v[98:101], v113 offset:6256
	s_waitcnt vmcnt(32)
	s_waitcnt lgkmcnt(3)
	v_fmac_f32_e32 v66, v108, v30
	v_fmac_f32_e32 v66, v109, v31
	v_fmac_f32_e32 v66, v110, v32
	v_fmac_f32_e32 v66, v111, v33
	ds_read_b128 v[108:111], v113 offset:8304
	s_waitcnt lgkmcnt(3)
	v_fmac_f32_e32 v67, v90, v30
	v_fmac_f32_e32 v67, v91, v31
	v_fmac_f32_e32 v67, v92, v32
	v_fmac_f32_e32 v67, v93, v33
	ds_read_b128 v[90:93], v113 offset:10352
	s_waitcnt lgkmcnt(3)
	v_fmac_f32_e32 v68, v94, v30
	v_fmac_f32_e32 v68, v95, v31
	v_fmac_f32_e32 v68, v96, v32
	v_fmac_f32_e32 v68, v97, v33
	ds_read_b128 v[94:97], v113 offset:12400
	s_waitcnt lgkmcnt(3)
	v_fmac_f32_e32 v69, v98, v30
	v_fmac_f32_e32 v69, v99, v31
	v_fmac_f32_e32 v69, v100, v32
	v_fmac_f32_e32 v69, v101, v33
	ds_read_b128 v[98:101], v113 offset:14448
	s_waitcnt lgkmcnt(3)
	v_fmac_f32_e32 v70, v108, v30
	v_fmac_f32_e32 v70, v109, v31
	v_fmac_f32_e32 v70, v110, v32
	v_fmac_f32_e32 v70, v111, v33
	ds_read_b128 v[108:111], v113 offset:16496
	s_waitcnt lgkmcnt(3)
	v_fmac_f32_e32 v71, v90, v30
	v_fmac_f32_e32 v71, v91, v31
	v_fmac_f32_e32 v71, v92, v32
	v_fmac_f32_e32 v71, v93, v33
	ds_read_b128 v[90:93], v113 offset:18544
	s_waitcnt lgkmcnt(3)
	v_fmac_f32_e32 v72, v94, v30
	v_fmac_f32_e32 v72, v95, v31
	v_fmac_f32_e32 v72, v96, v32
	v_fmac_f32_e32 v72, v97, v33
	ds_read_b128 v[94:97], v113 offset:20592
	s_waitcnt lgkmcnt(3)
	v_fmac_f32_e32 v73, v98, v30
	v_fmac_f32_e32 v73, v99, v31
	v_fmac_f32_e32 v73, v100, v32
	v_fmac_f32_e32 v73, v101, v33
	ds_read_b128 v[98:101], v113 offset:22640
	s_waitcnt lgkmcnt(3)
	v_fmac_f32_e32 v74, v108, v30
	v_fmac_f32_e32 v74, v109, v31
	v_fmac_f32_e32 v74, v110, v32
	v_fmac_f32_e32 v74, v111, v33
	ds_read_b128 v[108:111], v113 offset:24688
	s_waitcnt lgkmcnt(3)
	v_fmac_f32_e32 v75, v90, v30
	v_fmac_f32_e32 v75, v91, v31
	v_fmac_f32_e32 v75, v92, v32
	v_fmac_f32_e32 v75, v93, v33
	ds_read_b128 v[90:93], v113 offset:26736
	s_waitcnt lgkmcnt(3)
	v_fmac_f32_e32 v76, v94, v30
	v_fmac_f32_e32 v76, v95, v31
	v_fmac_f32_e32 v76, v96, v32
	v_fmac_f32_e32 v76, v97, v33
	ds_read_b128 v[94:97], v113 offset:28784
	s_waitcnt lgkmcnt(3)
	v_fmac_f32_e32 v77, v98, v30
	v_fmac_f32_e32 v77, v99, v31
	v_fmac_f32_e32 v77, v100, v32
	v_fmac_f32_e32 v77, v101, v33
	ds_read_b128 v[98:101], v113 offset:30832
	s_waitcnt lgkmcnt(3)
; DI void gemv17(const float* in16, int istride, const float* in1, bool do_silu, const float* W, int ldw, int n0,
;                const float* bvec, float* out, int ostride, char* lds) {
;     ...
;     __syncthreads();
;     const float* wp = W + (size_t)(kh * 512 + kp * 64) * ldw + n0 + col;
; #pragma unroll 16
;     for (int kk = 0; kk < 64; ++kk) {
;       const float wv = wp[(size_t)kk * ldw];
;       const float* sp = sc + kp * 64 + kk;
; #pragma unroll
;       for (int j = 0; j < 17; ++j) acc[j] += sp[j * 512] * wv;
	v_fmac_f32_e32 v78, v108, v30
	v_fmac_f32_e32 v78, v109, v31
	v_fmac_f32_e32 v78, v110, v32
	v_fmac_f32_e32 v78, v111, v33
	ds_read_b128 v[108:111], v113 offset:32880
	s_waitcnt lgkmcnt(3)
	v_fmac_f32_e32 v79, v90, v30
	v_fmac_f32_e32 v79, v91, v31
	v_fmac_f32_e32 v79, v92, v32
	v_fmac_f32_e32 v79, v93, v33
	ds_read_b128 v[90:93], v113 offset:128
	s_waitcnt lgkmcnt(3)
	v_fmac_f32_e32 v80, v94, v30
	v_fmac_f32_e32 v80, v95, v31
	v_fmac_f32_e32 v80, v96, v32
	v_fmac_f32_e32 v80, v97, v33
	ds_read_b128 v[94:97], v113 offset:2176
	s_waitcnt lgkmcnt(3)
	v_fmac_f32_e32 v81, v98, v30
	v_fmac_f32_e32 v81, v99, v31
	v_fmac_f32_e32 v81, v100, v32
	v_fmac_f32_e32 v81, v101, v33
	ds_read_b128 v[98:101], v113 offset:4224
	s_waitcnt lgkmcnt(3)
	v_fmac_f32_e32 v89, v108, v30
	v_fmac_f32_e32 v89, v109, v31
	v_fmac_f32_e32 v89, v110, v32
	v_fmac_f32_e32 v89, v111, v33
	ds_read_b128 v[108:111], v113 offset:6272
	s_waitcnt vmcnt(28)
	s_waitcnt lgkmcnt(3)
	v_fmac_f32_e32 v66, v90, v34
	v_fmac_f32_e32 v66, v91, v35
	v_fmac_f32_e32 v66, v92, v36
	v_fmac_f32_e32 v66, v93, v37
	ds_read_b128 v[90:93], v113 offset:8320
	s_waitcnt lgkmcnt(3)
	v_fmac_f32_e32 v67, v94, v34
	v_fmac_f32_e32 v67, v95, v35
	v_fmac_f32_e32 v67, v96, v36
	v_fmac_f32_e32 v67, v97, v37
	ds_read_b128 v[94:97], v113 offset:10368
	s_waitcnt lgkmcnt(3)
	v_fmac_f32_e32 v68, v98, v34
	v_fmac_f32_e32 v68, v99, v35
	v_fmac_f32_e32 v68, v100, v36
	v_fmac_f32_e32 v68, v101, v37
	ds_read_b128 v[98:101], v113 offset:12416
	s_waitcnt lgkmcnt(3)
	v_fmac_f32_e32 v69, v108, v34
	v_fmac_f32_e32 v69, v109, v35
	v_fmac_f32_e32 v69, v110, v36
	v_fmac_f32_e32 v69, v111, v37
	ds_read_b128 v[108:111], v113 offset:14464
	s_waitcnt lgkmcnt(3)
	v_fmac_f32_e32 v70, v90, v34
	v_fmac_f32_e32 v70, v91, v35
	v_fmac_f32_e32 v70, v92, v36
	v_fmac_f32_e32 v70, v93, v37
	ds_read_b128 v[90:93], v113 offset:16512
	s_waitcnt lgkmcnt(3)
	v_fmac_f32_e32 v71, v94, v34
	v_fmac_f32_e32 v71, v95, v35
	v_fmac_f32_e32 v71, v96, v36
	v_fmac_f32_e32 v71, v97, v37
	ds_read_b128 v[94:97], v113 offset:18560
	s_waitcnt lgkmcnt(3)
	v_fmac_f32_e32 v72, v98, v34
	v_fmac_f32_e32 v72, v99, v35
	v_fmac_f32_e32 v72, v100, v36
	v_fmac_f32_e32 v72, v101, v37
	ds_read_b128 v[98:101], v113 offset:20608
	s_waitcnt lgkmcnt(3)
	v_fmac_f32_e32 v73, v108, v34
	v_fmac_f32_e32 v73, v109, v35
	v_fmac_f32_e32 v73, v110, v36
	v_fmac_f32_e32 v73, v111, v37
	ds_read_b128 v[108:111], v113 offset:22656
	s_waitcnt lgkmcnt(3)
	v_fmac_f32_e32 v74, v90, v34
	v_fmac_f32_e32 v74, v91, v35
	v_fmac_f32_e32 v74, v92, v36
	v_fmac_f32_e32 v74, v93, v37
	ds_read_b128 v[90:93], v113 offset:24704
	s_waitcnt lgkmcnt(3)
	v_fmac_f32_e32 v75, v94, v34
	v_fmac_f32_e32 v75, v95, v35
	v_fmac_f32_e32 v75, v96, v36
	v_fmac_f32_e32 v75, v97, v37
	ds_read_b128 v[94:97], v113 offset:26752
	s_waitcnt lgkmcnt(3)
	v_fmac_f32_e32 v76, v98, v34
	v_fmac_f32_e32 v76, v99, v35
	v_fmac_f32_e32 v76, v100, v36
	v_fmac_f32_e32 v76, v101, v37
	ds_read_b128 v[98:101], v113 offset:28800
	s_waitcnt lgkmcnt(3)
	v_fmac_f32_e32 v77, v108, v34
	v_fmac_f32_e32 v77, v109, v35
	v_fmac_f32_e32 v77, v110, v36
	v_fmac_f32_e32 v77, v111, v37
	ds_read_b128 v[108:111], v113 offset:30848
	s_waitcnt lgkmcnt(3)
	v_fmac_f32_e32 v78, v90, v34
	v_fmac_f32_e32 v78, v91, v35
	v_fmac_f32_e32 v78, v92, v36
	v_fmac_f32_e32 v78, v93, v37
	ds_read_b128 v[90:93], v113 offset:32896
	s_waitcnt lgkmcnt(3)
	v_fmac_f32_e32 v79, v94, v34
	v_fmac_f32_e32 v79, v95, v35
	v_fmac_f32_e32 v79, v96, v36
	v_fmac_f32_e32 v79, v97, v37
	ds_read_b128 v[94:97], v113 offset:144
	s_waitcnt lgkmcnt(3)
	v_fmac_f32_e32 v80, v98, v34
	v_fmac_f32_e32 v80, v99, v35
	v_fmac_f32_e32 v80, v100, v36
	v_fmac_f32_e32 v80, v101, v37
	ds_read_b128 v[98:101], v113 offset:2192
	s_waitcnt lgkmcnt(3)
	v_fmac_f32_e32 v81, v108, v34
	v_fmac_f32_e32 v81, v109, v35
	v_fmac_f32_e32 v81, v110, v36
	v_fmac_f32_e32 v81, v111, v37
	ds_read_b128 v[108:111], v113 offset:4240
	s_waitcnt lgkmcnt(3)
	v_fmac_f32_e32 v89, v90, v34
	v_fmac_f32_e32 v89, v91, v35
	v_fmac_f32_e32 v89, v92, v36
	v_fmac_f32_e32 v89, v93, v37
	ds_read_b128 v[90:93], v113 offset:6288
	s_waitcnt vmcnt(24)
	s_waitcnt lgkmcnt(3)
	v_fmac_f32_e32 v66, v94, v38
	v_fmac_f32_e32 v66, v95, v39
	v_fmac_f32_e32 v66, v96, v40
	v_fmac_f32_e32 v66, v97, v41
	ds_read_b128 v[94:97], v113 offset:8336
	s_waitcnt lgkmcnt(3)
	v_fmac_f32_e32 v67, v98, v38
	v_fmac_f32_e32 v67, v99, v39
	v_fmac_f32_e32 v67, v100, v40
	v_fmac_f32_e32 v67, v101, v41
	ds_read_b128 v[98:101], v113 offset:10384
	s_waitcnt lgkmcnt(3)
	v_fmac_f32_e32 v68, v108, v38
	v_fmac_f32_e32 v68, v109, v39
	v_fmac_f32_e32 v68, v110, v40
	v_fmac_f32_e32 v68, v111, v41
	ds_read_b128 v[108:111], v113 offset:12432
	s_waitcnt lgkmcnt(3)
	v_fmac_f32_e32 v69, v90, v38
	v_fmac_f32_e32 v69, v91, v39
	v_fmac_f32_e32 v69, v92, v40
	v_fmac_f32_e32 v69, v93, v41
	ds_read_b128 v[90:93], v113 offset:14480
	s_waitcnt lgkmcnt(3)
	v_fmac_f32_e32 v70, v94, v38
	v_fmac_f32_e32 v70, v95, v39
	v_fmac_f32_e32 v70, v96, v40
	v_fmac_f32_e32 v70, v97, v41
	ds_read_b128 v[94:97], v113 offset:16528
	s_waitcnt lgkmcnt(3)
	v_fmac_f32_e32 v71, v98, v38
	v_fmac_f32_e32 v71, v99, v39
	v_fmac_f32_e32 v71, v100, v40
	v_fmac_f32_e32 v71, v101, v41
	ds_read_b128 v[98:101], v113 offset:18576
	s_waitcnt lgkmcnt(3)
	v_fmac_f32_e32 v72, v108, v38
	v_fmac_f32_e32 v72, v109, v39
	v_fmac_f32_e32 v72, v110, v40
	v_fmac_f32_e32 v72, v111, v41
	ds_read_b128 v[108:111], v113 offset:20624
	s_waitcnt lgkmcnt(3)
	v_fmac_f32_e32 v73, v90, v38
	v_fmac_f32_e32 v73, v91, v39
	v_fmac_f32_e32 v73, v92, v40
	v_fmac_f32_e32 v73, v93, v41
	ds_read_b128 v[90:93], v113 offset:22672
	s_waitcnt lgkmcnt(3)
; DI void gemv17(const float* in16, int istride, const float* in1, bool do_silu, const float* W, int ldw, int n0,
;                const float* bvec, float* out, int ostride, char* lds) {
;     ...
;     __syncthreads();
;     const float* wp = W + (size_t)(kh * 512 + kp * 64) * ldw + n0 + col;
; #pragma unroll 16
;     for (int kk = 0; kk < 64; ++kk) {
;       const float wv = wp[(size_t)kk * ldw];
;       const float* sp = sc + kp * 64 + kk;
; #pragma unroll
;       for (int j = 0; j < 17; ++j) acc[j] += sp[j * 512] * wv;
	v_fmac_f32_e32 v74, v94, v38
	v_fmac_f32_e32 v74, v95, v39
	v_fmac_f32_e32 v74, v96, v40
	v_fmac_f32_e32 v74, v97, v41
	ds_read_b128 v[94:97], v113 offset:24720
	s_waitcnt lgkmcnt(3)
	v_fmac_f32_e32 v75, v98, v38
	v_fmac_f32_e32 v75, v99, v39
	v_fmac_f32_e32 v75, v100, v40
	v_fmac_f32_e32 v75, v101, v41
	ds_read_b128 v[98:101], v113 offset:26768
	s_waitcnt lgkmcnt(3)
	v_fmac_f32_e32 v76, v108, v38
	v_fmac_f32_e32 v76, v109, v39
	v_fmac_f32_e32 v76, v110, v40
	v_fmac_f32_e32 v76, v111, v41
	ds_read_b128 v[108:111], v113 offset:28816
	s_waitcnt lgkmcnt(3)
	v_fmac_f32_e32 v77, v90, v38
	v_fmac_f32_e32 v77, v91, v39
	v_fmac_f32_e32 v77, v92, v40
	v_fmac_f32_e32 v77, v93, v41
	ds_read_b128 v[90:93], v113 offset:30864
	s_waitcnt lgkmcnt(3)
	v_fmac_f32_e32 v78, v94, v38
	v_fmac_f32_e32 v78, v95, v39
	v_fmac_f32_e32 v78, v96, v40
	v_fmac_f32_e32 v78, v97, v41
	ds_read_b128 v[94:97], v113 offset:32912
	s_waitcnt lgkmcnt(3)
	v_fmac_f32_e32 v79, v98, v38
	v_fmac_f32_e32 v79, v99, v39
	v_fmac_f32_e32 v79, v100, v40
	v_fmac_f32_e32 v79, v101, v41
	ds_read_b128 v[98:101], v113 offset:160
	s_waitcnt lgkmcnt(3)
	v_fmac_f32_e32 v80, v108, v38
	v_fmac_f32_e32 v80, v109, v39
	v_fmac_f32_e32 v80, v110, v40
	v_fmac_f32_e32 v80, v111, v41
	ds_read_b128 v[108:111], v113 offset:2208
	s_waitcnt lgkmcnt(3)
	v_fmac_f32_e32 v81, v90, v38
	v_fmac_f32_e32 v81, v91, v39
	v_fmac_f32_e32 v81, v92, v40
	v_fmac_f32_e32 v81, v93, v41
	ds_read_b128 v[90:93], v113 offset:4256
	s_waitcnt lgkmcnt(3)
	v_fmac_f32_e32 v89, v94, v38
	v_fmac_f32_e32 v89, v95, v39
	v_fmac_f32_e32 v89, v96, v40
	v_fmac_f32_e32 v89, v97, v41
	ds_read_b128 v[94:97], v113 offset:6304
	s_waitcnt vmcnt(20)
	s_waitcnt lgkmcnt(3)
	v_fmac_f32_e32 v66, v98, v42
	v_fmac_f32_e32 v66, v99, v43
	v_fmac_f32_e32 v66, v100, v44
	v_fmac_f32_e32 v66, v101, v45
	ds_read_b128 v[98:101], v113 offset:8352
	s_waitcnt lgkmcnt(3)
	v_fmac_f32_e32 v67, v108, v42
	v_fmac_f32_e32 v67, v109, v43
	v_fmac_f32_e32 v67, v110, v44
	v_fmac_f32_e32 v67, v111, v45
	ds_read_b128 v[108:111], v113 offset:10400
	s_waitcnt lgkmcnt(3)
	v_fmac_f32_e32 v68, v90, v42
	v_fmac_f32_e32 v68, v91, v43
	v_fmac_f32_e32 v68, v92, v44
	v_fmac_f32_e32 v68, v93, v45
	ds_read_b128 v[90:93], v113 offset:12448
	s_waitcnt lgkmcnt(3)
	v_fmac_f32_e32 v69, v94, v42
	v_fmac_f32_e32 v69, v95, v43
	v_fmac_f32_e32 v69, v96, v44
	v_fmac_f32_e32 v69, v97, v45
	ds_read_b128 v[94:97], v113 offset:14496
	s_waitcnt lgkmcnt(3)
	v_fmac_f32_e32 v70, v98, v42
	v_fmac_f32_e32 v70, v99, v43
	v_fmac_f32_e32 v70, v100, v44
	v_fmac_f32_e32 v70, v101, v45
	ds_read_b128 v[98:101], v113 offset:16544
	s_waitcnt lgkmcnt(3)
	v_fmac_f32_e32 v71, v108, v42
	v_fmac_f32_e32 v71, v109, v43
	v_fmac_f32_e32 v71, v110, v44
	v_fmac_f32_e32 v71, v111, v45
	ds_read_b128 v[108:111], v113 offset:18592
	s_waitcnt lgkmcnt(3)
	v_fmac_f32_e32 v72, v90, v42
	v_fmac_f32_e32 v72, v91, v43
	v_fmac_f32_e32 v72, v92, v44
	v_fmac_f32_e32 v72, v93, v45
	ds_read_b128 v[90:93], v113 offset:20640
	s_waitcnt lgkmcnt(3)
	v_fmac_f32_e32 v73, v94, v42
	v_fmac_f32_e32 v73, v95, v43
	v_fmac_f32_e32 v73, v96, v44
	v_fmac_f32_e32 v73, v97, v45
	ds_read_b128 v[94:97], v113 offset:22688
	s_waitcnt lgkmcnt(3)
	v_fmac_f32_e32 v74, v98, v42
	v_fmac_f32_e32 v74, v99, v43
	v_fmac_f32_e32 v74, v100, v44
	v_fmac_f32_e32 v74, v101, v45
	ds_read_b128 v[98:101], v113 offset:24736
	s_waitcnt lgkmcnt(3)
	v_fmac_f32_e32 v75, v108, v42
	v_fmac_f32_e32 v75, v109, v43
	v_fmac_f32_e32 v75, v110, v44
	v_fmac_f32_e32 v75, v111, v45
	ds_read_b128 v[108:111], v113 offset:26784
	s_waitcnt lgkmcnt(3)
	v_fmac_f32_e32 v76, v90, v42
	v_fmac_f32_e32 v76, v91, v43
	v_fmac_f32_e32 v76, v92, v44
	v_fmac_f32_e32 v76, v93, v45
	ds_read_b128 v[90:93], v113 offset:28832
	s_waitcnt lgkmcnt(3)
	v_fmac_f32_e32 v77, v94, v42
	v_fmac_f32_e32 v77, v95, v43
	v_fmac_f32_e32 v77, v96, v44
	v_fmac_f32_e32 v77, v97, v45
	ds_read_b128 v[94:97], v113 offset:30880
	s_waitcnt lgkmcnt(3)
	v_fmac_f32_e32 v78, v98, v42
	v_fmac_f32_e32 v78, v99, v43
	v_fmac_f32_e32 v78, v100, v44
	v_fmac_f32_e32 v78, v101, v45
	ds_read_b128 v[98:101], v113 offset:32928
	s_waitcnt lgkmcnt(3)
	v_fmac_f32_e32 v79, v108, v42
	v_fmac_f32_e32 v79, v109, v43
	v_fmac_f32_e32 v79, v110, v44
	v_fmac_f32_e32 v79, v111, v45
	ds_read_b128 v[108:111], v113 offset:176
	s_waitcnt lgkmcnt(3)
	v_fmac_f32_e32 v80, v90, v42
	v_fmac_f32_e32 v80, v91, v43
	v_fmac_f32_e32 v80, v92, v44
	v_fmac_f32_e32 v80, v93, v45
	ds_read_b128 v[90:93], v113 offset:2224
	s_waitcnt lgkmcnt(3)
	v_fmac_f32_e32 v81, v94, v42
	v_fmac_f32_e32 v81, v95, v43
	v_fmac_f32_e32 v81, v96, v44
	v_fmac_f32_e32 v81, v97, v45
	ds_read_b128 v[94:97], v113 offset:4272
	s_waitcnt lgkmcnt(3)
	v_fmac_f32_e32 v89, v98, v42
	v_fmac_f32_e32 v89, v99, v43
	v_fmac_f32_e32 v89, v100, v44
	v_fmac_f32_e32 v89, v101, v45
	ds_read_b128 v[98:101], v113 offset:6320
	s_waitcnt vmcnt(16)
	s_waitcnt lgkmcnt(3)
	v_fmac_f32_e32 v66, v108, v46
	v_fmac_f32_e32 v66, v109, v47
	v_fmac_f32_e32 v66, v110, v48
	v_fmac_f32_e32 v66, v111, v49
	ds_read_b128 v[108:111], v113 offset:8368
	s_waitcnt lgkmcnt(3)
	v_fmac_f32_e32 v67, v90, v46
	v_fmac_f32_e32 v67, v91, v47
	v_fmac_f32_e32 v67, v92, v48
	v_fmac_f32_e32 v67, v93, v49
	ds_read_b128 v[90:93], v113 offset:10416
	s_waitcnt lgkmcnt(3)
	v_fmac_f32_e32 v68, v94, v46
	v_fmac_f32_e32 v68, v95, v47
	v_fmac_f32_e32 v68, v96, v48
	v_fmac_f32_e32 v68, v97, v49
	ds_read_b128 v[94:97], v113 offset:12464
	s_waitcnt lgkmcnt(3)
	v_fmac_f32_e32 v69, v98, v46
	v_fmac_f32_e32 v69, v99, v47
	v_fmac_f32_e32 v69, v100, v48
	v_fmac_f32_e32 v69, v101, v49
	ds_read_b128 v[98:101], v113 offset:14512
	s_waitcnt lgkmcnt(3)
; DI void gemv17(const float* in16, int istride, const float* in1, bool do_silu, const float* W, int ldw, int n0,
;                const float* bvec, float* out, int ostride, char* lds) {
;     ...
;     __syncthreads();
;     const float* wp = W + (size_t)(kh * 512 + kp * 64) * ldw + n0 + col;
; #pragma unroll 16
;     for (int kk = 0; kk < 64; ++kk) {
;       const float wv = wp[(size_t)kk * ldw];
;       const float* sp = sc + kp * 64 + kk;
; #pragma unroll
;       for (int j = 0; j < 17; ++j) acc[j] += sp[j * 512] * wv;
	v_fmac_f32_e32 v70, v108, v46
	v_fmac_f32_e32 v70, v109, v47
	v_fmac_f32_e32 v70, v110, v48
	v_fmac_f32_e32 v70, v111, v49
	ds_read_b128 v[108:111], v113 offset:16560
	s_waitcnt lgkmcnt(3)
	v_fmac_f32_e32 v71, v90, v46
	v_fmac_f32_e32 v71, v91, v47
	v_fmac_f32_e32 v71, v92, v48
	v_fmac_f32_e32 v71, v93, v49
	ds_read_b128 v[90:93], v113 offset:18608
	s_waitcnt lgkmcnt(3)
	v_fmac_f32_e32 v72, v94, v46
	v_fmac_f32_e32 v72, v95, v47
	v_fmac_f32_e32 v72, v96, v48
	v_fmac_f32_e32 v72, v97, v49
	ds_read_b128 v[94:97], v113 offset:20656
	s_waitcnt lgkmcnt(3)
	v_fmac_f32_e32 v73, v98, v46
	v_fmac_f32_e32 v73, v99, v47
	v_fmac_f32_e32 v73, v100, v48
	v_fmac_f32_e32 v73, v101, v49
	ds_read_b128 v[98:101], v113 offset:22704
	s_waitcnt lgkmcnt(3)
	v_fmac_f32_e32 v74, v108, v46
	v_fmac_f32_e32 v74, v109, v47
	v_fmac_f32_e32 v74, v110, v48
	v_fmac_f32_e32 v74, v111, v49
	ds_read_b128 v[108:111], v113 offset:24752
	s_waitcnt lgkmcnt(3)
	v_fmac_f32_e32 v75, v90, v46
	v_fmac_f32_e32 v75, v91, v47
	v_fmac_f32_e32 v75, v92, v48
	v_fmac_f32_e32 v75, v93, v49
	ds_read_b128 v[90:93], v113 offset:26800
	s_waitcnt lgkmcnt(3)
	v_fmac_f32_e32 v76, v94, v46
	v_fmac_f32_e32 v76, v95, v47
	v_fmac_f32_e32 v76, v96, v48
	v_fmac_f32_e32 v76, v97, v49
	ds_read_b128 v[94:97], v113 offset:28848
	s_waitcnt lgkmcnt(3)
	v_fmac_f32_e32 v77, v98, v46
	v_fmac_f32_e32 v77, v99, v47
	v_fmac_f32_e32 v77, v100, v48
	v_fmac_f32_e32 v77, v101, v49
	ds_read_b128 v[98:101], v113 offset:30896
	s_waitcnt lgkmcnt(3)
	v_fmac_f32_e32 v78, v108, v46
	v_fmac_f32_e32 v78, v109, v47
	v_fmac_f32_e32 v78, v110, v48
	v_fmac_f32_e32 v78, v111, v49
	ds_read_b128 v[108:111], v113 offset:32944
	s_waitcnt lgkmcnt(3)
	v_fmac_f32_e32 v79, v90, v46
	v_fmac_f32_e32 v79, v91, v47
	v_fmac_f32_e32 v79, v92, v48
	v_fmac_f32_e32 v79, v93, v49
	ds_read_b128 v[90:93], v113 offset:192
	s_waitcnt lgkmcnt(3)
	v_fmac_f32_e32 v80, v94, v46
	v_fmac_f32_e32 v80, v95, v47
	v_fmac_f32_e32 v80, v96, v48
	v_fmac_f32_e32 v80, v97, v49
	ds_read_b128 v[94:97], v113 offset:2240
	s_waitcnt lgkmcnt(3)
	v_fmac_f32_e32 v81, v98, v46
	v_fmac_f32_e32 v81, v99, v47
	v_fmac_f32_e32 v81, v100, v48
	v_fmac_f32_e32 v81, v101, v49
	ds_read_b128 v[98:101], v113 offset:4288
	s_waitcnt lgkmcnt(3)
	v_fmac_f32_e32 v89, v108, v46
	v_fmac_f32_e32 v89, v109, v47
	v_fmac_f32_e32 v89, v110, v48
	v_fmac_f32_e32 v89, v111, v49
	ds_read_b128 v[108:111], v113 offset:6336
	s_waitcnt vmcnt(12)
	s_waitcnt lgkmcnt(3)
	v_fmac_f32_e32 v66, v90, v50
	v_fmac_f32_e32 v66, v91, v51
	v_fmac_f32_e32 v66, v92, v52
	v_fmac_f32_e32 v66, v93, v53
	ds_read_b128 v[90:93], v113 offset:8384
	s_waitcnt lgkmcnt(3)
	v_fmac_f32_e32 v67, v94, v50
	v_fmac_f32_e32 v67, v95, v51
	v_fmac_f32_e32 v67, v96, v52
	v_fmac_f32_e32 v67, v97, v53
	ds_read_b128 v[94:97], v113 offset:10432
	s_waitcnt lgkmcnt(3)
	v_fmac_f32_e32 v68, v98, v50
	v_fmac_f32_e32 v68, v99, v51
	v_fmac_f32_e32 v68, v100, v52
	v_fmac_f32_e32 v68, v101, v53
	ds_read_b128 v[98:101], v113 offset:12480
	s_waitcnt lgkmcnt(3)
	v_fmac_f32_e32 v69, v108, v50
	v_fmac_f32_e32 v69, v109, v51
	v_fmac_f32_e32 v69, v110, v52
	v_fmac_f32_e32 v69, v111, v53
	ds_read_b128 v[108:111], v113 offset:14528
	s_waitcnt lgkmcnt(3)
	v_fmac_f32_e32 v70, v90, v50
	v_fmac_f32_e32 v70, v91, v51
	v_fmac_f32_e32 v70, v92, v52
	v_fmac_f32_e32 v70, v93, v53
	ds_read_b128 v[90:93], v113 offset:16576
	s_waitcnt lgkmcnt(3)
	v_fmac_f32_e32 v71, v94, v50
	v_fmac_f32_e32 v71, v95, v51
	v_fmac_f32_e32 v71, v96, v52
	v_fmac_f32_e32 v71, v97, v53
	ds_read_b128 v[94:97], v113 offset:18624
	s_waitcnt lgkmcnt(3)
	v_fmac_f32_e32 v72, v98, v50
	v_fmac_f32_e32 v72, v99, v51
	v_fmac_f32_e32 v72, v100, v52
	v_fmac_f32_e32 v72, v101, v53
	ds_read_b128 v[98:101], v113 offset:20672
	s_waitcnt lgkmcnt(3)
	v_fmac_f32_e32 v73, v108, v50
	v_fmac_f32_e32 v73, v109, v51
	v_fmac_f32_e32 v73, v110, v52
	v_fmac_f32_e32 v73, v111, v53
	ds_read_b128 v[108:111], v113 offset:22720
	s_waitcnt lgkmcnt(3)
	v_fmac_f32_e32 v74, v90, v50
	v_fmac_f32_e32 v74, v91, v51
	v_fmac_f32_e32 v74, v92, v52
	v_fmac_f32_e32 v74, v93, v53
	ds_read_b128 v[90:93], v113 offset:24768
	s_waitcnt lgkmcnt(3)
	v_fmac_f32_e32 v75, v94, v50
	v_fmac_f32_e32 v75, v95, v51
	v_fmac_f32_e32 v75, v96, v52
	v_fmac_f32_e32 v75, v97, v53
	ds_read_b128 v[94:97], v113 offset:26816
	s_waitcnt lgkmcnt(3)
	v_fmac_f32_e32 v76, v98, v50
	v_fmac_f32_e32 v76, v99, v51
	v_fmac_f32_e32 v76, v100, v52
	v_fmac_f32_e32 v76, v101, v53
	ds_read_b128 v[98:101], v113 offset:28864
	s_waitcnt lgkmcnt(3)
	v_fmac_f32_e32 v77, v108, v50
	v_fmac_f32_e32 v77, v109, v51
	v_fmac_f32_e32 v77, v110, v52
	v_fmac_f32_e32 v77, v111, v53
	ds_read_b128 v[108:111], v113 offset:30912
	s_waitcnt lgkmcnt(3)
	v_fmac_f32_e32 v78, v90, v50
	v_fmac_f32_e32 v78, v91, v51
	v_fmac_f32_e32 v78, v92, v52
	v_fmac_f32_e32 v78, v93, v53
	ds_read_b128 v[90:93], v113 offset:32960
	s_waitcnt lgkmcnt(3)
	v_fmac_f32_e32 v79, v94, v50
	v_fmac_f32_e32 v79, v95, v51
	v_fmac_f32_e32 v79, v96, v52
	v_fmac_f32_e32 v79, v97, v53
	ds_read_b128 v[94:97], v113 offset:208
	s_waitcnt lgkmcnt(3)
	v_fmac_f32_e32 v80, v98, v50
	v_fmac_f32_e32 v80, v99, v51
	v_fmac_f32_e32 v80, v100, v52
	v_fmac_f32_e32 v80, v101, v53
	ds_read_b128 v[98:101], v113 offset:2256
	s_waitcnt lgkmcnt(3)
	v_fmac_f32_e32 v81, v108, v50
	v_fmac_f32_e32 v81, v109, v51
	v_fmac_f32_e32 v81, v110, v52
	v_fmac_f32_e32 v81, v111, v53
	ds_read_b128 v[108:111], v113 offset:4304
	s_waitcnt lgkmcnt(3)
	v_fmac_f32_e32 v89, v90, v50
	v_fmac_f32_e32 v89, v91, v51
	v_fmac_f32_e32 v89, v92, v52
	v_fmac_f32_e32 v89, v93, v53
	ds_read_b128 v[90:93], v113 offset:6352
	s_waitcnt vmcnt(8)
	s_waitcnt lgkmcnt(3)
; DI void gemv17(const float* in16, int istride, const float* in1, bool do_silu, const float* W, int ldw, int n0,
;                const float* bvec, float* out, int ostride, char* lds) {
;     ...
;     __syncthreads();
;     const float* wp = W + (size_t)(kh * 512 + kp * 64) * ldw + n0 + col;
; #pragma unroll 16
;     for (int kk = 0; kk < 64; ++kk) {
;       const float wv = wp[(size_t)kk * ldw];
;       const float* sp = sc + kp * 64 + kk;
; #pragma unroll
;       for (int j = 0; j < 17; ++j) acc[j] += sp[j * 512] * wv;
	v_fmac_f32_e32 v66, v94, v54
	v_fmac_f32_e32 v66, v95, v55
	v_fmac_f32_e32 v66, v96, v56
	v_fmac_f32_e32 v66, v97, v57
	ds_read_b128 v[94:97], v113 offset:8400
	s_waitcnt lgkmcnt(3)
	v_fmac_f32_e32 v67, v98, v54
	v_fmac_f32_e32 v67, v99, v55
	v_fmac_f32_e32 v67, v100, v56
	v_fmac_f32_e32 v67, v101, v57
	ds_read_b128 v[98:101], v113 offset:10448
	s_waitcnt lgkmcnt(3)
	v_fmac_f32_e32 v68, v108, v54
	v_fmac_f32_e32 v68, v109, v55
	v_fmac_f32_e32 v68, v110, v56
	v_fmac_f32_e32 v68, v111, v57
	ds_read_b128 v[108:111], v113 offset:12496
	s_waitcnt lgkmcnt(3)
	v_fmac_f32_e32 v69, v90, v54
	v_fmac_f32_e32 v69, v91, v55
	v_fmac_f32_e32 v69, v92, v56
	v_fmac_f32_e32 v69, v93, v57
	ds_read_b128 v[90:93], v113 offset:14544
	s_waitcnt lgkmcnt(3)
	v_fmac_f32_e32 v70, v94, v54
	v_fmac_f32_e32 v70, v95, v55
	v_fmac_f32_e32 v70, v96, v56
	v_fmac_f32_e32 v70, v97, v57
	ds_read_b128 v[94:97], v113 offset:16592
	s_waitcnt lgkmcnt(3)
	v_fmac_f32_e32 v71, v98, v54
	v_fmac_f32_e32 v71, v99, v55
	v_fmac_f32_e32 v71, v100, v56
	v_fmac_f32_e32 v71, v101, v57
	ds_read_b128 v[98:101], v113 offset:18640
	s_waitcnt lgkmcnt(3)
	v_fmac_f32_e32 v72, v108, v54
	v_fmac_f32_e32 v72, v109, v55
	v_fmac_f32_e32 v72, v110, v56
	v_fmac_f32_e32 v72, v111, v57
	ds_read_b128 v[108:111], v113 offset:20688
	s_waitcnt lgkmcnt(3)
	v_fmac_f32_e32 v73, v90, v54
	v_fmac_f32_e32 v73, v91, v55
	v_fmac_f32_e32 v73, v92, v56
	v_fmac_f32_e32 v73, v93, v57
	ds_read_b128 v[90:93], v113 offset:22736
	s_waitcnt lgkmcnt(3)
	v_fmac_f32_e32 v74, v94, v54
	v_fmac_f32_e32 v74, v95, v55
	v_fmac_f32_e32 v74, v96, v56
	v_fmac_f32_e32 v74, v97, v57
	ds_read_b128 v[94:97], v113 offset:24784
	s_waitcnt lgkmcnt(3)
	v_fmac_f32_e32 v75, v98, v54
	v_fmac_f32_e32 v75, v99, v55
	v_fmac_f32_e32 v75, v100, v56
	v_fmac_f32_e32 v75, v101, v57
	ds_read_b128 v[98:101], v113 offset:26832
	s_waitcnt lgkmcnt(3)
	v_fmac_f32_e32 v76, v108, v54
	v_fmac_f32_e32 v76, v109, v55
	v_fmac_f32_e32 v76, v110, v56
	v_fmac_f32_e32 v76, v111, v57
	ds_read_b128 v[108:111], v113 offset:28880
	s_waitcnt lgkmcnt(3)
	v_fmac_f32_e32 v77, v90, v54
	v_fmac_f32_e32 v77, v91, v55
	v_fmac_f32_e32 v77, v92, v56
	v_fmac_f32_e32 v77, v93, v57
	ds_read_b128 v[90:93], v113 offset:30928
	s_waitcnt lgkmcnt(3)
	v_fmac_f32_e32 v78, v94, v54
	v_fmac_f32_e32 v78, v95, v55
	v_fmac_f32_e32 v78, v96, v56
	v_fmac_f32_e32 v78, v97, v57
	ds_read_b128 v[94:97], v113 offset:32976
	s_waitcnt lgkmcnt(3)
	v_fmac_f32_e32 v79, v98, v54
	v_fmac_f32_e32 v79, v99, v55
	v_fmac_f32_e32 v79, v100, v56
	v_fmac_f32_e32 v79, v101, v57
	ds_read_b128 v[98:101], v113 offset:224
	s_waitcnt lgkmcnt(3)
	v_fmac_f32_e32 v80, v108, v54
	v_fmac_f32_e32 v80, v109, v55
	v_fmac_f32_e32 v80, v110, v56
	v_fmac_f32_e32 v80, v111, v57
	ds_read_b128 v[108:111], v113 offset:2272
	s_waitcnt lgkmcnt(3)
	v_fmac_f32_e32 v81, v90, v54
	v_fmac_f32_e32 v81, v91, v55
	v_fmac_f32_e32 v81, v92, v56
	v_fmac_f32_e32 v81, v93, v57
	ds_read_b128 v[90:93], v113 offset:4320
	s_waitcnt lgkmcnt(3)
	v_fmac_f32_e32 v89, v94, v54
	v_fmac_f32_e32 v89, v95, v55
	v_fmac_f32_e32 v89, v96, v56
	v_fmac_f32_e32 v89, v97, v57
	ds_read_b128 v[94:97], v113 offset:6368
	s_waitcnt vmcnt(4)
	s_waitcnt lgkmcnt(3)
	v_fmac_f32_e32 v66, v98, v58
	v_fmac_f32_e32 v66, v99, v59
	v_fmac_f32_e32 v66, v100, v60
	v_fmac_f32_e32 v66, v101, v61
	ds_read_b128 v[98:101], v113 offset:8416
	s_waitcnt lgkmcnt(3)
	v_fmac_f32_e32 v67, v108, v58
	v_fmac_f32_e32 v67, v109, v59
	v_fmac_f32_e32 v67, v110, v60
	v_fmac_f32_e32 v67, v111, v61
	ds_read_b128 v[108:111], v113 offset:10464
	s_waitcnt lgkmcnt(3)
	v_fmac_f32_e32 v68, v90, v58
	v_fmac_f32_e32 v68, v91, v59
	v_fmac_f32_e32 v68, v92, v60
	v_fmac_f32_e32 v68, v93, v61
	ds_read_b128 v[90:93], v113 offset:12512
	s_waitcnt lgkmcnt(3)
	v_fmac_f32_e32 v69, v94, v58
	v_fmac_f32_e32 v69, v95, v59
	v_fmac_f32_e32 v69, v96, v60
	v_fmac_f32_e32 v69, v97, v61
	ds_read_b128 v[94:97], v113 offset:14560
	s_waitcnt lgkmcnt(3)
	v_fmac_f32_e32 v70, v98, v58
	v_fmac_f32_e32 v70, v99, v59
	v_fmac_f32_e32 v70, v100, v60
	v_fmac_f32_e32 v70, v101, v61
	ds_read_b128 v[98:101], v113 offset:16608
	s_waitcnt lgkmcnt(3)
	v_fmac_f32_e32 v71, v108, v58
	v_fmac_f32_e32 v71, v109, v59
	v_fmac_f32_e32 v71, v110, v60
	v_fmac_f32_e32 v71, v111, v61
	ds_read_b128 v[108:111], v113 offset:18656
	s_waitcnt lgkmcnt(3)
	v_fmac_f32_e32 v72, v90, v58
	v_fmac_f32_e32 v72, v91, v59
	v_fmac_f32_e32 v72, v92, v60
	v_fmac_f32_e32 v72, v93, v61
	ds_read_b128 v[90:93], v113 offset:20704
	s_waitcnt lgkmcnt(3)
	v_fmac_f32_e32 v73, v94, v58
	v_fmac_f32_e32 v73, v95, v59
	v_fmac_f32_e32 v73, v96, v60
	v_fmac_f32_e32 v73, v97, v61
	ds_read_b128 v[94:97], v113 offset:22752
	s_waitcnt lgkmcnt(3)
	v_fmac_f32_e32 v74, v98, v58
	v_fmac_f32_e32 v74, v99, v59
	v_fmac_f32_e32 v74, v100, v60
	v_fmac_f32_e32 v74, v101, v61
	ds_read_b128 v[98:101], v113 offset:24800
	s_waitcnt lgkmcnt(3)
	v_fmac_f32_e32 v75, v108, v58
	v_fmac_f32_e32 v75, v109, v59
	v_fmac_f32_e32 v75, v110, v60
	v_fmac_f32_e32 v75, v111, v61
	ds_read_b128 v[108:111], v113 offset:26848
	s_waitcnt lgkmcnt(3)
	v_fmac_f32_e32 v76, v90, v58
	v_fmac_f32_e32 v76, v91, v59
	v_fmac_f32_e32 v76, v92, v60
	v_fmac_f32_e32 v76, v93, v61
	ds_read_b128 v[90:93], v113 offset:28896
	s_waitcnt lgkmcnt(3)
	v_fmac_f32_e32 v77, v94, v58
	v_fmac_f32_e32 v77, v95, v59
	v_fmac_f32_e32 v77, v96, v60
	v_fmac_f32_e32 v77, v97, v61
	ds_read_b128 v[94:97], v113 offset:30944
	s_waitcnt lgkmcnt(3)
	v_fmac_f32_e32 v78, v98, v58
	v_fmac_f32_e32 v78, v99, v59
	v_fmac_f32_e32 v78, v100, v60
	v_fmac_f32_e32 v78, v101, v61
	ds_read_b128 v[98:101], v113 offset:32992
	s_waitcnt lgkmcnt(3)
; DI void gemv17(const float* in16, int istride, const float* in1, bool do_silu, const float* W, int ldw, int n0,
;                const float* bvec, float* out, int ostride, char* lds) {
;     ...
; #pragma unroll 16
;     for (int kk = 0; kk < 64; ++kk) {
;       const float wv = wp[(size_t)kk * ldw];
;       const float* sp = sc + kp * 64 + kk;
; #pragma unroll
;       for (int j = 0; j < 17; ++j) acc[j] += sp[j * 512] * wv;
;     }
;   }
; #pragma unroll
;   for (int j = 0; j < 17; ++j) red[(kp * 17 + j) * 64 + col] = acc[j];
;   __syncthreads();
;   for (int e = tid; e < 17 * 64; e += NTHREADS) {
;     const int j = e >> 6, cc = e & 63;
;     float v = ((red[(0 * 17 + j) * 64 + cc] + red[(1 * 17 + j) * 64 + cc]) +
;                (red[(2 * 17 + j) * 64 + cc] + red[(3 * 17 + j) * 64 + cc])) +
;               ((red[(4 * 17 + j) * 64 + cc] + red[(5 * 17 + j) * 64 + cc]) +
;                (red[(6 * 17 + j) * 64 + cc] + red[(7 * 17 + j) * 64 + cc]));
;     if (bvec) v += bvec[n0 + cc];
;     out[(size_t)j * ostride + n0 + cc] = v;
;   }
;   __syncthreads();
	v_fmac_f32_e32 v79, v108, v58
	v_fmac_f32_e32 v79, v109, v59
	v_fmac_f32_e32 v79, v110, v60
	v_fmac_f32_e32 v79, v111, v61
	ds_read_b128 v[108:111], v113 offset:240
	s_waitcnt lgkmcnt(3)
	v_fmac_f32_e32 v80, v90, v58
	v_fmac_f32_e32 v80, v91, v59
	v_fmac_f32_e32 v80, v92, v60
	v_fmac_f32_e32 v80, v93, v61
	ds_read_b128 v[90:93], v113 offset:2288
	s_waitcnt lgkmcnt(3)
	v_fmac_f32_e32 v81, v94, v58
	v_fmac_f32_e32 v81, v95, v59
	v_fmac_f32_e32 v81, v96, v60
	v_fmac_f32_e32 v81, v97, v61
	ds_read_b128 v[94:97], v113 offset:4336
	s_waitcnt lgkmcnt(3)
	v_fmac_f32_e32 v89, v98, v58
	v_fmac_f32_e32 v89, v99, v59
	v_fmac_f32_e32 v89, v100, v60
	v_fmac_f32_e32 v89, v101, v61
	ds_read_b128 v[98:101], v113 offset:6384
	s_waitcnt vmcnt(0)
	s_waitcnt lgkmcnt(3)
	v_fmac_f32_e32 v66, v108, v62
	v_fmac_f32_e32 v66, v109, v63
	v_fmac_f32_e32 v66, v110, v64
	v_fmac_f32_e32 v66, v111, v65
	ds_read_b128 v[108:111], v113 offset:8432
	s_waitcnt lgkmcnt(3)
	v_fmac_f32_e32 v67, v90, v62
	v_fmac_f32_e32 v67, v91, v63
	v_fmac_f32_e32 v67, v92, v64
	v_fmac_f32_e32 v67, v93, v65
	ds_read_b128 v[90:93], v113 offset:10480
	s_waitcnt lgkmcnt(3)
	v_fmac_f32_e32 v68, v94, v62
	v_fmac_f32_e32 v68, v95, v63
	v_fmac_f32_e32 v68, v96, v64
	v_fmac_f32_e32 v68, v97, v65
	ds_read_b128 v[94:97], v113 offset:12528
	s_waitcnt lgkmcnt(3)
	v_fmac_f32_e32 v69, v98, v62
	v_fmac_f32_e32 v69, v99, v63
	v_fmac_f32_e32 v69, v100, v64
	v_fmac_f32_e32 v69, v101, v65
	ds_read_b128 v[98:101], v113 offset:14576
	s_waitcnt lgkmcnt(3)
	v_fmac_f32_e32 v70, v108, v62
	v_fmac_f32_e32 v70, v109, v63
	v_fmac_f32_e32 v70, v110, v64
	v_fmac_f32_e32 v70, v111, v65
	ds_read_b128 v[108:111], v113 offset:16624
	s_waitcnt lgkmcnt(3)
	v_fmac_f32_e32 v71, v90, v62
	v_fmac_f32_e32 v71, v91, v63
	v_fmac_f32_e32 v71, v92, v64
	v_fmac_f32_e32 v71, v93, v65
	ds_read_b128 v[90:93], v113 offset:18672
	s_waitcnt lgkmcnt(3)
	v_fmac_f32_e32 v72, v94, v62
	v_fmac_f32_e32 v72, v95, v63
	v_fmac_f32_e32 v72, v96, v64
	v_fmac_f32_e32 v72, v97, v65
	ds_read_b128 v[94:97], v113 offset:20720
	s_waitcnt lgkmcnt(3)
	v_fmac_f32_e32 v73, v98, v62
	v_fmac_f32_e32 v73, v99, v63
	v_fmac_f32_e32 v73, v100, v64
	v_fmac_f32_e32 v73, v101, v65
	ds_read_b128 v[98:101], v113 offset:22768
	s_waitcnt lgkmcnt(3)
	v_fmac_f32_e32 v74, v108, v62
	v_fmac_f32_e32 v74, v109, v63
	v_fmac_f32_e32 v74, v110, v64
	v_fmac_f32_e32 v74, v111, v65
	ds_read_b128 v[108:111], v113 offset:24816
	s_waitcnt lgkmcnt(3)
	v_fmac_f32_e32 v75, v90, v62
	v_fmac_f32_e32 v75, v91, v63
	v_fmac_f32_e32 v75, v92, v64
	v_fmac_f32_e32 v75, v93, v65
	ds_read_b128 v[90:93], v113 offset:26864
	s_waitcnt lgkmcnt(3)
	v_fmac_f32_e32 v76, v94, v62
	v_fmac_f32_e32 v76, v95, v63
	v_fmac_f32_e32 v76, v96, v64
	v_fmac_f32_e32 v76, v97, v65
	ds_read_b128 v[94:97], v113 offset:28912
	s_waitcnt lgkmcnt(3)
	v_fmac_f32_e32 v77, v98, v62
	v_fmac_f32_e32 v77, v99, v63
	v_fmac_f32_e32 v77, v100, v64
	v_fmac_f32_e32 v77, v101, v65
	ds_read_b128 v[98:101], v113 offset:30960
	s_waitcnt lgkmcnt(3)
	v_fmac_f32_e32 v78, v108, v62
	v_fmac_f32_e32 v78, v109, v63
	v_fmac_f32_e32 v78, v110, v64
	v_fmac_f32_e32 v78, v111, v65
	ds_read_b128 v[108:111], v113 offset:33008
	s_waitcnt lgkmcnt(3)
	v_fmac_f32_e32 v79, v90, v62
	v_fmac_f32_e32 v79, v91, v63
	v_fmac_f32_e32 v79, v92, v64
	v_fmac_f32_e32 v79, v93, v65
	s_waitcnt lgkmcnt(2)
	v_fmac_f32_e32 v80, v94, v62
	v_fmac_f32_e32 v80, v95, v63
	v_fmac_f32_e32 v80, v96, v64
	v_fmac_f32_e32 v80, v97, v65
	s_waitcnt lgkmcnt(1)
	v_fmac_f32_e32 v81, v98, v62
	v_fmac_f32_e32 v81, v99, v63
	v_fmac_f32_e32 v81, v100, v64
	v_fmac_f32_e32 v81, v101, v65
	s_waitcnt lgkmcnt(0)
	v_fmac_f32_e32 v89, v108, v62
	v_fmac_f32_e32 v89, v109, v63
	v_fmac_f32_e32 v89, v110, v64
	v_fmac_f32_e32 v89, v111, v65
	s_add_u32 s36, s36, 0x800
	s_addc_u32 s37, s37, 0
	s_add_u32 s40, s40, 5767168
	s_addc_u32 s41, s41, 0
	s_add_i32 s47, s47, 1
	s_cmp_lt_u32 s47, 2
	s_cbranch_scc1 .Lgv_bias_kh
	v_lshrrev_b32_e32 v0, 6, v251
	v_mul_u32_u24_e32 v90, 0x1100, v0
	v_and_b32_e32 v91, 63, v251
	v_lshlrev_b32_e32 v91, 2, v91
	v_add_u32_e32 v90, v90, v91
	v_add_u32_e32 v90, 0x8800, v90
	ds_write_b32 v90, v66
	ds_write_b32 v90, v67 offset:256
	ds_write_b32 v90, v68 offset:512
	ds_write_b32 v90, v69 offset:768
	ds_write_b32 v90, v70 offset:1024
	ds_write_b32 v90, v71 offset:1280
	ds_write_b32 v90, v72 offset:1536
	ds_write_b32 v90, v73 offset:1792
	ds_write_b32 v90, v74 offset:2048
	ds_write_b32 v90, v75 offset:2304
	ds_write_b32 v90, v76 offset:2560
	ds_write_b32 v90, v77 offset:2816
	ds_write_b32 v90, v78 offset:3072
	ds_write_b32 v90, v79 offset:3328
	ds_write_b32 v90, v80 offset:3584
	ds_write_b32 v90, v81 offset:3840
	ds_write_b32 v90, v89 offset:4096
	s_waitcnt lgkmcnt(0)
	s_barrier
	v_lshlrev_b32_e32 v90, 8, v0
	v_add_u32_e32 v90, v90, v91
	v_add_u32_e32 v90, 0x8800, v90
	s_mul_i32 s3, s46, 11264
	s_add_u32 s44, s44, s3
	s_addc_u32 s45, s45, 0
	ds_read_b32 v92, v90 offset:0
	ds_read_b32 v93, v90 offset:4352
	ds_read_b32 v94, v90 offset:8704
	ds_read_b32 v95, v90 offset:13056
	ds_read_b32 v96, v90 offset:17408
	ds_read_b32 v97, v90 offset:21760
	ds_read_b32 v98, v90 offset:26112
	ds_read_b32 v99, v90 offset:30464
	s_waitcnt lgkmcnt(0)
	v_add_f32_e32 v92, v92, v93
	v_add_f32_e32 v94, v94, v95
	v_add_f32_e32 v96, v96, v97
	v_add_f32_e32 v98, v98, v99
	v_add_f32_e32 v92, v92, v94
	v_add_f32_e32 v96, v96, v98
	v_add_f32_e32 v92, v92, v96
	global_store_dword v91, v92, s[44:45]
	s_add_u32 s44, s44, 90112
	s_addc_u32 s45, s45, 0
	ds_read_b32 v92, v90 offset:2048
	ds_read_b32 v93, v90 offset:6400
	ds_read_b32 v94, v90 offset:10752
	ds_read_b32 v95, v90 offset:15104
	ds_read_b32 v96, v90 offset:19456
	ds_read_b32 v97, v90 offset:23808
	ds_read_b32 v98, v90 offset:28160
	ds_read_b32 v99, v90 offset:32512
	s_waitcnt lgkmcnt(0)
	v_add_f32_e32 v92, v92, v93
	v_add_f32_e32 v94, v94, v95
	v_add_f32_e32 v96, v96, v97
	v_add_f32_e32 v98, v98, v99
	v_add_f32_e32 v92, v92, v94
	v_add_f32_e32 v96, v96, v98
	v_add_f32_e32 v92, v92, v96
	global_store_dword v91, v92, s[44:45]
	s_add_u32 s44, s44, 90112
	s_addc_u32 s45, s45, 0
	s_cmp_lg_u32 s46, 0
	s_cbranch_scc1 .Lgv_bias_done
	ds_read_b32 v92, v90 offset:4096
	ds_read_b32 v93, v90 offset:8448
	ds_read_b32 v94, v90 offset:12800
	ds_read_b32 v95, v90 offset:17152
	ds_read_b32 v96, v90 offset:21504
	ds_read_b32 v97, v90 offset:25856
	ds_read_b32 v98, v90 offset:30208
	ds_read_b32 v99, v90 offset:34560
	s_waitcnt lgkmcnt(0)
	v_add_f32_e32 v92, v92, v93
	v_add_f32_e32 v94, v94, v95
	v_add_f32_e32 v96, v96, v97
	v_add_f32_e32 v98, v98, v99
	v_add_f32_e32 v92, v92, v94
	v_add_f32_e32 v96, v96, v98
	v_add_f32_e32 v92, v92, v96
	global_store_dword v91, v92, s[44:45]
.Lgv_bias_done:
	s_barrier
	s_mov_b32 s25, 0xbfb8aa3b
	s_branch .LBB0_15

; DI int get_tid() { int t = threadIdx.x; asm volatile("" : "+v"(t)); return t; }
; DI int get_bid() { int t = blockIdx.x; asm volatile("" : "+s"(t)); return t; }
; DI void gemv17(const float* in16, int istride, const float* in1, bool do_silu, const float* W, int ldw, int n0,
;                const float* bvec, float* out, int ostride, char* lds) {
;   const int tid = get_tid(), col = tid & 63, kp = tid >> 6;
;   float* sc = (float*)lds;
;   float* red = (float*)(lds + 34816);
;   float acc[17];
; #pragma unroll
;   for (int j = 0; j < 17; ++j) acc[j] = 0.f;
;   for (int kh = 0; kh < 2; ++kh) {
;     __syncthreads();
;     for (int e = tid; e < 17 * 512; e += NTHREADS) {
;       const int j = e >> 9, k = e & 511;
;       float v = (j < 16) ? in16[(size_t)j * istride + kh * 512 + k] : in1[kh * 512 + k];
;       if (do_silu) v = v / (1.f + expf(-v));
;       sc[e] = v;
;     }
;     __syncthreads();
;     const float* wp = W + (size_t)(kh * 512 + kp * 64) * ldw + n0 + col;
; DI void phase0(const Params& p, char* lds) {
;     ...
;   for (int it = get_bid(); it < total; it += gridDim.x) {
;     if (it < N_MOD) {
;       const int l = it / 48, nc = it % 48;
;       gemv17(p.c, DM, p.c_ctx, true, p.w_mod + (size_t)l * DM * 3072, 3072, nc * 64, p.b_mod + l * 3072,
;              p.mod + (size_t)l * 17 * 3072, 3072, lds);
.LBB0_524:
	s_mul_i32 s0, s20, 1366
	s_lshr_b32 s0, s0, 16
	s_mul_i32 s2, s0, 48
	s_sub_i32 s2, s20, s2
	s_lshl_b32 s2, s2, 8
	v_readlane_b32 s36, v254, 11
	v_readlane_b32 s37, v254, 12
	v_readlane_b32 s38, v254, 15
	v_readlane_b32 s39, v254, 16
	v_readlane_b32 s40, v254, 19
	v_readlane_b32 s41, v254, 20
	v_readlane_b32 s42, v254, 21
	v_readlane_b32 s43, v254, 22
	v_readlane_b32 s44, v254, 59
	v_readlane_b32 s45, v254, 60
	s_nop 3
	s_mul_i32 s3, s0, 0xc00000
	s_add_u32 s40, s40, s3
	s_addc_u32 s41, s41, 0
	s_mul_i32 s3, s0, 0x3000
	s_add_u32 s42, s42, s3
	s_addc_u32 s43, s43, 0
	s_add_u32 s42, s42, s2
	s_addc_u32 s43, s43, 0
	s_mul_i32 s3, s0, 0x33000
	s_add_u32 s44, s44, s3
	s_addc_u32 s45, s45, 0
	s_add_u32 s40, s40, s2
	s_addc_u32 s41, s41, 0
	s_add_u32 s44, s44, s2
	s_addc_u32 s45, s45, 0
	v_lshrrev_b32_e32 v0, 6, v251
	s_nop 0
	v_readfirstlane_b32 s46, v0
	s_nop 3
	s_mul_i32 s3, s46, 786432
	s_add_u32 s40, s40, s3
	s_addc_u32 s41, s41, 0
	v_mov_b32_e32 v66, 0
	v_mov_b32_e32 v67, 0
	v_mov_b32_e32 v68, 0
	v_mov_b32_e32 v69, 0
	v_mov_b32_e32 v70, 0
	v_mov_b32_e32 v71, 0
	v_mov_b32_e32 v72, 0
	v_mov_b32_e32 v73, 0
	v_mov_b32_e32 v74, 0
	v_mov_b32_e32 v75, 0
	v_mov_b32_e32 v76, 0
	v_mov_b32_e32 v77, 0
	v_mov_b32_e32 v78, 0
	v_mov_b32_e32 v79, 0
	v_mov_b32_e32 v80, 0
	v_mov_b32_e32 v81, 0
	v_mov_b32_e32 v89, 0
	s_mov_b32 s47, 0
.Lgv_mod_kh:
	v_and_b32_e32 v111, 63, v251
	v_lshlrev_b32_e32 v111, 2, v111
	v_lshlrev_b32_e32 v112, 2, v251
	s_mov_b64 s[48:49], s[36:37]
	global_load_dword v90, v112, s[48:49]
	s_add_u32 s48, s48, 4096
	s_addc_u32 s49, s49, 0
	global_load_dword v91, v112, s[48:49]
	s_add_u32 s48, s48, 4096
	s_addc_u32 s49, s49, 0
	global_load_dword v92, v112, s[48:49]
	s_add_u32 s48, s48, 4096
	s_addc_u32 s49, s49, 0
	global_load_dword v93, v112, s[48:49]
	s_add_u32 s48, s48, 4096
	s_addc_u32 s49, s49, 0
	global_load_dword v94, v112, s[48:49]
	s_add_u32 s48, s48, 4096
	s_addc_u32 s49, s49, 0
	global_load_dword v95, v112, s[48:49]
	s_add_u32 s48, s48, 4096
	s_addc_u32 s49, s49, 0
	global_load_dword v96, v112, s[48:49]
	s_add_u32 s48, s48, 4096
	s_addc_u32 s49, s49, 0
	global_load_dword v97, v112, s[48:49]
	s_add_u32 s48, s48, 4096
	s_addc_u32 s49, s49, 0
	global_load_dword v98, v112, s[48:49]
	s_add_u32 s48, s48, 4096
	s_addc_u32 s49, s49, 0
	global_load_dword v99, v112, s[48:49]
	s_add_u32 s48, s48, 4096
	s_addc_u32 s49, s49, 0
	global_load_dword v100, v112, s[48:49]
	s_add_u32 s48, s48, 4096
	s_addc_u32 s49, s49, 0
	global_load_dword v101, v112, s[48:49]
	s_add_u32 s48, s48, 4096
	s_addc_u32 s49, s49, 0
	global_load_dword v102, v112, s[48:49]
	s_add_u32 s48, s48, 4096
	s_addc_u32 s49, s49, 0
	global_load_dword v103, v112, s[48:49]
	s_add_u32 s48, s48, 4096
	s_addc_u32 s49, s49, 0
	global_load_dword v108, v112, s[48:49]
	s_add_u32 s48, s48, 4096
	s_addc_u32 s49, s49, 0
	global_load_dword v109, v112, s[48:49]
	s_add_u32 s48, s48, 4096
	s_addc_u32 s49, s49, 0
	global_load_dword v110, v112, s[38:39]
	s_mov_b64 s[50:51], s[40:41]
	global_load_dword v2, v111, s[50:51]
	s_add_u32 s50, s50, 12288
	s_addc_u32 s51, s51, 0
	global_load_dword v3, v111, s[50:51]
	s_add_u32 s50, s50, 12288
	s_addc_u32 s51, s51, 0
	global_load_dword v4, v111, s[50:51]
	s_add_u32 s50, s50, 12288
	s_addc_u32 s51, s51, 0
	global_load_dword v5, v111, s[50:51]
	s_add_u32 s50, s50, 12288
	s_addc_u32 s51, s51, 0
	global_load_dword v6, v111, s[50:51]
	s_add_u32 s50, s50, 12288
	s_addc_u32 s51, s51, 0
	global_load_dword v7, v111, s[50:51]
	s_add_u32 s50, s50, 12288
	s_addc_u32 s51, s51, 0
	global_load_dword v8, v111, s[50:51]
	s_add_u32 s50, s50, 12288
	s_addc_u32 s51, s51, 0
	global_load_dword v9, v111, s[50:51]
	s_add_u32 s50, s50, 12288
	s_addc_u32 s51, s51, 0
	global_load_dword v10, v111, s[50:51]
	s_add_u32 s50, s50, 12288
	s_addc_u32 s51, s51, 0
	global_load_dword v11, v111, s[50:51]
	s_add_u32 s50, s50, 12288
	s_addc_u32 s51, s51, 0
	global_load_dword v12, v111, s[50:51]
	s_add_u32 s50, s50, 12288
	s_addc_u32 s51, s51, 0
	global_load_dword v13, v111, s[50:51]
	s_add_u32 s50, s50, 12288
	s_addc_u32 s51, s51, 0
	global_load_dword v14, v111, s[50:51]
	s_add_u32 s50, s50, 12288
	s_addc_u32 s51, s51, 0
	global_load_dword v15, v111, s[50:51]
	s_add_u32 s50, s50, 12288
	s_addc_u32 s51, s51, 0
	global_load_dword v16, v111, s[50:51]
	s_add_u32 s50, s50, 12288
	s_addc_u32 s51, s51, 0
	global_load_dword v17, v111, s[50:51]
	s_add_u32 s50, s50, 12288
	s_addc_u32 s51, s51, 0
	global_load_dword v18, v111, s[50:51]
	s_add_u32 s50, s50, 12288
	s_addc_u32 s51, s51, 0
	global_load_dword v19, v111, s[50:51]
	s_add_u32 s50, s50, 12288
	s_addc_u32 s51, s51, 0
	global_load_dword v20, v111, s[50:51]
	s_add_u32 s50, s50, 12288
	s_addc_u32 s51, s51, 0
	global_load_dword v21, v111, s[50:51]
	s_add_u32 s50, s50, 12288
	s_addc_u32 s51, s51, 0
	global_load_dword v22, v111, s[50:51]
	s_add_u32 s50, s50, 12288
	s_addc_u32 s51, s51, 0
	global_load_dword v23, v111, s[50:51]
	s_add_u32 s50, s50, 12288
	s_addc_u32 s51, s51, 0
	global_load_dword v24, v111, s[50:51]
	s_add_u32 s50, s50, 12288
	s_addc_u32 s51, s51, 0
	global_load_dword v25, v111, s[50:51]
	s_add_u32 s50, s50, 12288
	s_addc_u32 s51, s51, 0
	global_load_dword v26, v111, s[50:51]
	s_add_u32 s50, s50, 12288
	s_addc_u32 s51, s51, 0
	global_load_dword v27, v111, s[50:51]
	s_add_u32 s50, s50, 12288
	s_addc_u32 s51, s51, 0
	global_load_dword v28, v111, s[50:51]
	s_add_u32 s50, s50, 12288
	s_addc_u32 s51, s51, 0
	global_load_dword v29, v111, s[50:51]
	s_add_u32 s50, s50, 12288
	s_addc_u32 s51, s51, 0
	global_load_dword v30, v111, s[50:51]
	s_add_u32 s50, s50, 12288
	s_addc_u32 s51, s51, 0
	global_load_dword v31, v111, s[50:51]
	s_add_u32 s50, s50, 12288
	s_addc_u32 s51, s51, 0
	global_load_dword v32, v111, s[50:51]
	s_add_u32 s50, s50, 12288
	s_addc_u32 s51, s51, 0
	global_load_dword v33, v111, s[50:51]
	s_add_u32 s50, s50, 12288
	s_addc_u32 s51, s51, 0
	s_waitcnt vmcnt(32)
; DI void gemv17(const float* in16, int istride, const float* in1, bool do_silu, const float* W, int ldw, int n0,
;                const float* bvec, float* out, int ostride, char* lds) {
;     ...
;     for (int e = tid; e < 17 * 512; e += NTHREADS) {
;       const int j = e >> 9, k = e & 511;
;       float v = (j < 16) ? in16[(size_t)j * istride + kh * 512 + k] : in1[kh * 512 + k];
;       if (do_silu) v = v / (1.f + expf(-v));
;       sc[e] = v;
;     }
;     __syncthreads();
	v_mul_f32_e32 v34, 0xbfb8aa3b, v90
	v_fma_f32 v35, v90, s25, -v34
	v_rndne_f32_e32 v36, v34
	v_fmac_f32_e32 v35, 0xb2a5705f, v90
	v_sub_f32_e32 v34, v34, v36
	v_add_f32_e32 v34, v34, v35
	v_exp_f32_e32 v34, v34
	v_cvt_i32_f32_e32 v35, v36
	v_cmp_nlt_f32_e32 vcc, s96, v90
	v_ldexp_f32 v34, v34, v35
	s_nop 0
	v_cndmask_b32_e32 v34, 0, v34, vcc
	v_cmp_ngt_f32_e32 vcc, s97, v90
	s_nop 1
	v_cndmask_b32_e32 v34, v250, v34, vcc
	v_add_f32_e32 v34, 1.0, v34
	v_div_scale_f32 v35, s[2:3], v34, v34, v90
	v_rcp_f32_e32 v36, v35
	s_nop 0
	v_fma_f32 v37, -v35, v36, 1.0
	v_fmac_f32_e32 v36, v37, v36
	v_div_scale_f32 v37, vcc, v90, v34, v90
	v_mul_f32_e32 v38, v37, v36
	v_fma_f32 v39, -v35, v38, v37
	v_fmac_f32_e32 v38, v39, v36
	v_fma_f32 v35, -v35, v38, v37
	v_div_fmas_f32 v35, v35, v36, v38
	v_div_fixup_f32 v90, v35, v34, v90
	v_mul_f32_e32 v34, 0xbfb8aa3b, v91
	v_fma_f32 v35, v91, s25, -v34
	v_rndne_f32_e32 v36, v34
	v_fmac_f32_e32 v35, 0xb2a5705f, v91
	v_sub_f32_e32 v34, v34, v36
	v_add_f32_e32 v34, v34, v35
	v_exp_f32_e32 v34, v34
	v_cvt_i32_f32_e32 v35, v36
	v_cmp_nlt_f32_e32 vcc, s96, v91
	v_ldexp_f32 v34, v34, v35
	s_nop 0
	v_cndmask_b32_e32 v34, 0, v34, vcc
	v_cmp_ngt_f32_e32 vcc, s97, v91
	s_nop 1
	v_cndmask_b32_e32 v34, v250, v34, vcc
	v_add_f32_e32 v34, 1.0, v34
	v_div_scale_f32 v35, s[2:3], v34, v34, v91
	v_rcp_f32_e32 v36, v35
	s_nop 0
	v_fma_f32 v37, -v35, v36, 1.0
	v_fmac_f32_e32 v36, v37, v36
	v_div_scale_f32 v37, vcc, v91, v34, v91
	v_mul_f32_e32 v38, v37, v36
	v_fma_f32 v39, -v35, v38, v37
	v_fmac_f32_e32 v38, v39, v36
	v_fma_f32 v35, -v35, v38, v37
	v_div_fmas_f32 v35, v35, v36, v38
	v_div_fixup_f32 v91, v35, v34, v91
	v_mul_f32_e32 v34, 0xbfb8aa3b, v92
	v_fma_f32 v35, v92, s25, -v34
	v_rndne_f32_e32 v36, v34
	v_fmac_f32_e32 v35, 0xb2a5705f, v92
	v_sub_f32_e32 v34, v34, v36
	v_add_f32_e32 v34, v34, v35
	v_exp_f32_e32 v34, v34
	v_cvt_i32_f32_e32 v35, v36
	v_cmp_nlt_f32_e32 vcc, s96, v92
	v_ldexp_f32 v34, v34, v35
	s_nop 0
	v_cndmask_b32_e32 v34, 0, v34, vcc
	v_cmp_ngt_f32_e32 vcc, s97, v92
	s_nop 1
	v_cndmask_b32_e32 v34, v250, v34, vcc
	v_add_f32_e32 v34, 1.0, v34
	v_div_scale_f32 v35, s[2:3], v34, v34, v92
	v_rcp_f32_e32 v36, v35
	s_nop 0
	v_fma_f32 v37, -v35, v36, 1.0
	v_fmac_f32_e32 v36, v37, v36
	v_div_scale_f32 v37, vcc, v92, v34, v92
	v_mul_f32_e32 v38, v37, v36
	v_fma_f32 v39, -v35, v38, v37
	v_fmac_f32_e32 v38, v39, v36
	v_fma_f32 v35, -v35, v38, v37
	v_div_fmas_f32 v35, v35, v36, v38
	v_div_fixup_f32 v92, v35, v34, v92
	v_mul_f32_e32 v34, 0xbfb8aa3b, v93
	v_fma_f32 v35, v93, s25, -v34
	v_rndne_f32_e32 v36, v34
	v_fmac_f32_e32 v35, 0xb2a5705f, v93
	v_sub_f32_e32 v34, v34, v36
	v_add_f32_e32 v34, v34, v35
	v_exp_f32_e32 v34, v34
	v_cvt_i32_f32_e32 v35, v36
	v_cmp_nlt_f32_e32 vcc, s96, v93
	v_ldexp_f32 v34, v34, v35
	s_nop 0
	v_cndmask_b32_e32 v34, 0, v34, vcc
	v_cmp_ngt_f32_e32 vcc, s97, v93
	s_nop 1
	v_cndmask_b32_e32 v34, v250, v34, vcc
	v_add_f32_e32 v34, 1.0, v34
	v_div_scale_f32 v35, s[2:3], v34, v34, v93
	v_rcp_f32_e32 v36, v35
	s_nop 0
	v_fma_f32 v37, -v35, v36, 1.0
	v_fmac_f32_e32 v36, v37, v36
	v_div_scale_f32 v37, vcc, v93, v34, v93
	v_mul_f32_e32 v38, v37, v36
	v_fma_f32 v39, -v35, v38, v37
	v_fmac_f32_e32 v38, v39, v36
	v_fma_f32 v35, -v35, v38, v37
	v_div_fmas_f32 v35, v35, v36, v38
	v_div_fixup_f32 v93, v35, v34, v93
	v_mul_f32_e32 v34, 0xbfb8aa3b, v94
	v_fma_f32 v35, v94, s25, -v34
	v_rndne_f32_e32 v36, v34
	v_fmac_f32_e32 v35, 0xb2a5705f, v94
	v_sub_f32_e32 v34, v34, v36
	v_add_f32_e32 v34, v34, v35
	v_exp_f32_e32 v34, v34
	v_cvt_i32_f32_e32 v35, v36
	v_cmp_nlt_f32_e32 vcc, s96, v94
	v_ldexp_f32 v34, v34, v35
	s_nop 0
	v_cndmask_b32_e32 v34, 0, v34, vcc
	v_cmp_ngt_f32_e32 vcc, s97, v94
	s_nop 1
	v_cndmask_b32_e32 v34, v250, v34, vcc
	v_add_f32_e32 v34, 1.0, v34
	v_div_scale_f32 v35, s[2:3], v34, v34, v94
	v_rcp_f32_e32 v36, v35
	s_nop 0
	v_fma_f32 v37, -v35, v36, 1.0
	v_fmac_f32_e32 v36, v37, v36
	v_div_scale_f32 v37, vcc, v94, v34, v94
	v_mul_f32_e32 v38, v37, v36
	v_fma_f32 v39, -v35, v38, v37
	v_fmac_f32_e32 v38, v39, v36
	v_fma_f32 v35, -v35, v38, v37
	v_div_fmas_f32 v35, v35, v36, v38
	v_div_fixup_f32 v94, v35, v34, v94
	v_mul_f32_e32 v34, 0xbfb8aa3b, v95
	v_fma_f32 v35, v95, s25, -v34
	v_rndne_f32_e32 v36, v34
	v_fmac_f32_e32 v35, 0xb2a5705f, v95
	v_sub_f32_e32 v34, v34, v36
	v_add_f32_e32 v34, v34, v35
	v_exp_f32_e32 v34, v34
	v_cvt_i32_f32_e32 v35, v36
	v_cmp_nlt_f32_e32 vcc, s96, v95
	v_ldexp_f32 v34, v34, v35
	s_nop 0
	v_cndmask_b32_e32 v34, 0, v34, vcc
	v_cmp_ngt_f32_e32 vcc, s97, v95
	s_nop 1
	v_cndmask_b32_e32 v34, v250, v34, vcc
	v_add_f32_e32 v34, 1.0, v34
	v_div_scale_f32 v35, s[2:3], v34, v34, v95
	v_rcp_f32_e32 v36, v35
	s_nop 0
	v_fma_f32 v37, -v35, v36, 1.0
	v_fmac_f32_e32 v36, v37, v36
	v_div_scale_f32 v37, vcc, v95, v34, v95
	v_mul_f32_e32 v38, v37, v36
	v_fma_f32 v39, -v35, v38, v37
	v_fmac_f32_e32 v38, v39, v36
	v_fma_f32 v35, -v35, v38, v37
	v_div_fmas_f32 v35, v35, v36, v38
	v_div_fixup_f32 v95, v35, v34, v95
	v_mul_f32_e32 v34, 0xbfb8aa3b, v96
	v_fma_f32 v35, v96, s25, -v34
	v_rndne_f32_e32 v36, v34
	v_fmac_f32_e32 v35, 0xb2a5705f, v96
	v_sub_f32_e32 v34, v34, v36
	v_add_f32_e32 v34, v34, v35
	v_exp_f32_e32 v34, v34
	v_cvt_i32_f32_e32 v35, v36
	v_cmp_nlt_f32_e32 vcc, s96, v96
	v_ldexp_f32 v34, v34, v35
	s_nop 0
	v_cndmask_b32_e32 v34, 0, v34, vcc
	v_cmp_ngt_f32_e32 vcc, s97, v96
	s_nop 1
	v_cndmask_b32_e32 v34, v250, v34, vcc
	v_add_f32_e32 v34, 1.0, v34
	v_div_scale_f32 v35, s[2:3], v34, v34, v96
	v_rcp_f32_e32 v36, v35
	s_nop 0
	v_fma_f32 v37, -v35, v36, 1.0
	v_fmac_f32_e32 v36, v37, v36
	v_div_scale_f32 v37, vcc, v96, v34, v96
	v_mul_f32_e32 v38, v37, v36
	v_fma_f32 v39, -v35, v38, v37
; DI void gemv17(const float* in16, int istride, const float* in1, bool do_silu, const float* W, int ldw, int n0,
;                const float* bvec, float* out, int ostride, char* lds) {
;     ...
;       float v = (j < 16) ? in16[(size_t)j * istride + kh * 512 + k] : in1[kh * 512 + k];
;       if (do_silu) v = v / (1.f + expf(-v));
	v_fmac_f32_e32 v38, v39, v36
	v_fma_f32 v35, -v35, v38, v37
	v_div_fmas_f32 v35, v35, v36, v38
	v_div_fixup_f32 v96, v35, v34, v96
	v_mul_f32_e32 v34, 0xbfb8aa3b, v97
	v_fma_f32 v35, v97, s25, -v34
	v_rndne_f32_e32 v36, v34
	v_fmac_f32_e32 v35, 0xb2a5705f, v97
	v_sub_f32_e32 v34, v34, v36
	v_add_f32_e32 v34, v34, v35
	v_exp_f32_e32 v34, v34
	v_cvt_i32_f32_e32 v35, v36
	v_cmp_nlt_f32_e32 vcc, s96, v97
	v_ldexp_f32 v34, v34, v35
	s_nop 0
	v_cndmask_b32_e32 v34, 0, v34, vcc
	v_cmp_ngt_f32_e32 vcc, s97, v97
	s_nop 1
	v_cndmask_b32_e32 v34, v250, v34, vcc
	v_add_f32_e32 v34, 1.0, v34
	v_div_scale_f32 v35, s[2:3], v34, v34, v97
	v_rcp_f32_e32 v36, v35
	s_nop 0
	v_fma_f32 v37, -v35, v36, 1.0
	v_fmac_f32_e32 v36, v37, v36
	v_div_scale_f32 v37, vcc, v97, v34, v97
	v_mul_f32_e32 v38, v37, v36
	v_fma_f32 v39, -v35, v38, v37
	v_fmac_f32_e32 v38, v39, v36
	v_fma_f32 v35, -v35, v38, v37
	v_div_fmas_f32 v35, v35, v36, v38
	v_div_fixup_f32 v97, v35, v34, v97
	v_mul_f32_e32 v34, 0xbfb8aa3b, v98
	v_fma_f32 v35, v98, s25, -v34
	v_rndne_f32_e32 v36, v34
	v_fmac_f32_e32 v35, 0xb2a5705f, v98
	v_sub_f32_e32 v34, v34, v36
	v_add_f32_e32 v34, v34, v35
	v_exp_f32_e32 v34, v34
	v_cvt_i32_f32_e32 v35, v36
	v_cmp_nlt_f32_e32 vcc, s96, v98
	v_ldexp_f32 v34, v34, v35
	s_nop 0
	v_cndmask_b32_e32 v34, 0, v34, vcc
	v_cmp_ngt_f32_e32 vcc, s97, v98
	s_nop 1
	v_cndmask_b32_e32 v34, v250, v34, vcc
	v_add_f32_e32 v34, 1.0, v34
	v_div_scale_f32 v35, s[2:3], v34, v34, v98
	v_rcp_f32_e32 v36, v35
	s_nop 0
	v_fma_f32 v37, -v35, v36, 1.0
	v_fmac_f32_e32 v36, v37, v36
	v_div_scale_f32 v37, vcc, v98, v34, v98
	v_mul_f32_e32 v38, v37, v36
	v_fma_f32 v39, -v35, v38, v37
	v_fmac_f32_e32 v38, v39, v36
	v_fma_f32 v35, -v35, v38, v37
	v_div_fmas_f32 v35, v35, v36, v38
	v_div_fixup_f32 v98, v35, v34, v98
	v_mul_f32_e32 v34, 0xbfb8aa3b, v99
	v_fma_f32 v35, v99, s25, -v34
	v_rndne_f32_e32 v36, v34
	v_fmac_f32_e32 v35, 0xb2a5705f, v99
	v_sub_f32_e32 v34, v34, v36
	v_add_f32_e32 v34, v34, v35
	v_exp_f32_e32 v34, v34
	v_cvt_i32_f32_e32 v35, v36
	v_cmp_nlt_f32_e32 vcc, s96, v99
	v_ldexp_f32 v34, v34, v35
	s_nop 0
	v_cndmask_b32_e32 v34, 0, v34, vcc
	v_cmp_ngt_f32_e32 vcc, s97, v99
	s_nop 1
	v_cndmask_b32_e32 v34, v250, v34, vcc
	v_add_f32_e32 v34, 1.0, v34
	v_div_scale_f32 v35, s[2:3], v34, v34, v99
	v_rcp_f32_e32 v36, v35
	s_nop 0
	v_fma_f32 v37, -v35, v36, 1.0
	v_fmac_f32_e32 v36, v37, v36
	v_div_scale_f32 v37, vcc, v99, v34, v99
	v_mul_f32_e32 v38, v37, v36
	v_fma_f32 v39, -v35, v38, v37
	v_fmac_f32_e32 v38, v39, v36
	v_fma_f32 v35, -v35, v38, v37
	v_div_fmas_f32 v35, v35, v36, v38
	v_div_fixup_f32 v99, v35, v34, v99
	v_mul_f32_e32 v34, 0xbfb8aa3b, v100
	v_fma_f32 v35, v100, s25, -v34
	v_rndne_f32_e32 v36, v34
	v_fmac_f32_e32 v35, 0xb2a5705f, v100
	v_sub_f32_e32 v34, v34, v36
	v_add_f32_e32 v34, v34, v35
	v_exp_f32_e32 v34, v34
	v_cvt_i32_f32_e32 v35, v36
	v_cmp_nlt_f32_e32 vcc, s96, v100
	v_ldexp_f32 v34, v34, v35
	s_nop 0
	v_cndmask_b32_e32 v34, 0, v34, vcc
	v_cmp_ngt_f32_e32 vcc, s97, v100
	s_nop 1
	v_cndmask_b32_e32 v34, v250, v34, vcc
	v_add_f32_e32 v34, 1.0, v34
	v_div_scale_f32 v35, s[2:3], v34, v34, v100
	v_rcp_f32_e32 v36, v35
	s_nop 0
	v_fma_f32 v37, -v35, v36, 1.0
	v_fmac_f32_e32 v36, v37, v36
	v_div_scale_f32 v37, vcc, v100, v34, v100
	v_mul_f32_e32 v38, v37, v36
	v_fma_f32 v39, -v35, v38, v37
	v_fmac_f32_e32 v38, v39, v36
	v_fma_f32 v35, -v35, v38, v37
	v_div_fmas_f32 v35, v35, v36, v38
	v_div_fixup_f32 v100, v35, v34, v100
	v_mul_f32_e32 v34, 0xbfb8aa3b, v101
	v_fma_f32 v35, v101, s25, -v34
	v_rndne_f32_e32 v36, v34
	v_fmac_f32_e32 v35, 0xb2a5705f, v101
	v_sub_f32_e32 v34, v34, v36
	v_add_f32_e32 v34, v34, v35
	v_exp_f32_e32 v34, v34
	v_cvt_i32_f32_e32 v35, v36
	v_cmp_nlt_f32_e32 vcc, s96, v101
	v_ldexp_f32 v34, v34, v35
	s_nop 0
	v_cndmask_b32_e32 v34, 0, v34, vcc
	v_cmp_ngt_f32_e32 vcc, s97, v101
	s_nop 1
	v_cndmask_b32_e32 v34, v250, v34, vcc
	v_add_f32_e32 v34, 1.0, v34
	v_div_scale_f32 v35, s[2:3], v34, v34, v101
	v_rcp_f32_e32 v36, v35
	s_nop 0
	v_fma_f32 v37, -v35, v36, 1.0
	v_fmac_f32_e32 v36, v37, v36
	v_div_scale_f32 v37, vcc, v101, v34, v101
	v_mul_f32_e32 v38, v37, v36
	v_fma_f32 v39, -v35, v38, v37
	v_fmac_f32_e32 v38, v39, v36
	v_fma_f32 v35, -v35, v38, v37
	v_div_fmas_f32 v35, v35, v36, v38
	v_div_fixup_f32 v101, v35, v34, v101
	v_mul_f32_e32 v34, 0xbfb8aa3b, v102
	v_fma_f32 v35, v102, s25, -v34
	v_rndne_f32_e32 v36, v34
	v_fmac_f32_e32 v35, 0xb2a5705f, v102
	v_sub_f32_e32 v34, v34, v36
	v_add_f32_e32 v34, v34, v35
	v_exp_f32_e32 v34, v34
	v_cvt_i32_f32_e32 v35, v36
	v_cmp_nlt_f32_e32 vcc, s96, v102
	v_ldexp_f32 v34, v34, v35
	s_nop 0
	v_cndmask_b32_e32 v34, 0, v34, vcc
	v_cmp_ngt_f32_e32 vcc, s97, v102
	s_nop 1
	v_cndmask_b32_e32 v34, v250, v34, vcc
	v_add_f32_e32 v34, 1.0, v34
	v_div_scale_f32 v35, s[2:3], v34, v34, v102
	v_rcp_f32_e32 v36, v35
	s_nop 0
	v_fma_f32 v37, -v35, v36, 1.0
	v_fmac_f32_e32 v36, v37, v36
	v_div_scale_f32 v37, vcc, v102, v34, v102
	v_mul_f32_e32 v38, v37, v36
	v_fma_f32 v39, -v35, v38, v37
	v_fmac_f32_e32 v38, v39, v36
	v_fma_f32 v35, -v35, v38, v37
	v_div_fmas_f32 v35, v35, v36, v38
	v_div_fixup_f32 v102, v35, v34, v102
	v_mul_f32_e32 v34, 0xbfb8aa3b, v103
	v_fma_f32 v35, v103, s25, -v34
	v_rndne_f32_e32 v36, v34
	v_fmac_f32_e32 v35, 0xb2a5705f, v103
	v_sub_f32_e32 v34, v34, v36
	v_add_f32_e32 v34, v34, v35
	v_exp_f32_e32 v34, v34
	v_cvt_i32_f32_e32 v35, v36
	v_cmp_nlt_f32_e32 vcc, s96, v103
	v_ldexp_f32 v34, v34, v35
	s_nop 0
	v_cndmask_b32_e32 v34, 0, v34, vcc
	v_cmp_ngt_f32_e32 vcc, s97, v103
	s_nop 1
	v_cndmask_b32_e32 v34, v250, v34, vcc
	v_add_f32_e32 v34, 1.0, v34
	v_div_scale_f32 v35, s[2:3], v34, v34, v103
	v_rcp_f32_e32 v36, v35
; DI void gemv17(const float* in16, int istride, const float* in1, bool do_silu, const float* W, int ldw, int n0,
;                const float* bvec, float* out, int ostride, char* lds) {
;     ...
;     __syncthreads();
;     for (int e = tid; e < 17 * 512; e += NTHREADS) {
;       const int j = e >> 9, k = e & 511;
;       float v = (j < 16) ? in16[(size_t)j * istride + kh * 512 + k] : in1[kh * 512 + k];
;       if (do_silu) v = v / (1.f + expf(-v));
;       sc[e] = v;
;     }
;     __syncthreads();
;     const float* wp = W + (size_t)(kh * 512 + kp * 64) * ldw + n0 + col;
; #pragma unroll 16
;     for (int kk = 0; kk < 64; ++kk) {
;       const float wv = wp[(size_t)kk * ldw];
	s_nop 0
	v_fma_f32 v37, -v35, v36, 1.0
	v_fmac_f32_e32 v36, v37, v36
	v_div_scale_f32 v37, vcc, v103, v34, v103
	v_mul_f32_e32 v38, v37, v36
	v_fma_f32 v39, -v35, v38, v37
	v_fmac_f32_e32 v38, v39, v36
	v_fma_f32 v35, -v35, v38, v37
	v_div_fmas_f32 v35, v35, v36, v38
	v_div_fixup_f32 v103, v35, v34, v103
	v_mul_f32_e32 v34, 0xbfb8aa3b, v108
	v_fma_f32 v35, v108, s25, -v34
	v_rndne_f32_e32 v36, v34
	v_fmac_f32_e32 v35, 0xb2a5705f, v108
	v_sub_f32_e32 v34, v34, v36
	v_add_f32_e32 v34, v34, v35
	v_exp_f32_e32 v34, v34
	v_cvt_i32_f32_e32 v35, v36
	v_cmp_nlt_f32_e32 vcc, s96, v108
	v_ldexp_f32 v34, v34, v35
	s_nop 0
	v_cndmask_b32_e32 v34, 0, v34, vcc
	v_cmp_ngt_f32_e32 vcc, s97, v108
	s_nop 1
	v_cndmask_b32_e32 v34, v250, v34, vcc
	v_add_f32_e32 v34, 1.0, v34
	v_div_scale_f32 v35, s[2:3], v34, v34, v108
	v_rcp_f32_e32 v36, v35
	s_nop 0
	v_fma_f32 v37, -v35, v36, 1.0
	v_fmac_f32_e32 v36, v37, v36
	v_div_scale_f32 v37, vcc, v108, v34, v108
	v_mul_f32_e32 v38, v37, v36
	v_fma_f32 v39, -v35, v38, v37
	v_fmac_f32_e32 v38, v39, v36
	v_fma_f32 v35, -v35, v38, v37
	v_div_fmas_f32 v35, v35, v36, v38
	v_div_fixup_f32 v108, v35, v34, v108
	v_mul_f32_e32 v34, 0xbfb8aa3b, v109
	v_fma_f32 v35, v109, s25, -v34
	v_rndne_f32_e32 v36, v34
	v_fmac_f32_e32 v35, 0xb2a5705f, v109
	v_sub_f32_e32 v34, v34, v36
	v_add_f32_e32 v34, v34, v35
	v_exp_f32_e32 v34, v34
	v_cvt_i32_f32_e32 v35, v36
	v_cmp_nlt_f32_e32 vcc, s96, v109
	v_ldexp_f32 v34, v34, v35
	s_nop 0
	v_cndmask_b32_e32 v34, 0, v34, vcc
	v_cmp_ngt_f32_e32 vcc, s97, v109
	s_nop 1
	v_cndmask_b32_e32 v34, v250, v34, vcc
	v_add_f32_e32 v34, 1.0, v34
	v_div_scale_f32 v35, s[2:3], v34, v34, v109
	v_rcp_f32_e32 v36, v35
	s_nop 0
	v_fma_f32 v37, -v35, v36, 1.0
	v_fmac_f32_e32 v36, v37, v36
	v_div_scale_f32 v37, vcc, v109, v34, v109
	v_mul_f32_e32 v38, v37, v36
	v_fma_f32 v39, -v35, v38, v37
	v_fmac_f32_e32 v38, v39, v36
	v_fma_f32 v35, -v35, v38, v37
	v_div_fmas_f32 v35, v35, v36, v38
	v_div_fixup_f32 v109, v35, v34, v109
	v_mul_f32_e32 v34, 0xbfb8aa3b, v110
	v_fma_f32 v35, v110, s25, -v34
	v_rndne_f32_e32 v36, v34
	v_fmac_f32_e32 v35, 0xb2a5705f, v110
	v_sub_f32_e32 v34, v34, v36
	v_add_f32_e32 v34, v34, v35
	v_exp_f32_e32 v34, v34
	v_cvt_i32_f32_e32 v35, v36
	v_cmp_nlt_f32_e32 vcc, s96, v110
	v_ldexp_f32 v34, v34, v35
	s_nop 0
	v_cndmask_b32_e32 v34, 0, v34, vcc
	v_cmp_ngt_f32_e32 vcc, s97, v110
	s_nop 1
	v_cndmask_b32_e32 v34, v250, v34, vcc
	v_add_f32_e32 v34, 1.0, v34
	v_div_scale_f32 v35, s[2:3], v34, v34, v110
	v_rcp_f32_e32 v36, v35
	s_nop 0
	v_fma_f32 v37, -v35, v36, 1.0
	v_fmac_f32_e32 v36, v37, v36
	v_div_scale_f32 v37, vcc, v110, v34, v110
	v_mul_f32_e32 v38, v37, v36
	v_fma_f32 v39, -v35, v38, v37
	v_fmac_f32_e32 v38, v39, v36
	v_fma_f32 v35, -v35, v38, v37
	v_div_fmas_f32 v35, v35, v36, v38
	v_div_fixup_f32 v110, v35, v34, v110
	s_barrier
	ds_write_b32 v112, v90
	ds_write_b32 v112, v91 offset:2048
	ds_write_b32 v112, v92 offset:4096
	ds_write_b32 v112, v93 offset:6144
	ds_write_b32 v112, v94 offset:8192
	ds_write_b32 v112, v95 offset:10240
	ds_write_b32 v112, v96 offset:12288
	ds_write_b32 v112, v97 offset:14336
	ds_write_b32 v112, v98 offset:16384
	ds_write_b32 v112, v99 offset:18432
	ds_write_b32 v112, v100 offset:20480
	ds_write_b32 v112, v101 offset:22528
	ds_write_b32 v112, v102 offset:24576
	ds_write_b32 v112, v103 offset:26624
	ds_write_b32 v112, v108 offset:28672
	ds_write_b32 v112, v109 offset:30720
	ds_write_b32 v112, v110 offset:32768
	global_load_dword v34, v111, s[50:51]
	s_add_u32 s50, s50, 12288
	s_addc_u32 s51, s51, 0
	global_load_dword v35, v111, s[50:51]
	s_add_u32 s50, s50, 12288
	s_addc_u32 s51, s51, 0
	global_load_dword v36, v111, s[50:51]
	s_add_u32 s50, s50, 12288
	s_addc_u32 s51, s51, 0
	global_load_dword v37, v111, s[50:51]
	s_add_u32 s50, s50, 12288
	s_addc_u32 s51, s51, 0
	global_load_dword v38, v111, s[50:51]
	s_add_u32 s50, s50, 12288
	s_addc_u32 s51, s51, 0
	global_load_dword v39, v111, s[50:51]
	s_add_u32 s50, s50, 12288
	s_addc_u32 s51, s51, 0
	global_load_dword v40, v111, s[50:51]
	s_add_u32 s50, s50, 12288
	s_addc_u32 s51, s51, 0
	global_load_dword v41, v111, s[50:51]
	s_add_u32 s50, s50, 12288
	s_addc_u32 s51, s51, 0
	global_load_dword v42, v111, s[50:51]
	s_add_u32 s50, s50, 12288
	s_addc_u32 s51, s51, 0
	global_load_dword v43, v111, s[50:51]
	s_add_u32 s50, s50, 12288
	s_addc_u32 s51, s51, 0
	global_load_dword v44, v111, s[50:51]
	s_add_u32 s50, s50, 12288
	s_addc_u32 s51, s51, 0
	global_load_dword v45, v111, s[50:51]
	s_add_u32 s50, s50, 12288
	s_addc_u32 s51, s51, 0
	global_load_dword v46, v111, s[50:51]
	s_add_u32 s50, s50, 12288
	s_addc_u32 s51, s51, 0
	global_load_dword v47, v111, s[50:51]
	s_add_u32 s50, s50, 12288
	s_addc_u32 s51, s51, 0
	global_load_dword v48, v111, s[50:51]
	s_add_u32 s50, s50, 12288
	s_addc_u32 s51, s51, 0
	global_load_dword v49, v111, s[50:51]
	s_add_u32 s50, s50, 12288
	s_addc_u32 s51, s51, 0
	global_load_dword v50, v111, s[50:51]
	s_add_u32 s50, s50, 12288
	s_addc_u32 s51, s51, 0
	global_load_dword v51, v111, s[50:51]
	s_add_u32 s50, s50, 12288
	s_addc_u32 s51, s51, 0
	global_load_dword v52, v111, s[50:51]
	s_add_u32 s50, s50, 12288
	s_addc_u32 s51, s51, 0
	global_load_dword v53, v111, s[50:51]
	s_add_u32 s50, s50, 12288
	s_addc_u32 s51, s51, 0
	global_load_dword v54, v111, s[50:51]
	s_add_u32 s50, s50, 12288
	s_addc_u32 s51, s51, 0
	global_load_dword v55, v111, s[50:51]
	s_add_u32 s50, s50, 12288
	s_addc_u32 s51, s51, 0
	global_load_dword v56, v111, s[50:51]
	s_add_u32 s50, s50, 12288
	s_addc_u32 s51, s51, 0
	global_load_dword v57, v111, s[50:51]
	s_add_u32 s50, s50, 12288
	s_addc_u32 s51, s51, 0
	global_load_dword v58, v111, s[50:51]
	s_add_u32 s50, s50, 12288
	s_addc_u32 s51, s51, 0
	global_load_dword v59, v111, s[50:51]
	s_add_u32 s50, s50, 12288
	s_addc_u32 s51, s51, 0
	global_load_dword v60, v111, s[50:51]
	s_add_u32 s50, s50, 12288
	s_addc_u32 s51, s51, 0
	global_load_dword v61, v111, s[50:51]
	s_add_u32 s50, s50, 12288
	s_addc_u32 s51, s51, 0
	global_load_dword v62, v111, s[50:51]
	s_add_u32 s50, s50, 12288
	s_addc_u32 s51, s51, 0
	global_load_dword v63, v111, s[50:51]
	s_add_u32 s50, s50, 12288
	s_addc_u32 s51, s51, 0
	global_load_dword v64, v111, s[50:51]
	s_add_u32 s50, s50, 12288
	s_addc_u32 s51, s51, 0
	global_load_dword v65, v111, s[50:51]
	v_lshrrev_b32_e32 v0, 6, v251
	v_lshlrev_b32_e32 v113, 8, v0
	s_waitcnt lgkmcnt(0)
	s_barrier
; DI void gemv17(const float* in16, int istride, const float* in1, bool do_silu, const float* W, int ldw, int n0,
;                const float* bvec, float* out, int ostride, char* lds) {
;     ...
; #pragma unroll 16
;     for (int kk = 0; kk < 64; ++kk) {
;       const float wv = wp[(size_t)kk * ldw];
;       const float* sp = sc + kp * 64 + kk;
; #pragma unroll
;       for (int j = 0; j < 17; ++j) acc[j] += sp[j * 512] * wv;
;     }
	ds_read_b128 v[90:93], v113 offset:0
	ds_read_b128 v[94:97], v113 offset:2048
	ds_read_b128 v[98:101], v113 offset:4096
	ds_read_b128 v[108:111], v113 offset:6144
	s_waitcnt vmcnt(60)
	s_waitcnt lgkmcnt(3)
	v_fmac_f32_e32 v66, v90, v2
	v_fmac_f32_e32 v66, v91, v3
	v_fmac_f32_e32 v66, v92, v4
	v_fmac_f32_e32 v66, v93, v5
	ds_read_b128 v[90:93], v113 offset:8192
	s_waitcnt lgkmcnt(3)
	v_fmac_f32_e32 v67, v94, v2
	v_fmac_f32_e32 v67, v95, v3
	v_fmac_f32_e32 v67, v96, v4
	v_fmac_f32_e32 v67, v97, v5
	ds_read_b128 v[94:97], v113 offset:10240
	s_waitcnt lgkmcnt(3)
	v_fmac_f32_e32 v68, v98, v2
	v_fmac_f32_e32 v68, v99, v3
	v_fmac_f32_e32 v68, v100, v4
	v_fmac_f32_e32 v68, v101, v5
	ds_read_b128 v[98:101], v113 offset:12288
	s_waitcnt lgkmcnt(3)
	v_fmac_f32_e32 v69, v108, v2
	v_fmac_f32_e32 v69, v109, v3
	v_fmac_f32_e32 v69, v110, v4
	v_fmac_f32_e32 v69, v111, v5
	ds_read_b128 v[108:111], v113 offset:14336
	s_waitcnt lgkmcnt(3)
	v_fmac_f32_e32 v70, v90, v2
	v_fmac_f32_e32 v70, v91, v3
	v_fmac_f32_e32 v70, v92, v4
	v_fmac_f32_e32 v70, v93, v5
	ds_read_b128 v[90:93], v113 offset:16384
	s_waitcnt lgkmcnt(3)
	v_fmac_f32_e32 v71, v94, v2
	v_fmac_f32_e32 v71, v95, v3
	v_fmac_f32_e32 v71, v96, v4
	v_fmac_f32_e32 v71, v97, v5
	ds_read_b128 v[94:97], v113 offset:18432
	s_waitcnt lgkmcnt(3)
	v_fmac_f32_e32 v72, v98, v2
	v_fmac_f32_e32 v72, v99, v3
	v_fmac_f32_e32 v72, v100, v4
	v_fmac_f32_e32 v72, v101, v5
	ds_read_b128 v[98:101], v113 offset:20480
	s_waitcnt lgkmcnt(3)
	v_fmac_f32_e32 v73, v108, v2
	v_fmac_f32_e32 v73, v109, v3
	v_fmac_f32_e32 v73, v110, v4
	v_fmac_f32_e32 v73, v111, v5
	ds_read_b128 v[108:111], v113 offset:22528
	s_waitcnt lgkmcnt(3)
	v_fmac_f32_e32 v74, v90, v2
	v_fmac_f32_e32 v74, v91, v3
	v_fmac_f32_e32 v74, v92, v4
	v_fmac_f32_e32 v74, v93, v5
	ds_read_b128 v[90:93], v113 offset:24576
	s_waitcnt lgkmcnt(3)
	v_fmac_f32_e32 v75, v94, v2
	v_fmac_f32_e32 v75, v95, v3
	v_fmac_f32_e32 v75, v96, v4
	v_fmac_f32_e32 v75, v97, v5
	ds_read_b128 v[94:97], v113 offset:26624
	s_waitcnt lgkmcnt(3)
	v_fmac_f32_e32 v76, v98, v2
	v_fmac_f32_e32 v76, v99, v3
	v_fmac_f32_e32 v76, v100, v4
	v_fmac_f32_e32 v76, v101, v5
	ds_read_b128 v[98:101], v113 offset:28672
	s_waitcnt lgkmcnt(3)
	v_fmac_f32_e32 v77, v108, v2
	v_fmac_f32_e32 v77, v109, v3
	v_fmac_f32_e32 v77, v110, v4
	v_fmac_f32_e32 v77, v111, v5
	ds_read_b128 v[108:111], v113 offset:30720
	s_waitcnt lgkmcnt(3)
	v_fmac_f32_e32 v78, v90, v2
	v_fmac_f32_e32 v78, v91, v3
	v_fmac_f32_e32 v78, v92, v4
	v_fmac_f32_e32 v78, v93, v5
	ds_read_b128 v[90:93], v113 offset:32768
	s_waitcnt lgkmcnt(3)
	v_fmac_f32_e32 v79, v94, v2
	v_fmac_f32_e32 v79, v95, v3
	v_fmac_f32_e32 v79, v96, v4
	v_fmac_f32_e32 v79, v97, v5
	ds_read_b128 v[94:97], v113 offset:16
	s_waitcnt lgkmcnt(3)
	v_fmac_f32_e32 v80, v98, v2
	v_fmac_f32_e32 v80, v99, v3
	v_fmac_f32_e32 v80, v100, v4
	v_fmac_f32_e32 v80, v101, v5
	ds_read_b128 v[98:101], v113 offset:2064
	s_waitcnt lgkmcnt(3)
	v_fmac_f32_e32 v81, v108, v2
	v_fmac_f32_e32 v81, v109, v3
	v_fmac_f32_e32 v81, v110, v4
	v_fmac_f32_e32 v81, v111, v5
	ds_read_b128 v[108:111], v113 offset:4112
	s_waitcnt lgkmcnt(3)
	v_fmac_f32_e32 v89, v90, v2
	v_fmac_f32_e32 v89, v91, v3
	v_fmac_f32_e32 v89, v92, v4
	v_fmac_f32_e32 v89, v93, v5
	ds_read_b128 v[90:93], v113 offset:6160
	s_waitcnt vmcnt(56)
	s_waitcnt lgkmcnt(3)
	v_fmac_f32_e32 v66, v94, v6
	v_fmac_f32_e32 v66, v95, v7
	v_fmac_f32_e32 v66, v96, v8
	v_fmac_f32_e32 v66, v97, v9
	ds_read_b128 v[94:97], v113 offset:8208
	s_waitcnt lgkmcnt(3)
	v_fmac_f32_e32 v67, v98, v6
	v_fmac_f32_e32 v67, v99, v7
	v_fmac_f32_e32 v67, v100, v8
	v_fmac_f32_e32 v67, v101, v9
	ds_read_b128 v[98:101], v113 offset:10256
	s_waitcnt lgkmcnt(3)
	v_fmac_f32_e32 v68, v108, v6
	v_fmac_f32_e32 v68, v109, v7
	v_fmac_f32_e32 v68, v110, v8
	v_fmac_f32_e32 v68, v111, v9
	ds_read_b128 v[108:111], v113 offset:12304
	s_waitcnt lgkmcnt(3)
	v_fmac_f32_e32 v69, v90, v6
	v_fmac_f32_e32 v69, v91, v7
	v_fmac_f32_e32 v69, v92, v8
	v_fmac_f32_e32 v69, v93, v9
	ds_read_b128 v[90:93], v113 offset:14352
	s_waitcnt lgkmcnt(3)
	v_fmac_f32_e32 v70, v94, v6
	v_fmac_f32_e32 v70, v95, v7
	v_fmac_f32_e32 v70, v96, v8
	v_fmac_f32_e32 v70, v97, v9
	ds_read_b128 v[94:97], v113 offset:16400
	s_waitcnt lgkmcnt(3)
	v_fmac_f32_e32 v71, v98, v6
	v_fmac_f32_e32 v71, v99, v7
	v_fmac_f32_e32 v71, v100, v8
	v_fmac_f32_e32 v71, v101, v9
	ds_read_b128 v[98:101], v113 offset:18448
	s_waitcnt lgkmcnt(3)
	v_fmac_f32_e32 v72, v108, v6
	v_fmac_f32_e32 v72, v109, v7
	v_fmac_f32_e32 v72, v110, v8
	v_fmac_f32_e32 v72, v111, v9
	ds_read_b128 v[108:111], v113 offset:20496
	s_waitcnt lgkmcnt(3)
	v_fmac_f32_e32 v73, v90, v6
	v_fmac_f32_e32 v73, v91, v7
	v_fmac_f32_e32 v73, v92, v8
	v_fmac_f32_e32 v73, v93, v9
	ds_read_b128 v[90:93], v113 offset:22544
	s_waitcnt lgkmcnt(3)
	v_fmac_f32_e32 v74, v94, v6
	v_fmac_f32_e32 v74, v95, v7
	v_fmac_f32_e32 v74, v96, v8
	v_fmac_f32_e32 v74, v97, v9
	ds_read_b128 v[94:97], v113 offset:24592
	s_waitcnt lgkmcnt(3)
	v_fmac_f32_e32 v75, v98, v6
	v_fmac_f32_e32 v75, v99, v7
	v_fmac_f32_e32 v75, v100, v8
	v_fmac_f32_e32 v75, v101, v9
	ds_read_b128 v[98:101], v113 offset:26640
	s_waitcnt lgkmcnt(3)
	v_fmac_f32_e32 v76, v108, v6
	v_fmac_f32_e32 v76, v109, v7
	v_fmac_f32_e32 v76, v110, v8
	v_fmac_f32_e32 v76, v111, v9
	ds_read_b128 v[108:111], v113 offset:28688
	s_waitcnt lgkmcnt(3)
	v_fmac_f32_e32 v77, v90, v6
	v_fmac_f32_e32 v77, v91, v7
	v_fmac_f32_e32 v77, v92, v8
	v_fmac_f32_e32 v77, v93, v9
	ds_read_b128 v[90:93], v113 offset:30736
	s_waitcnt lgkmcnt(3)
	v_fmac_f32_e32 v78, v94, v6
	v_fmac_f32_e32 v78, v95, v7
	v_fmac_f32_e32 v78, v96, v8
	v_fmac_f32_e32 v78, v97, v9
	ds_read_b128 v[94:97], v113 offset:32784
	s_waitcnt lgkmcnt(3)
; DI void gemv17(const float* in16, int istride, const float* in1, bool do_silu, const float* W, int ldw, int n0,
;                const float* bvec, float* out, int ostride, char* lds) {
;     ...
; #pragma unroll 16
;     for (int kk = 0; kk < 64; ++kk) {
;       const float wv = wp[(size_t)kk * ldw];
;       const float* sp = sc + kp * 64 + kk;
; #pragma unroll
;       for (int j = 0; j < 17; ++j) acc[j] += sp[j * 512] * wv;
;     }
	v_fmac_f32_e32 v79, v98, v6
	v_fmac_f32_e32 v79, v99, v7
	v_fmac_f32_e32 v79, v100, v8
	v_fmac_f32_e32 v79, v101, v9
	ds_read_b128 v[98:101], v113 offset:32
	s_waitcnt lgkmcnt(3)
	v_fmac_f32_e32 v80, v108, v6
	v_fmac_f32_e32 v80, v109, v7
	v_fmac_f32_e32 v80, v110, v8
	v_fmac_f32_e32 v80, v111, v9
	ds_read_b128 v[108:111], v113 offset:2080
	s_waitcnt lgkmcnt(3)
	v_fmac_f32_e32 v81, v90, v6
	v_fmac_f32_e32 v81, v91, v7
	v_fmac_f32_e32 v81, v92, v8
	v_fmac_f32_e32 v81, v93, v9
	ds_read_b128 v[90:93], v113 offset:4128
	s_waitcnt lgkmcnt(3)
	v_fmac_f32_e32 v89, v94, v6
	v_fmac_f32_e32 v89, v95, v7
	v_fmac_f32_e32 v89, v96, v8
	v_fmac_f32_e32 v89, v97, v9
	ds_read_b128 v[94:97], v113 offset:6176
	s_waitcnt vmcnt(52)
	s_waitcnt lgkmcnt(3)
	v_fmac_f32_e32 v66, v98, v10
	v_fmac_f32_e32 v66, v99, v11
	v_fmac_f32_e32 v66, v100, v12
	v_fmac_f32_e32 v66, v101, v13
	ds_read_b128 v[98:101], v113 offset:8224
	s_waitcnt lgkmcnt(3)
	v_fmac_f32_e32 v67, v108, v10
	v_fmac_f32_e32 v67, v109, v11
	v_fmac_f32_e32 v67, v110, v12
	v_fmac_f32_e32 v67, v111, v13
	ds_read_b128 v[108:111], v113 offset:10272
	s_waitcnt lgkmcnt(3)
	v_fmac_f32_e32 v68, v90, v10
	v_fmac_f32_e32 v68, v91, v11
	v_fmac_f32_e32 v68, v92, v12
	v_fmac_f32_e32 v68, v93, v13
	ds_read_b128 v[90:93], v113 offset:12320
	s_waitcnt lgkmcnt(3)
	v_fmac_f32_e32 v69, v94, v10
	v_fmac_f32_e32 v69, v95, v11
	v_fmac_f32_e32 v69, v96, v12
	v_fmac_f32_e32 v69, v97, v13
	ds_read_b128 v[94:97], v113 offset:14368
	s_waitcnt lgkmcnt(3)
	v_fmac_f32_e32 v70, v98, v10
	v_fmac_f32_e32 v70, v99, v11
	v_fmac_f32_e32 v70, v100, v12
	v_fmac_f32_e32 v70, v101, v13
	ds_read_b128 v[98:101], v113 offset:16416
	s_waitcnt lgkmcnt(3)
	v_fmac_f32_e32 v71, v108, v10
	v_fmac_f32_e32 v71, v109, v11
	v_fmac_f32_e32 v71, v110, v12
	v_fmac_f32_e32 v71, v111, v13
	ds_read_b128 v[108:111], v113 offset:18464
	s_waitcnt lgkmcnt(3)
	v_fmac_f32_e32 v72, v90, v10
	v_fmac_f32_e32 v72, v91, v11
	v_fmac_f32_e32 v72, v92, v12
	v_fmac_f32_e32 v72, v93, v13
	ds_read_b128 v[90:93], v113 offset:20512
	s_waitcnt lgkmcnt(3)
	v_fmac_f32_e32 v73, v94, v10
	v_fmac_f32_e32 v73, v95, v11
	v_fmac_f32_e32 v73, v96, v12
	v_fmac_f32_e32 v73, v97, v13
	ds_read_b128 v[94:97], v113 offset:22560
	s_waitcnt lgkmcnt(3)
	v_fmac_f32_e32 v74, v98, v10
	v_fmac_f32_e32 v74, v99, v11
	v_fmac_f32_e32 v74, v100, v12
	v_fmac_f32_e32 v74, v101, v13
	ds_read_b128 v[98:101], v113 offset:24608
	s_waitcnt lgkmcnt(3)
	v_fmac_f32_e32 v75, v108, v10
	v_fmac_f32_e32 v75, v109, v11
	v_fmac_f32_e32 v75, v110, v12
	v_fmac_f32_e32 v75, v111, v13
	ds_read_b128 v[108:111], v113 offset:26656
	s_waitcnt lgkmcnt(3)
	v_fmac_f32_e32 v76, v90, v10
	v_fmac_f32_e32 v76, v91, v11
	v_fmac_f32_e32 v76, v92, v12
	v_fmac_f32_e32 v76, v93, v13
	ds_read_b128 v[90:93], v113 offset:28704
	s_waitcnt lgkmcnt(3)
	v_fmac_f32_e32 v77, v94, v10
	v_fmac_f32_e32 v77, v95, v11
	v_fmac_f32_e32 v77, v96, v12
	v_fmac_f32_e32 v77, v97, v13
	ds_read_b128 v[94:97], v113 offset:30752
	s_waitcnt lgkmcnt(3)
	v_fmac_f32_e32 v78, v98, v10
	v_fmac_f32_e32 v78, v99, v11
	v_fmac_f32_e32 v78, v100, v12
	v_fmac_f32_e32 v78, v101, v13
	ds_read_b128 v[98:101], v113 offset:32800
	s_waitcnt lgkmcnt(3)
	v_fmac_f32_e32 v79, v108, v10
	v_fmac_f32_e32 v79, v109, v11
	v_fmac_f32_e32 v79, v110, v12
	v_fmac_f32_e32 v79, v111, v13
	ds_read_b128 v[108:111], v113 offset:48
	s_waitcnt lgkmcnt(3)
	v_fmac_f32_e32 v80, v90, v10
	v_fmac_f32_e32 v80, v91, v11
	v_fmac_f32_e32 v80, v92, v12
	v_fmac_f32_e32 v80, v93, v13
	ds_read_b128 v[90:93], v113 offset:2096
	s_waitcnt lgkmcnt(3)
	v_fmac_f32_e32 v81, v94, v10
	v_fmac_f32_e32 v81, v95, v11
	v_fmac_f32_e32 v81, v96, v12
	v_fmac_f32_e32 v81, v97, v13
	ds_read_b128 v[94:97], v113 offset:4144
	s_waitcnt lgkmcnt(3)
	v_fmac_f32_e32 v89, v98, v10
	v_fmac_f32_e32 v89, v99, v11
	v_fmac_f32_e32 v89, v100, v12
	v_fmac_f32_e32 v89, v101, v13
	ds_read_b128 v[98:101], v113 offset:6192
	s_waitcnt vmcnt(48)
	s_waitcnt lgkmcnt(3)
	v_fmac_f32_e32 v66, v108, v14
	v_fmac_f32_e32 v66, v109, v15
	v_fmac_f32_e32 v66, v110, v16
	v_fmac_f32_e32 v66, v111, v17
	ds_read_b128 v[108:111], v113 offset:8240
	s_waitcnt lgkmcnt(3)
	v_fmac_f32_e32 v67, v90, v14
	v_fmac_f32_e32 v67, v91, v15
	v_fmac_f32_e32 v67, v92, v16
	v_fmac_f32_e32 v67, v93, v17
	ds_read_b128 v[90:93], v113 offset:10288
	s_waitcnt lgkmcnt(3)
	v_fmac_f32_e32 v68, v94, v14
	v_fmac_f32_e32 v68, v95, v15
	v_fmac_f32_e32 v68, v96, v16
	v_fmac_f32_e32 v68, v97, v17
	ds_read_b128 v[94:97], v113 offset:12336
	s_waitcnt lgkmcnt(3)
	v_fmac_f32_e32 v69, v98, v14
	v_fmac_f32_e32 v69, v99, v15
	v_fmac_f32_e32 v69, v100, v16
	v_fmac_f32_e32 v69, v101, v17
	ds_read_b128 v[98:101], v113 offset:14384
	s_waitcnt lgkmcnt(3)
	v_fmac_f32_e32 v70, v108, v14
	v_fmac_f32_e32 v70, v109, v15
	v_fmac_f32_e32 v70, v110, v16
	v_fmac_f32_e32 v70, v111, v17
	ds_read_b128 v[108:111], v113 offset:16432
	s_waitcnt lgkmcnt(3)
	v_fmac_f32_e32 v71, v90, v14
	v_fmac_f32_e32 v71, v91, v15
	v_fmac_f32_e32 v71, v92, v16
	v_fmac_f32_e32 v71, v93, v17
	ds_read_b128 v[90:93], v113 offset:18480
	s_waitcnt lgkmcnt(3)
	v_fmac_f32_e32 v72, v94, v14
	v_fmac_f32_e32 v72, v95, v15
	v_fmac_f32_e32 v72, v96, v16
	v_fmac_f32_e32 v72, v97, v17
	ds_read_b128 v[94:97], v113 offset:20528
	s_waitcnt lgkmcnt(3)
	v_fmac_f32_e32 v73, v98, v14
	v_fmac_f32_e32 v73, v99, v15
	v_fmac_f32_e32 v73, v100, v16
	v_fmac_f32_e32 v73, v101, v17
	ds_read_b128 v[98:101], v113 offset:22576
	s_waitcnt lgkmcnt(3)
	v_fmac_f32_e32 v74, v108, v14
	v_fmac_f32_e32 v74, v109, v15
	v_fmac_f32_e32 v74, v110, v16
	v_fmac_f32_e32 v74, v111, v17
	ds_read_b128 v[108:111], v113 offset:24624
	s_waitcnt lgkmcnt(3)
; DI void gemv17(const float* in16, int istride, const float* in1, bool do_silu, const float* W, int ldw, int n0,
;                const float* bvec, float* out, int ostride, char* lds) {
;     ...
; #pragma unroll 16
;     for (int kk = 0; kk < 64; ++kk) {
;       const float wv = wp[(size_t)kk * ldw];
;       const float* sp = sc + kp * 64 + kk;
; #pragma unroll
;       for (int j = 0; j < 17; ++j) acc[j] += sp[j * 512] * wv;
;     }
	v_fmac_f32_e32 v75, v90, v14
	v_fmac_f32_e32 v75, v91, v15
	v_fmac_f32_e32 v75, v92, v16
	v_fmac_f32_e32 v75, v93, v17
	ds_read_b128 v[90:93], v113 offset:26672
	s_waitcnt lgkmcnt(3)
	v_fmac_f32_e32 v76, v94, v14
	v_fmac_f32_e32 v76, v95, v15
	v_fmac_f32_e32 v76, v96, v16
	v_fmac_f32_e32 v76, v97, v17
	ds_read_b128 v[94:97], v113 offset:28720
	s_waitcnt lgkmcnt(3)
	v_fmac_f32_e32 v77, v98, v14
	v_fmac_f32_e32 v77, v99, v15
	v_fmac_f32_e32 v77, v100, v16
	v_fmac_f32_e32 v77, v101, v17
	ds_read_b128 v[98:101], v113 offset:30768
	s_waitcnt lgkmcnt(3)
	v_fmac_f32_e32 v78, v108, v14
	v_fmac_f32_e32 v78, v109, v15
	v_fmac_f32_e32 v78, v110, v16
	v_fmac_f32_e32 v78, v111, v17
	ds_read_b128 v[108:111], v113 offset:32816
	s_waitcnt lgkmcnt(3)
	v_fmac_f32_e32 v79, v90, v14
	v_fmac_f32_e32 v79, v91, v15
	v_fmac_f32_e32 v79, v92, v16
	v_fmac_f32_e32 v79, v93, v17
	ds_read_b128 v[90:93], v113 offset:64
	s_waitcnt lgkmcnt(3)
	v_fmac_f32_e32 v80, v94, v14
	v_fmac_f32_e32 v80, v95, v15
	v_fmac_f32_e32 v80, v96, v16
	v_fmac_f32_e32 v80, v97, v17
	ds_read_b128 v[94:97], v113 offset:2112
	s_waitcnt lgkmcnt(3)
	v_fmac_f32_e32 v81, v98, v14
	v_fmac_f32_e32 v81, v99, v15
	v_fmac_f32_e32 v81, v100, v16
	v_fmac_f32_e32 v81, v101, v17
	ds_read_b128 v[98:101], v113 offset:4160
	s_waitcnt lgkmcnt(3)
	v_fmac_f32_e32 v89, v108, v14
	v_fmac_f32_e32 v89, v109, v15
	v_fmac_f32_e32 v89, v110, v16
	v_fmac_f32_e32 v89, v111, v17
	ds_read_b128 v[108:111], v113 offset:6208
	s_waitcnt vmcnt(44)
	s_waitcnt lgkmcnt(3)
	v_fmac_f32_e32 v66, v90, v18
	v_fmac_f32_e32 v66, v91, v19
	v_fmac_f32_e32 v66, v92, v20
	v_fmac_f32_e32 v66, v93, v21
	ds_read_b128 v[90:93], v113 offset:8256
	s_waitcnt lgkmcnt(3)
	v_fmac_f32_e32 v67, v94, v18
	v_fmac_f32_e32 v67, v95, v19
	v_fmac_f32_e32 v67, v96, v20
	v_fmac_f32_e32 v67, v97, v21
	ds_read_b128 v[94:97], v113 offset:10304
	s_waitcnt lgkmcnt(3)
	v_fmac_f32_e32 v68, v98, v18
	v_fmac_f32_e32 v68, v99, v19
	v_fmac_f32_e32 v68, v100, v20
	v_fmac_f32_e32 v68, v101, v21
	ds_read_b128 v[98:101], v113 offset:12352
	s_waitcnt lgkmcnt(3)
	v_fmac_f32_e32 v69, v108, v18
	v_fmac_f32_e32 v69, v109, v19
	v_fmac_f32_e32 v69, v110, v20
	v_fmac_f32_e32 v69, v111, v21
	ds_read_b128 v[108:111], v113 offset:14400
	s_waitcnt lgkmcnt(3)
	v_fmac_f32_e32 v70, v90, v18
	v_fmac_f32_e32 v70, v91, v19
	v_fmac_f32_e32 v70, v92, v20
	v_fmac_f32_e32 v70, v93, v21
	ds_read_b128 v[90:93], v113 offset:16448
	s_waitcnt lgkmcnt(3)
	v_fmac_f32_e32 v71, v94, v18
	v_fmac_f32_e32 v71, v95, v19
	v_fmac_f32_e32 v71, v96, v20
	v_fmac_f32_e32 v71, v97, v21
	ds_read_b128 v[94:97], v113 offset:18496
	s_waitcnt lgkmcnt(3)
	v_fmac_f32_e32 v72, v98, v18
	v_fmac_f32_e32 v72, v99, v19
	v_fmac_f32_e32 v72, v100, v20
	v_fmac_f32_e32 v72, v101, v21
	ds_read_b128 v[98:101], v113 offset:20544
	s_waitcnt lgkmcnt(3)
	v_fmac_f32_e32 v73, v108, v18
	v_fmac_f32_e32 v73, v109, v19
	v_fmac_f32_e32 v73, v110, v20
	v_fmac_f32_e32 v73, v111, v21
	ds_read_b128 v[108:111], v113 offset:22592
	s_waitcnt lgkmcnt(3)
	v_fmac_f32_e32 v74, v90, v18
	v_fmac_f32_e32 v74, v91, v19
	v_fmac_f32_e32 v74, v92, v20
	v_fmac_f32_e32 v74, v93, v21
	ds_read_b128 v[90:93], v113 offset:24640
	s_waitcnt lgkmcnt(3)
	v_fmac_f32_e32 v75, v94, v18
	v_fmac_f32_e32 v75, v95, v19
	v_fmac_f32_e32 v75, v96, v20
	v_fmac_f32_e32 v75, v97, v21
	ds_read_b128 v[94:97], v113 offset:26688
	s_waitcnt lgkmcnt(3)
	v_fmac_f32_e32 v76, v98, v18
	v_fmac_f32_e32 v76, v99, v19
	v_fmac_f32_e32 v76, v100, v20
	v_fmac_f32_e32 v76, v101, v21
	ds_read_b128 v[98:101], v113 offset:28736
	s_waitcnt lgkmcnt(3)
	v_fmac_f32_e32 v77, v108, v18
	v_fmac_f32_e32 v77, v109, v19
	v_fmac_f32_e32 v77, v110, v20
	v_fmac_f32_e32 v77, v111, v21
	ds_read_b128 v[108:111], v113 offset:30784
	s_waitcnt lgkmcnt(3)
	v_fmac_f32_e32 v78, v90, v18
	v_fmac_f32_e32 v78, v91, v19
	v_fmac_f32_e32 v78, v92, v20
	v_fmac_f32_e32 v78, v93, v21
	ds_read_b128 v[90:93], v113 offset:32832
	s_waitcnt lgkmcnt(3)
	v_fmac_f32_e32 v79, v94, v18
	v_fmac_f32_e32 v79, v95, v19
	v_fmac_f32_e32 v79, v96, v20
	v_fmac_f32_e32 v79, v97, v21
	ds_read_b128 v[94:97], v113 offset:80
	s_waitcnt lgkmcnt(3)
	v_fmac_f32_e32 v80, v98, v18
	v_fmac_f32_e32 v80, v99, v19
	v_fmac_f32_e32 v80, v100, v20
	v_fmac_f32_e32 v80, v101, v21
	ds_read_b128 v[98:101], v113 offset:2128
	s_waitcnt lgkmcnt(3)
	v_fmac_f32_e32 v81, v108, v18
	v_fmac_f32_e32 v81, v109, v19
	v_fmac_f32_e32 v81, v110, v20
	v_fmac_f32_e32 v81, v111, v21
	ds_read_b128 v[108:111], v113 offset:4176
	s_waitcnt lgkmcnt(3)
	v_fmac_f32_e32 v89, v90, v18
	v_fmac_f32_e32 v89, v91, v19
	v_fmac_f32_e32 v89, v92, v20
	v_fmac_f32_e32 v89, v93, v21
	ds_read_b128 v[90:93], v113 offset:6224
	s_waitcnt vmcnt(40)
	s_waitcnt lgkmcnt(3)
	v_fmac_f32_e32 v66, v94, v22
	v_fmac_f32_e32 v66, v95, v23
	v_fmac_f32_e32 v66, v96, v24
	v_fmac_f32_e32 v66, v97, v25
	ds_read_b128 v[94:97], v113 offset:8272
	s_waitcnt lgkmcnt(3)
	v_fmac_f32_e32 v67, v98, v22
	v_fmac_f32_e32 v67, v99, v23
	v_fmac_f32_e32 v67, v100, v24
	v_fmac_f32_e32 v67, v101, v25
	ds_read_b128 v[98:101], v113 offset:10320
	s_waitcnt lgkmcnt(3)
	v_fmac_f32_e32 v68, v108, v22
	v_fmac_f32_e32 v68, v109, v23
	v_fmac_f32_e32 v68, v110, v24
	v_fmac_f32_e32 v68, v111, v25
	ds_read_b128 v[108:111], v113 offset:12368
	s_waitcnt lgkmcnt(3)
	v_fmac_f32_e32 v69, v90, v22
	v_fmac_f32_e32 v69, v91, v23
	v_fmac_f32_e32 v69, v92, v24
	v_fmac_f32_e32 v69, v93, v25
	ds_read_b128 v[90:93], v113 offset:14416
	s_waitcnt lgkmcnt(3)
	v_fmac_f32_e32 v70, v94, v22
	v_fmac_f32_e32 v70, v95, v23
	v_fmac_f32_e32 v70, v96, v24
	v_fmac_f32_e32 v70, v97, v25
	ds_read_b128 v[94:97], v113 offset:16464
	s_waitcnt lgkmcnt(3)
; DI void gemv17(const float* in16, int istride, const float* in1, bool do_silu, const float* W, int ldw, int n0,
;                const float* bvec, float* out, int ostride, char* lds) {
;     ...
; #pragma unroll 16
;     for (int kk = 0; kk < 64; ++kk) {
;       const float wv = wp[(size_t)kk * ldw];
;       const float* sp = sc + kp * 64 + kk;
; #pragma unroll
;       for (int j = 0; j < 17; ++j) acc[j] += sp[j * 512] * wv;
;     }
	v_fmac_f32_e32 v71, v98, v22
	v_fmac_f32_e32 v71, v99, v23
	v_fmac_f32_e32 v71, v100, v24
	v_fmac_f32_e32 v71, v101, v25
	ds_read_b128 v[98:101], v113 offset:18512
	s_waitcnt lgkmcnt(3)
	v_fmac_f32_e32 v72, v108, v22
	v_fmac_f32_e32 v72, v109, v23
	v_fmac_f32_e32 v72, v110, v24
	v_fmac_f32_e32 v72, v111, v25
	ds_read_b128 v[108:111], v113 offset:20560
	s_waitcnt lgkmcnt(3)
	v_fmac_f32_e32 v73, v90, v22
	v_fmac_f32_e32 v73, v91, v23
	v_fmac_f32_e32 v73, v92, v24
	v_fmac_f32_e32 v73, v93, v25
	ds_read_b128 v[90:93], v113 offset:22608
	s_waitcnt lgkmcnt(3)
	v_fmac_f32_e32 v74, v94, v22
	v_fmac_f32_e32 v74, v95, v23
	v_fmac_f32_e32 v74, v96, v24
	v_fmac_f32_e32 v74, v97, v25
	ds_read_b128 v[94:97], v113 offset:24656
	s_waitcnt lgkmcnt(3)
	v_fmac_f32_e32 v75, v98, v22
	v_fmac_f32_e32 v75, v99, v23
	v_fmac_f32_e32 v75, v100, v24
	v_fmac_f32_e32 v75, v101, v25
	ds_read_b128 v[98:101], v113 offset:26704
	s_waitcnt lgkmcnt(3)
	v_fmac_f32_e32 v76, v108, v22
	v_fmac_f32_e32 v76, v109, v23
	v_fmac_f32_e32 v76, v110, v24
	v_fmac_f32_e32 v76, v111, v25
	ds_read_b128 v[108:111], v113 offset:28752
	s_waitcnt lgkmcnt(3)
	v_fmac_f32_e32 v77, v90, v22
	v_fmac_f32_e32 v77, v91, v23
	v_fmac_f32_e32 v77, v92, v24
	v_fmac_f32_e32 v77, v93, v25
	ds_read_b128 v[90:93], v113 offset:30800
	s_waitcnt lgkmcnt(3)
	v_fmac_f32_e32 v78, v94, v22
	v_fmac_f32_e32 v78, v95, v23
	v_fmac_f32_e32 v78, v96, v24
	v_fmac_f32_e32 v78, v97, v25
	ds_read_b128 v[94:97], v113 offset:32848
	s_waitcnt lgkmcnt(3)
	v_fmac_f32_e32 v79, v98, v22
	v_fmac_f32_e32 v79, v99, v23
	v_fmac_f32_e32 v79, v100, v24
	v_fmac_f32_e32 v79, v101, v25
	ds_read_b128 v[98:101], v113 offset:96
	s_waitcnt lgkmcnt(3)
	v_fmac_f32_e32 v80, v108, v22
	v_fmac_f32_e32 v80, v109, v23
	v_fmac_f32_e32 v80, v110, v24
	v_fmac_f32_e32 v80, v111, v25
	ds_read_b128 v[108:111], v113 offset:2144
	s_waitcnt lgkmcnt(3)
	v_fmac_f32_e32 v81, v90, v22
	v_fmac_f32_e32 v81, v91, v23
	v_fmac_f32_e32 v81, v92, v24
	v_fmac_f32_e32 v81, v93, v25
	ds_read_b128 v[90:93], v113 offset:4192
	s_waitcnt lgkmcnt(3)
	v_fmac_f32_e32 v89, v94, v22
	v_fmac_f32_e32 v89, v95, v23
	v_fmac_f32_e32 v89, v96, v24
	v_fmac_f32_e32 v89, v97, v25
	ds_read_b128 v[94:97], v113 offset:6240
	s_waitcnt vmcnt(36)
	s_waitcnt lgkmcnt(3)
	v_fmac_f32_e32 v66, v98, v26
	v_fmac_f32_e32 v66, v99, v27
	v_fmac_f32_e32 v66, v100, v28
	v_fmac_f32_e32 v66, v101, v29
	ds_read_b128 v[98:101], v113 offset:8288
	s_waitcnt lgkmcnt(3)
	v_fmac_f32_e32 v67, v108, v26
	v_fmac_f32_e32 v67, v109, v27
	v_fmac_f32_e32 v67, v110, v28
	v_fmac_f32_e32 v67, v111, v29
	ds_read_b128 v[108:111], v113 offset:10336
	s_waitcnt lgkmcnt(3)
	v_fmac_f32_e32 v68, v90, v26
	v_fmac_f32_e32 v68, v91, v27
	v_fmac_f32_e32 v68, v92, v28
	v_fmac_f32_e32 v68, v93, v29
	ds_read_b128 v[90:93], v113 offset:12384
	s_waitcnt lgkmcnt(3)
	v_fmac_f32_e32 v69, v94, v26
	v_fmac_f32_e32 v69, v95, v27
	v_fmac_f32_e32 v69, v96, v28
	v_fmac_f32_e32 v69, v97, v29
	ds_read_b128 v[94:97], v113 offset:14432
	s_waitcnt lgkmcnt(3)
	v_fmac_f32_e32 v70, v98, v26
	v_fmac_f32_e32 v70, v99, v27
	v_fmac_f32_e32 v70, v100, v28
	v_fmac_f32_e32 v70, v101, v29
	ds_read_b128 v[98:101], v113 offset:16480
	s_waitcnt lgkmcnt(3)
	v_fmac_f32_e32 v71, v108, v26
	v_fmac_f32_e32 v71, v109, v27
	v_fmac_f32_e32 v71, v110, v28
	v_fmac_f32_e32 v71, v111, v29
	ds_read_b128 v[108:111], v113 offset:18528
	s_waitcnt lgkmcnt(3)
	v_fmac_f32_e32 v72, v90, v26
	v_fmac_f32_e32 v72, v91, v27
	v_fmac_f32_e32 v72, v92, v28
	v_fmac_f32_e32 v72, v93, v29
	ds_read_b128 v[90:93], v113 offset:20576
	s_waitcnt lgkmcnt(3)
	v_fmac_f32_e32 v73, v94, v26
	v_fmac_f32_e32 v73, v95, v27
	v_fmac_f32_e32 v73, v96, v28
	v_fmac_f32_e32 v73, v97, v29
	ds_read_b128 v[94:97], v113 offset:22624
	s_waitcnt lgkmcnt(3)
	v_fmac_f32_e32 v74, v98, v26
	v_fmac_f32_e32 v74, v99, v27
	v_fmac_f32_e32 v74, v100, v28
	v_fmac_f32_e32 v74, v101, v29
	ds_read_b128 v[98:101], v113 offset:24672
	s_waitcnt lgkmcnt(3)
	v_fmac_f32_e32 v75, v108, v26
	v_fmac_f32_e32 v75, v109, v27
	v_fmac_f32_e32 v75, v110, v28
	v_fmac_f32_e32 v75, v111, v29
	ds_read_b128 v[108:111], v113 offset:26720
	s_waitcnt lgkmcnt(3)
	v_fmac_f32_e32 v76, v90, v26
	v_fmac_f32_e32 v76, v91, v27
	v_fmac_f32_e32 v76, v92, v28
	v_fmac_f32_e32 v76, v93, v29
	ds_read_b128 v[90:93], v113 offset:28768
	s_waitcnt lgkmcnt(3)
	v_fmac_f32_e32 v77, v94, v26
	v_fmac_f32_e32 v77, v95, v27
	v_fmac_f32_e32 v77, v96, v28
	v_fmac_f32_e32 v77, v97, v29
	ds_read_b128 v[94:97], v113 offset:30816
	s_waitcnt lgkmcnt(3)
	v_fmac_f32_e32 v78, v98, v26
	v_fmac_f32_e32 v78, v99, v27
	v_fmac_f32_e32 v78, v100, v28
	v_fmac_f32_e32 v78, v101, v29
	ds_read_b128 v[98:101], v113 offset:32864
	s_waitcnt lgkmcnt(3)
	v_fmac_f32_e32 v79, v108, v26
	v_fmac_f32_e32 v79, v109, v27
	v_fmac_f32_e32 v79, v110, v28
	v_fmac_f32_e32 v79, v111, v29
	ds_read_b128 v[108:111], v113 offset:112
	s_waitcnt lgkmcnt(3)
	v_fmac_f32_e32 v80, v90, v26
	v_fmac_f32_e32 v80, v91, v27
	v_fmac_f32_e32 v80, v92, v28
	v_fmac_f32_e32 v80, v93, v29
	ds_read_b128 v[90:93], v113 offset:2160
	s_waitcnt lgkmcnt(3)
	v_fmac_f32_e32 v81, v94, v26
	v_fmac_f32_e32 v81, v95, v27
	v_fmac_f32_e32 v81, v96, v28
	v_fmac_f32_e32 v81, v97, v29
	ds_read_b128 v[94:97], v113 offset:4208
	s_waitcnt lgkmcnt(3)
	v_fmac_f32_e32 v89, v98, v26
	v_fmac_f32_e32 v89, v99, v27
	v_fmac_f32_e32 v89, v100, v28
	v_fmac_f32_e32 v89, v101, v29
	ds_read_b128 v[98:101], v113 offset:6256
	s_waitcnt vmcnt(32)
	s_waitcnt lgkmcnt(3)
	v_fmac_f32_e32 v66, v108, v30
	v_fmac_f32_e32 v66, v109, v31
	v_fmac_f32_e32 v66, v110, v32
	v_fmac_f32_e32 v66, v111, v33
	ds_read_b128 v[108:111], v113 offset:8304
	s_waitcnt lgkmcnt(3)
; DI void gemv17(const float* in16, int istride, const float* in1, bool do_silu, const float* W, int ldw, int n0,
;                const float* bvec, float* out, int ostride, char* lds) {
;     ...
; #pragma unroll 16
;     for (int kk = 0; kk < 64; ++kk) {
;       const float wv = wp[(size_t)kk * ldw];
;       const float* sp = sc + kp * 64 + kk;
; #pragma unroll
;       for (int j = 0; j < 17; ++j) acc[j] += sp[j * 512] * wv;
;     }
	v_fmac_f32_e32 v67, v90, v30
	v_fmac_f32_e32 v67, v91, v31
	v_fmac_f32_e32 v67, v92, v32
	v_fmac_f32_e32 v67, v93, v33
	ds_read_b128 v[90:93], v113 offset:10352
	s_waitcnt lgkmcnt(3)
	v_fmac_f32_e32 v68, v94, v30
	v_fmac_f32_e32 v68, v95, v31
	v_fmac_f32_e32 v68, v96, v32
	v_fmac_f32_e32 v68, v97, v33
	ds_read_b128 v[94:97], v113 offset:12400
	s_waitcnt lgkmcnt(3)
	v_fmac_f32_e32 v69, v98, v30
	v_fmac_f32_e32 v69, v99, v31
	v_fmac_f32_e32 v69, v100, v32
	v_fmac_f32_e32 v69, v101, v33
	ds_read_b128 v[98:101], v113 offset:14448
	s_waitcnt lgkmcnt(3)
	v_fmac_f32_e32 v70, v108, v30
	v_fmac_f32_e32 v70, v109, v31
	v_fmac_f32_e32 v70, v110, v32
	v_fmac_f32_e32 v70, v111, v33
	ds_read_b128 v[108:111], v113 offset:16496
	s_waitcnt lgkmcnt(3)
	v_fmac_f32_e32 v71, v90, v30
	v_fmac_f32_e32 v71, v91, v31
	v_fmac_f32_e32 v71, v92, v32
	v_fmac_f32_e32 v71, v93, v33
	ds_read_b128 v[90:93], v113 offset:18544
	s_waitcnt lgkmcnt(3)
	v_fmac_f32_e32 v72, v94, v30
	v_fmac_f32_e32 v72, v95, v31
	v_fmac_f32_e32 v72, v96, v32
	v_fmac_f32_e32 v72, v97, v33
	ds_read_b128 v[94:97], v113 offset:20592
	s_waitcnt lgkmcnt(3)
	v_fmac_f32_e32 v73, v98, v30
	v_fmac_f32_e32 v73, v99, v31
	v_fmac_f32_e32 v73, v100, v32
	v_fmac_f32_e32 v73, v101, v33
	ds_read_b128 v[98:101], v113 offset:22640
	s_waitcnt lgkmcnt(3)
	v_fmac_f32_e32 v74, v108, v30
	v_fmac_f32_e32 v74, v109, v31
	v_fmac_f32_e32 v74, v110, v32
	v_fmac_f32_e32 v74, v111, v33
	ds_read_b128 v[108:111], v113 offset:24688
	s_waitcnt lgkmcnt(3)
	v_fmac_f32_e32 v75, v90, v30
	v_fmac_f32_e32 v75, v91, v31
	v_fmac_f32_e32 v75, v92, v32
	v_fmac_f32_e32 v75, v93, v33
	ds_read_b128 v[90:93], v113 offset:26736
	s_waitcnt lgkmcnt(3)
	v_fmac_f32_e32 v76, v94, v30
	v_fmac_f32_e32 v76, v95, v31
	v_fmac_f32_e32 v76, v96, v32
	v_fmac_f32_e32 v76, v97, v33
	ds_read_b128 v[94:97], v113 offset:28784
	s_waitcnt lgkmcnt(3)
	v_fmac_f32_e32 v77, v98, v30
	v_fmac_f32_e32 v77, v99, v31
	v_fmac_f32_e32 v77, v100, v32
	v_fmac_f32_e32 v77, v101, v33
	ds_read_b128 v[98:101], v113 offset:30832
	s_waitcnt lgkmcnt(3)
	v_fmac_f32_e32 v78, v108, v30
	v_fmac_f32_e32 v78, v109, v31
	v_fmac_f32_e32 v78, v110, v32
	v_fmac_f32_e32 v78, v111, v33
	ds_read_b128 v[108:111], v113 offset:32880
	s_waitcnt lgkmcnt(3)
	v_fmac_f32_e32 v79, v90, v30
	v_fmac_f32_e32 v79, v91, v31
	v_fmac_f32_e32 v79, v92, v32
	v_fmac_f32_e32 v79, v93, v33
	ds_read_b128 v[90:93], v113 offset:128
	s_waitcnt lgkmcnt(3)
	v_fmac_f32_e32 v80, v94, v30
	v_fmac_f32_e32 v80, v95, v31
	v_fmac_f32_e32 v80, v96, v32
	v_fmac_f32_e32 v80, v97, v33
	ds_read_b128 v[94:97], v113 offset:2176
	s_waitcnt lgkmcnt(3)
	v_fmac_f32_e32 v81, v98, v30
	v_fmac_f32_e32 v81, v99, v31
	v_fmac_f32_e32 v81, v100, v32
	v_fmac_f32_e32 v81, v101, v33
	ds_read_b128 v[98:101], v113 offset:4224
	s_waitcnt lgkmcnt(3)
	v_fmac_f32_e32 v89, v108, v30
	v_fmac_f32_e32 v89, v109, v31
	v_fmac_f32_e32 v89, v110, v32
	v_fmac_f32_e32 v89, v111, v33
	ds_read_b128 v[108:111], v113 offset:6272
	s_waitcnt vmcnt(28)
	s_waitcnt lgkmcnt(3)
	v_fmac_f32_e32 v66, v90, v34
	v_fmac_f32_e32 v66, v91, v35
	v_fmac_f32_e32 v66, v92, v36
	v_fmac_f32_e32 v66, v93, v37
	ds_read_b128 v[90:93], v113 offset:8320
	s_waitcnt lgkmcnt(3)
	v_fmac_f32_e32 v67, v94, v34
	v_fmac_f32_e32 v67, v95, v35
	v_fmac_f32_e32 v67, v96, v36
	v_fmac_f32_e32 v67, v97, v37
	ds_read_b128 v[94:97], v113 offset:10368
	s_waitcnt lgkmcnt(3)
	v_fmac_f32_e32 v68, v98, v34
	v_fmac_f32_e32 v68, v99, v35
	v_fmac_f32_e32 v68, v100, v36
	v_fmac_f32_e32 v68, v101, v37
	ds_read_b128 v[98:101], v113 offset:12416
	s_waitcnt lgkmcnt(3)
	v_fmac_f32_e32 v69, v108, v34
	v_fmac_f32_e32 v69, v109, v35
	v_fmac_f32_e32 v69, v110, v36
	v_fmac_f32_e32 v69, v111, v37
	ds_read_b128 v[108:111], v113 offset:14464
	s_waitcnt lgkmcnt(3)
	v_fmac_f32_e32 v70, v90, v34
	v_fmac_f32_e32 v70, v91, v35
	v_fmac_f32_e32 v70, v92, v36
	v_fmac_f32_e32 v70, v93, v37
	ds_read_b128 v[90:93], v113 offset:16512
	s_waitcnt lgkmcnt(3)
	v_fmac_f32_e32 v71, v94, v34
	v_fmac_f32_e32 v71, v95, v35
	v_fmac_f32_e32 v71, v96, v36
	v_fmac_f32_e32 v71, v97, v37
	ds_read_b128 v[94:97], v113 offset:18560
	s_waitcnt lgkmcnt(3)
	v_fmac_f32_e32 v72, v98, v34
	v_fmac_f32_e32 v72, v99, v35
	v_fmac_f32_e32 v72, v100, v36
	v_fmac_f32_e32 v72, v101, v37
	ds_read_b128 v[98:101], v113 offset:20608
	s_waitcnt lgkmcnt(3)
	v_fmac_f32_e32 v73, v108, v34
	v_fmac_f32_e32 v73, v109, v35
	v_fmac_f32_e32 v73, v110, v36
	v_fmac_f32_e32 v73, v111, v37
	ds_read_b128 v[108:111], v113 offset:22656
	s_waitcnt lgkmcnt(3)
	v_fmac_f32_e32 v74, v90, v34
	v_fmac_f32_e32 v74, v91, v35
	v_fmac_f32_e32 v74, v92, v36
	v_fmac_f32_e32 v74, v93, v37
	ds_read_b128 v[90:93], v113 offset:24704
	s_waitcnt lgkmcnt(3)
	v_fmac_f32_e32 v75, v94, v34
	v_fmac_f32_e32 v75, v95, v35
	v_fmac_f32_e32 v75, v96, v36
	v_fmac_f32_e32 v75, v97, v37
	ds_read_b128 v[94:97], v113 offset:26752
	s_waitcnt lgkmcnt(3)
	v_fmac_f32_e32 v76, v98, v34
	v_fmac_f32_e32 v76, v99, v35
	v_fmac_f32_e32 v76, v100, v36
	v_fmac_f32_e32 v76, v101, v37
	ds_read_b128 v[98:101], v113 offset:28800
	s_waitcnt lgkmcnt(3)
	v_fmac_f32_e32 v77, v108, v34
	v_fmac_f32_e32 v77, v109, v35
	v_fmac_f32_e32 v77, v110, v36
	v_fmac_f32_e32 v77, v111, v37
	ds_read_b128 v[108:111], v113 offset:30848
	s_waitcnt lgkmcnt(3)
	v_fmac_f32_e32 v78, v90, v34
	v_fmac_f32_e32 v78, v91, v35
	v_fmac_f32_e32 v78, v92, v36
	v_fmac_f32_e32 v78, v93, v37
	ds_read_b128 v[90:93], v113 offset:32896
	s_waitcnt lgkmcnt(3)
	v_fmac_f32_e32 v79, v94, v34
	v_fmac_f32_e32 v79, v95, v35
	v_fmac_f32_e32 v79, v96, v36
	v_fmac_f32_e32 v79, v97, v37
	ds_read_b128 v[94:97], v113 offset:144
	s_waitcnt lgkmcnt(3)
; DI void gemv17(const float* in16, int istride, const float* in1, bool do_silu, const float* W, int ldw, int n0,
;                const float* bvec, float* out, int ostride, char* lds) {
;     ...
; #pragma unroll 16
;     for (int kk = 0; kk < 64; ++kk) {
;       const float wv = wp[(size_t)kk * ldw];
;       const float* sp = sc + kp * 64 + kk;
; #pragma unroll
;       for (int j = 0; j < 17; ++j) acc[j] += sp[j * 512] * wv;
;     }
	v_fmac_f32_e32 v80, v98, v34
	v_fmac_f32_e32 v80, v99, v35
	v_fmac_f32_e32 v80, v100, v36
	v_fmac_f32_e32 v80, v101, v37
	ds_read_b128 v[98:101], v113 offset:2192
	s_waitcnt lgkmcnt(3)
	v_fmac_f32_e32 v81, v108, v34
	v_fmac_f32_e32 v81, v109, v35
	v_fmac_f32_e32 v81, v110, v36
	v_fmac_f32_e32 v81, v111, v37
	ds_read_b128 v[108:111], v113 offset:4240
	s_waitcnt lgkmcnt(3)
	v_fmac_f32_e32 v89, v90, v34
	v_fmac_f32_e32 v89, v91, v35
	v_fmac_f32_e32 v89, v92, v36
	v_fmac_f32_e32 v89, v93, v37
	ds_read_b128 v[90:93], v113 offset:6288
	s_waitcnt vmcnt(24)
	s_waitcnt lgkmcnt(3)
	v_fmac_f32_e32 v66, v94, v38
	v_fmac_f32_e32 v66, v95, v39
	v_fmac_f32_e32 v66, v96, v40
	v_fmac_f32_e32 v66, v97, v41
	ds_read_b128 v[94:97], v113 offset:8336
	s_waitcnt lgkmcnt(3)
	v_fmac_f32_e32 v67, v98, v38
	v_fmac_f32_e32 v67, v99, v39
	v_fmac_f32_e32 v67, v100, v40
	v_fmac_f32_e32 v67, v101, v41
	ds_read_b128 v[98:101], v113 offset:10384
	s_waitcnt lgkmcnt(3)
	v_fmac_f32_e32 v68, v108, v38
	v_fmac_f32_e32 v68, v109, v39
	v_fmac_f32_e32 v68, v110, v40
	v_fmac_f32_e32 v68, v111, v41
	ds_read_b128 v[108:111], v113 offset:12432
	s_waitcnt lgkmcnt(3)
	v_fmac_f32_e32 v69, v90, v38
	v_fmac_f32_e32 v69, v91, v39
	v_fmac_f32_e32 v69, v92, v40
	v_fmac_f32_e32 v69, v93, v41
	ds_read_b128 v[90:93], v113 offset:14480
	s_waitcnt lgkmcnt(3)
	v_fmac_f32_e32 v70, v94, v38
	v_fmac_f32_e32 v70, v95, v39
	v_fmac_f32_e32 v70, v96, v40
	v_fmac_f32_e32 v70, v97, v41
	ds_read_b128 v[94:97], v113 offset:16528
	s_waitcnt lgkmcnt(3)
	v_fmac_f32_e32 v71, v98, v38
	v_fmac_f32_e32 v71, v99, v39
	v_fmac_f32_e32 v71, v100, v40
	v_fmac_f32_e32 v71, v101, v41
	ds_read_b128 v[98:101], v113 offset:18576
	s_waitcnt lgkmcnt(3)
	v_fmac_f32_e32 v72, v108, v38
	v_fmac_f32_e32 v72, v109, v39
	v_fmac_f32_e32 v72, v110, v40
	v_fmac_f32_e32 v72, v111, v41
	ds_read_b128 v[108:111], v113 offset:20624
	s_waitcnt lgkmcnt(3)
	v_fmac_f32_e32 v73, v90, v38
	v_fmac_f32_e32 v73, v91, v39
	v_fmac_f32_e32 v73, v92, v40
	v_fmac_f32_e32 v73, v93, v41
	ds_read_b128 v[90:93], v113 offset:22672
	s_waitcnt lgkmcnt(3)
	v_fmac_f32_e32 v74, v94, v38
	v_fmac_f32_e32 v74, v95, v39
	v_fmac_f32_e32 v74, v96, v40
	v_fmac_f32_e32 v74, v97, v41
	ds_read_b128 v[94:97], v113 offset:24720
	s_waitcnt lgkmcnt(3)
	v_fmac_f32_e32 v75, v98, v38
	v_fmac_f32_e32 v75, v99, v39
	v_fmac_f32_e32 v75, v100, v40
	v_fmac_f32_e32 v75, v101, v41
	ds_read_b128 v[98:101], v113 offset:26768
	s_waitcnt lgkmcnt(3)
	v_fmac_f32_e32 v76, v108, v38
	v_fmac_f32_e32 v76, v109, v39
	v_fmac_f32_e32 v76, v110, v40
	v_fmac_f32_e32 v76, v111, v41
	ds_read_b128 v[108:111], v113 offset:28816
	s_waitcnt lgkmcnt(3)
	v_fmac_f32_e32 v77, v90, v38
	v_fmac_f32_e32 v77, v91, v39
	v_fmac_f32_e32 v77, v92, v40
	v_fmac_f32_e32 v77, v93, v41
	ds_read_b128 v[90:93], v113 offset:30864
	s_waitcnt lgkmcnt(3)
	v_fmac_f32_e32 v78, v94, v38
	v_fmac_f32_e32 v78, v95, v39
	v_fmac_f32_e32 v78, v96, v40
	v_fmac_f32_e32 v78, v97, v41
	ds_read_b128 v[94:97], v113 offset:32912
	s_waitcnt lgkmcnt(3)
	v_fmac_f32_e32 v79, v98, v38
	v_fmac_f32_e32 v79, v99, v39
	v_fmac_f32_e32 v79, v100, v40
	v_fmac_f32_e32 v79, v101, v41
	ds_read_b128 v[98:101], v113 offset:160
	s_waitcnt lgkmcnt(3)
	v_fmac_f32_e32 v80, v108, v38
	v_fmac_f32_e32 v80, v109, v39
	v_fmac_f32_e32 v80, v110, v40
	v_fmac_f32_e32 v80, v111, v41
	ds_read_b128 v[108:111], v113 offset:2208
	s_waitcnt lgkmcnt(3)
	v_fmac_f32_e32 v81, v90, v38
	v_fmac_f32_e32 v81, v91, v39
	v_fmac_f32_e32 v81, v92, v40
	v_fmac_f32_e32 v81, v93, v41
	ds_read_b128 v[90:93], v113 offset:4256
	s_waitcnt lgkmcnt(3)
	v_fmac_f32_e32 v89, v94, v38
	v_fmac_f32_e32 v89, v95, v39
	v_fmac_f32_e32 v89, v96, v40
	v_fmac_f32_e32 v89, v97, v41
	ds_read_b128 v[94:97], v113 offset:6304
	s_waitcnt vmcnt(20)
	s_waitcnt lgkmcnt(3)
	v_fmac_f32_e32 v66, v98, v42
	v_fmac_f32_e32 v66, v99, v43
	v_fmac_f32_e32 v66, v100, v44
	v_fmac_f32_e32 v66, v101, v45
	ds_read_b128 v[98:101], v113 offset:8352
	s_waitcnt lgkmcnt(3)
	v_fmac_f32_e32 v67, v108, v42
	v_fmac_f32_e32 v67, v109, v43
	v_fmac_f32_e32 v67, v110, v44
	v_fmac_f32_e32 v67, v111, v45
	ds_read_b128 v[108:111], v113 offset:10400
	s_waitcnt lgkmcnt(3)
	v_fmac_f32_e32 v68, v90, v42
	v_fmac_f32_e32 v68, v91, v43
	v_fmac_f32_e32 v68, v92, v44
	v_fmac_f32_e32 v68, v93, v45
	ds_read_b128 v[90:93], v113 offset:12448
	s_waitcnt lgkmcnt(3)
	v_fmac_f32_e32 v69, v94, v42
	v_fmac_f32_e32 v69, v95, v43
	v_fmac_f32_e32 v69, v96, v44
	v_fmac_f32_e32 v69, v97, v45
	ds_read_b128 v[94:97], v113 offset:14496
	s_waitcnt lgkmcnt(3)
	v_fmac_f32_e32 v70, v98, v42
	v_fmac_f32_e32 v70, v99, v43
	v_fmac_f32_e32 v70, v100, v44
	v_fmac_f32_e32 v70, v101, v45
	ds_read_b128 v[98:101], v113 offset:16544
	s_waitcnt lgkmcnt(3)
	v_fmac_f32_e32 v71, v108, v42
	v_fmac_f32_e32 v71, v109, v43
	v_fmac_f32_e32 v71, v110, v44
	v_fmac_f32_e32 v71, v111, v45
	ds_read_b128 v[108:111], v113 offset:18592
	s_waitcnt lgkmcnt(3)
	v_fmac_f32_e32 v72, v90, v42
	v_fmac_f32_e32 v72, v91, v43
	v_fmac_f32_e32 v72, v92, v44
	v_fmac_f32_e32 v72, v93, v45
	ds_read_b128 v[90:93], v113 offset:20640
	s_waitcnt lgkmcnt(3)
	v_fmac_f32_e32 v73, v94, v42
	v_fmac_f32_e32 v73, v95, v43
	v_fmac_f32_e32 v73, v96, v44
	v_fmac_f32_e32 v73, v97, v45
	ds_read_b128 v[94:97], v113 offset:22688
	s_waitcnt lgkmcnt(3)
	v_fmac_f32_e32 v74, v98, v42
	v_fmac_f32_e32 v74, v99, v43
	v_fmac_f32_e32 v74, v100, v44
	v_fmac_f32_e32 v74, v101, v45
	ds_read_b128 v[98:101], v113 offset:24736
	s_waitcnt lgkmcnt(3)
	v_fmac_f32_e32 v75, v108, v42
	v_fmac_f32_e32 v75, v109, v43
	v_fmac_f32_e32 v75, v110, v44
	v_fmac_f32_e32 v75, v111, v45
	ds_read_b128 v[108:111], v113 offset:26784
	s_waitcnt lgkmcnt(3)
; DI void gemv17(const float* in16, int istride, const float* in1, bool do_silu, const float* W, int ldw, int n0,
;                const float* bvec, float* out, int ostride, char* lds) {
;     ...
; #pragma unroll 16
;     for (int kk = 0; kk < 64; ++kk) {
;       const float wv = wp[(size_t)kk * ldw];
;       const float* sp = sc + kp * 64 + kk;
; #pragma unroll
;       for (int j = 0; j < 17; ++j) acc[j] += sp[j * 512] * wv;
;     }
	v_fmac_f32_e32 v76, v90, v42
	v_fmac_f32_e32 v76, v91, v43
	v_fmac_f32_e32 v76, v92, v44
	v_fmac_f32_e32 v76, v93, v45
	ds_read_b128 v[90:93], v113 offset:28832
	s_waitcnt lgkmcnt(3)
	v_fmac_f32_e32 v77, v94, v42
	v_fmac_f32_e32 v77, v95, v43
	v_fmac_f32_e32 v77, v96, v44
	v_fmac_f32_e32 v77, v97, v45
	ds_read_b128 v[94:97], v113 offset:30880
	s_waitcnt lgkmcnt(3)
	v_fmac_f32_e32 v78, v98, v42
	v_fmac_f32_e32 v78, v99, v43
	v_fmac_f32_e32 v78, v100, v44
	v_fmac_f32_e32 v78, v101, v45
	ds_read_b128 v[98:101], v113 offset:32928
	s_waitcnt lgkmcnt(3)
	v_fmac_f32_e32 v79, v108, v42
	v_fmac_f32_e32 v79, v109, v43
	v_fmac_f32_e32 v79, v110, v44
	v_fmac_f32_e32 v79, v111, v45
	ds_read_b128 v[108:111], v113 offset:176
	s_waitcnt lgkmcnt(3)
	v_fmac_f32_e32 v80, v90, v42
	v_fmac_f32_e32 v80, v91, v43
	v_fmac_f32_e32 v80, v92, v44
	v_fmac_f32_e32 v80, v93, v45
	ds_read_b128 v[90:93], v113 offset:2224
	s_waitcnt lgkmcnt(3)
	v_fmac_f32_e32 v81, v94, v42
	v_fmac_f32_e32 v81, v95, v43
	v_fmac_f32_e32 v81, v96, v44
	v_fmac_f32_e32 v81, v97, v45
	ds_read_b128 v[94:97], v113 offset:4272
	s_waitcnt lgkmcnt(3)
	v_fmac_f32_e32 v89, v98, v42
	v_fmac_f32_e32 v89, v99, v43
	v_fmac_f32_e32 v89, v100, v44
	v_fmac_f32_e32 v89, v101, v45
	ds_read_b128 v[98:101], v113 offset:6320
	s_waitcnt vmcnt(16)
	s_waitcnt lgkmcnt(3)
	v_fmac_f32_e32 v66, v108, v46
	v_fmac_f32_e32 v66, v109, v47
	v_fmac_f32_e32 v66, v110, v48
	v_fmac_f32_e32 v66, v111, v49
	ds_read_b128 v[108:111], v113 offset:8368
	s_waitcnt lgkmcnt(3)
	v_fmac_f32_e32 v67, v90, v46
	v_fmac_f32_e32 v67, v91, v47
	v_fmac_f32_e32 v67, v92, v48
	v_fmac_f32_e32 v67, v93, v49
	ds_read_b128 v[90:93], v113 offset:10416
	s_waitcnt lgkmcnt(3)
	v_fmac_f32_e32 v68, v94, v46
	v_fmac_f32_e32 v68, v95, v47
	v_fmac_f32_e32 v68, v96, v48
	v_fmac_f32_e32 v68, v97, v49
	ds_read_b128 v[94:97], v113 offset:12464
	s_waitcnt lgkmcnt(3)
	v_fmac_f32_e32 v69, v98, v46
	v_fmac_f32_e32 v69, v99, v47
	v_fmac_f32_e32 v69, v100, v48
	v_fmac_f32_e32 v69, v101, v49
	ds_read_b128 v[98:101], v113 offset:14512
	s_waitcnt lgkmcnt(3)
	v_fmac_f32_e32 v70, v108, v46
	v_fmac_f32_e32 v70, v109, v47
	v_fmac_f32_e32 v70, v110, v48
	v_fmac_f32_e32 v70, v111, v49
	ds_read_b128 v[108:111], v113 offset:16560
	s_waitcnt lgkmcnt(3)
	v_fmac_f32_e32 v71, v90, v46
	v_fmac_f32_e32 v71, v91, v47
	v_fmac_f32_e32 v71, v92, v48
	v_fmac_f32_e32 v71, v93, v49
	ds_read_b128 v[90:93], v113 offset:18608
	s_waitcnt lgkmcnt(3)
	v_fmac_f32_e32 v72, v94, v46
	v_fmac_f32_e32 v72, v95, v47
	v_fmac_f32_e32 v72, v96, v48
	v_fmac_f32_e32 v72, v97, v49
	ds_read_b128 v[94:97], v113 offset:20656
	s_waitcnt lgkmcnt(3)
	v_fmac_f32_e32 v73, v98, v46
	v_fmac_f32_e32 v73, v99, v47
	v_fmac_f32_e32 v73, v100, v48
	v_fmac_f32_e32 v73, v101, v49
	ds_read_b128 v[98:101], v113 offset:22704
	s_waitcnt lgkmcnt(3)
	v_fmac_f32_e32 v74, v108, v46
	v_fmac_f32_e32 v74, v109, v47
	v_fmac_f32_e32 v74, v110, v48
	v_fmac_f32_e32 v74, v111, v49
	ds_read_b128 v[108:111], v113 offset:24752
	s_waitcnt lgkmcnt(3)
	v_fmac_f32_e32 v75, v90, v46
	v_fmac_f32_e32 v75, v91, v47
	v_fmac_f32_e32 v75, v92, v48
	v_fmac_f32_e32 v75, v93, v49
	ds_read_b128 v[90:93], v113 offset:26800
	s_waitcnt lgkmcnt(3)
	v_fmac_f32_e32 v76, v94, v46
	v_fmac_f32_e32 v76, v95, v47
	v_fmac_f32_e32 v76, v96, v48
	v_fmac_f32_e32 v76, v97, v49
	ds_read_b128 v[94:97], v113 offset:28848
	s_waitcnt lgkmcnt(3)
	v_fmac_f32_e32 v77, v98, v46
	v_fmac_f32_e32 v77, v99, v47
	v_fmac_f32_e32 v77, v100, v48
	v_fmac_f32_e32 v77, v101, v49
	ds_read_b128 v[98:101], v113 offset:30896
	s_waitcnt lgkmcnt(3)
	v_fmac_f32_e32 v78, v108, v46
	v_fmac_f32_e32 v78, v109, v47
	v_fmac_f32_e32 v78, v110, v48
	v_fmac_f32_e32 v78, v111, v49
	ds_read_b128 v[108:111], v113 offset:32944
	s_waitcnt lgkmcnt(3)
	v_fmac_f32_e32 v79, v90, v46
	v_fmac_f32_e32 v79, v91, v47
	v_fmac_f32_e32 v79, v92, v48
	v_fmac_f32_e32 v79, v93, v49
	ds_read_b128 v[90:93], v113 offset:192
	s_waitcnt lgkmcnt(3)
	v_fmac_f32_e32 v80, v94, v46
	v_fmac_f32_e32 v80, v95, v47
	v_fmac_f32_e32 v80, v96, v48
	v_fmac_f32_e32 v80, v97, v49
	ds_read_b128 v[94:97], v113 offset:2240
	s_waitcnt lgkmcnt(3)
	v_fmac_f32_e32 v81, v98, v46
	v_fmac_f32_e32 v81, v99, v47
	v_fmac_f32_e32 v81, v100, v48
	v_fmac_f32_e32 v81, v101, v49
	ds_read_b128 v[98:101], v113 offset:4288
	s_waitcnt lgkmcnt(3)
	v_fmac_f32_e32 v89, v108, v46
	v_fmac_f32_e32 v89, v109, v47
	v_fmac_f32_e32 v89, v110, v48
	v_fmac_f32_e32 v89, v111, v49
	ds_read_b128 v[108:111], v113 offset:6336
	s_waitcnt vmcnt(12)
	s_waitcnt lgkmcnt(3)
	v_fmac_f32_e32 v66, v90, v50
	v_fmac_f32_e32 v66, v91, v51
	v_fmac_f32_e32 v66, v92, v52
	v_fmac_f32_e32 v66, v93, v53
	ds_read_b128 v[90:93], v113 offset:8384
	s_waitcnt lgkmcnt(3)
	v_fmac_f32_e32 v67, v94, v50
	v_fmac_f32_e32 v67, v95, v51
	v_fmac_f32_e32 v67, v96, v52
	v_fmac_f32_e32 v67, v97, v53
	ds_read_b128 v[94:97], v113 offset:10432
	s_waitcnt lgkmcnt(3)
	v_fmac_f32_e32 v68, v98, v50
	v_fmac_f32_e32 v68, v99, v51
	v_fmac_f32_e32 v68, v100, v52
	v_fmac_f32_e32 v68, v101, v53
	ds_read_b128 v[98:101], v113 offset:12480
	s_waitcnt lgkmcnt(3)
	v_fmac_f32_e32 v69, v108, v50
	v_fmac_f32_e32 v69, v109, v51
	v_fmac_f32_e32 v69, v110, v52
	v_fmac_f32_e32 v69, v111, v53
	ds_read_b128 v[108:111], v113 offset:14528
	s_waitcnt lgkmcnt(3)
	v_fmac_f32_e32 v70, v90, v50
	v_fmac_f32_e32 v70, v91, v51
	v_fmac_f32_e32 v70, v92, v52
	v_fmac_f32_e32 v70, v93, v53
	ds_read_b128 v[90:93], v113 offset:16576
	s_waitcnt lgkmcnt(3)
	v_fmac_f32_e32 v71, v94, v50
	v_fmac_f32_e32 v71, v95, v51
	v_fmac_f32_e32 v71, v96, v52
	v_fmac_f32_e32 v71, v97, v53
	ds_read_b128 v[94:97], v113 offset:18624
	s_waitcnt lgkmcnt(3)
; DI void gemv17(const float* in16, int istride, const float* in1, bool do_silu, const float* W, int ldw, int n0,
;                const float* bvec, float* out, int ostride, char* lds) {
;     ...
; #pragma unroll 16
;     for (int kk = 0; kk < 64; ++kk) {
;       const float wv = wp[(size_t)kk * ldw];
;       const float* sp = sc + kp * 64 + kk;
; #pragma unroll
;       for (int j = 0; j < 17; ++j) acc[j] += sp[j * 512] * wv;
;     }
	v_fmac_f32_e32 v72, v98, v50
	v_fmac_f32_e32 v72, v99, v51
	v_fmac_f32_e32 v72, v100, v52
	v_fmac_f32_e32 v72, v101, v53
	ds_read_b128 v[98:101], v113 offset:20672
	s_waitcnt lgkmcnt(3)
	v_fmac_f32_e32 v73, v108, v50
	v_fmac_f32_e32 v73, v109, v51
	v_fmac_f32_e32 v73, v110, v52
	v_fmac_f32_e32 v73, v111, v53
	ds_read_b128 v[108:111], v113 offset:22720
	s_waitcnt lgkmcnt(3)
	v_fmac_f32_e32 v74, v90, v50
	v_fmac_f32_e32 v74, v91, v51
	v_fmac_f32_e32 v74, v92, v52
	v_fmac_f32_e32 v74, v93, v53
	ds_read_b128 v[90:93], v113 offset:24768
	s_waitcnt lgkmcnt(3)
	v_fmac_f32_e32 v75, v94, v50
	v_fmac_f32_e32 v75, v95, v51
	v_fmac_f32_e32 v75, v96, v52
	v_fmac_f32_e32 v75, v97, v53
	ds_read_b128 v[94:97], v113 offset:26816
	s_waitcnt lgkmcnt(3)
	v_fmac_f32_e32 v76, v98, v50
	v_fmac_f32_e32 v76, v99, v51
	v_fmac_f32_e32 v76, v100, v52
	v_fmac_f32_e32 v76, v101, v53
	ds_read_b128 v[98:101], v113 offset:28864
	s_waitcnt lgkmcnt(3)
	v_fmac_f32_e32 v77, v108, v50
	v_fmac_f32_e32 v77, v109, v51
	v_fmac_f32_e32 v77, v110, v52
	v_fmac_f32_e32 v77, v111, v53
	ds_read_b128 v[108:111], v113 offset:30912
	s_waitcnt lgkmcnt(3)
	v_fmac_f32_e32 v78, v90, v50
	v_fmac_f32_e32 v78, v91, v51
	v_fmac_f32_e32 v78, v92, v52
	v_fmac_f32_e32 v78, v93, v53
	ds_read_b128 v[90:93], v113 offset:32960
	s_waitcnt lgkmcnt(3)
	v_fmac_f32_e32 v79, v94, v50
	v_fmac_f32_e32 v79, v95, v51
	v_fmac_f32_e32 v79, v96, v52
	v_fmac_f32_e32 v79, v97, v53
	ds_read_b128 v[94:97], v113 offset:208
	s_waitcnt lgkmcnt(3)
	v_fmac_f32_e32 v80, v98, v50
	v_fmac_f32_e32 v80, v99, v51
	v_fmac_f32_e32 v80, v100, v52
	v_fmac_f32_e32 v80, v101, v53
	ds_read_b128 v[98:101], v113 offset:2256
	s_waitcnt lgkmcnt(3)
	v_fmac_f32_e32 v81, v108, v50
	v_fmac_f32_e32 v81, v109, v51
	v_fmac_f32_e32 v81, v110, v52
	v_fmac_f32_e32 v81, v111, v53
	ds_read_b128 v[108:111], v113 offset:4304
	s_waitcnt lgkmcnt(3)
	v_fmac_f32_e32 v89, v90, v50
	v_fmac_f32_e32 v89, v91, v51
	v_fmac_f32_e32 v89, v92, v52
	v_fmac_f32_e32 v89, v93, v53
	ds_read_b128 v[90:93], v113 offset:6352
	s_waitcnt vmcnt(8)
	s_waitcnt lgkmcnt(3)
	v_fmac_f32_e32 v66, v94, v54
	v_fmac_f32_e32 v66, v95, v55
	v_fmac_f32_e32 v66, v96, v56
	v_fmac_f32_e32 v66, v97, v57
	ds_read_b128 v[94:97], v113 offset:8400
	s_waitcnt lgkmcnt(3)
	v_fmac_f32_e32 v67, v98, v54
	v_fmac_f32_e32 v67, v99, v55
	v_fmac_f32_e32 v67, v100, v56
	v_fmac_f32_e32 v67, v101, v57
	ds_read_b128 v[98:101], v113 offset:10448
	s_waitcnt lgkmcnt(3)
	v_fmac_f32_e32 v68, v108, v54
	v_fmac_f32_e32 v68, v109, v55
	v_fmac_f32_e32 v68, v110, v56
	v_fmac_f32_e32 v68, v111, v57
	ds_read_b128 v[108:111], v113 offset:12496
	s_waitcnt lgkmcnt(3)
	v_fmac_f32_e32 v69, v90, v54
	v_fmac_f32_e32 v69, v91, v55
	v_fmac_f32_e32 v69, v92, v56
	v_fmac_f32_e32 v69, v93, v57
	ds_read_b128 v[90:93], v113 offset:14544
	s_waitcnt lgkmcnt(3)
	v_fmac_f32_e32 v70, v94, v54
	v_fmac_f32_e32 v70, v95, v55
	v_fmac_f32_e32 v70, v96, v56
	v_fmac_f32_e32 v70, v97, v57
	ds_read_b128 v[94:97], v113 offset:16592
	s_waitcnt lgkmcnt(3)
	v_fmac_f32_e32 v71, v98, v54
	v_fmac_f32_e32 v71, v99, v55
	v_fmac_f32_e32 v71, v100, v56
	v_fmac_f32_e32 v71, v101, v57
	ds_read_b128 v[98:101], v113 offset:18640
	s_waitcnt lgkmcnt(3)
	v_fmac_f32_e32 v72, v108, v54
	v_fmac_f32_e32 v72, v109, v55
	v_fmac_f32_e32 v72, v110, v56
	v_fmac_f32_e32 v72, v111, v57
	ds_read_b128 v[108:111], v113 offset:20688
	s_waitcnt lgkmcnt(3)
	v_fmac_f32_e32 v73, v90, v54
	v_fmac_f32_e32 v73, v91, v55
	v_fmac_f32_e32 v73, v92, v56
	v_fmac_f32_e32 v73, v93, v57
	ds_read_b128 v[90:93], v113 offset:22736
	s_waitcnt lgkmcnt(3)
	v_fmac_f32_e32 v74, v94, v54
	v_fmac_f32_e32 v74, v95, v55
	v_fmac_f32_e32 v74, v96, v56
	v_fmac_f32_e32 v74, v97, v57
	ds_read_b128 v[94:97], v113 offset:24784
	s_waitcnt lgkmcnt(3)
	v_fmac_f32_e32 v75, v98, v54
	v_fmac_f32_e32 v75, v99, v55
	v_fmac_f32_e32 v75, v100, v56
	v_fmac_f32_e32 v75, v101, v57
	ds_read_b128 v[98:101], v113 offset:26832
	s_waitcnt lgkmcnt(3)
	v_fmac_f32_e32 v76, v108, v54
	v_fmac_f32_e32 v76, v109, v55
	v_fmac_f32_e32 v76, v110, v56
	v_fmac_f32_e32 v76, v111, v57
	ds_read_b128 v[108:111], v113 offset:28880
	s_waitcnt lgkmcnt(3)
	v_fmac_f32_e32 v77, v90, v54
	v_fmac_f32_e32 v77, v91, v55
	v_fmac_f32_e32 v77, v92, v56
	v_fmac_f32_e32 v77, v93, v57
	ds_read_b128 v[90:93], v113 offset:30928
	s_waitcnt lgkmcnt(3)
	v_fmac_f32_e32 v78, v94, v54
	v_fmac_f32_e32 v78, v95, v55
	v_fmac_f32_e32 v78, v96, v56
	v_fmac_f32_e32 v78, v97, v57
	ds_read_b128 v[94:97], v113 offset:32976
	s_waitcnt lgkmcnt(3)
	v_fmac_f32_e32 v79, v98, v54
	v_fmac_f32_e32 v79, v99, v55
	v_fmac_f32_e32 v79, v100, v56
	v_fmac_f32_e32 v79, v101, v57
	ds_read_b128 v[98:101], v113 offset:224
	s_waitcnt lgkmcnt(3)
	v_fmac_f32_e32 v80, v108, v54
	v_fmac_f32_e32 v80, v109, v55
	v_fmac_f32_e32 v80, v110, v56
	v_fmac_f32_e32 v80, v111, v57
	ds_read_b128 v[108:111], v113 offset:2272
	s_waitcnt lgkmcnt(3)
	v_fmac_f32_e32 v81, v90, v54
	v_fmac_f32_e32 v81, v91, v55
	v_fmac_f32_e32 v81, v92, v56
	v_fmac_f32_e32 v81, v93, v57
	ds_read_b128 v[90:93], v113 offset:4320
	s_waitcnt lgkmcnt(3)
	v_fmac_f32_e32 v89, v94, v54
	v_fmac_f32_e32 v89, v95, v55
	v_fmac_f32_e32 v89, v96, v56
	v_fmac_f32_e32 v89, v97, v57
	ds_read_b128 v[94:97], v113 offset:6368
	s_waitcnt vmcnt(4)
	s_waitcnt lgkmcnt(3)
	v_fmac_f32_e32 v66, v98, v58
	v_fmac_f32_e32 v66, v99, v59
	v_fmac_f32_e32 v66, v100, v60
	v_fmac_f32_e32 v66, v101, v61
	ds_read_b128 v[98:101], v113 offset:8416
	s_waitcnt lgkmcnt(3)
	v_fmac_f32_e32 v67, v108, v58
	v_fmac_f32_e32 v67, v109, v59
	v_fmac_f32_e32 v67, v110, v60
	v_fmac_f32_e32 v67, v111, v61
	ds_read_b128 v[108:111], v113 offset:10464
	s_waitcnt lgkmcnt(3)
; DI void gemv17(const float* in16, int istride, const float* in1, bool do_silu, const float* W, int ldw, int n0,
;                const float* bvec, float* out, int ostride, char* lds) {
;     ...
; #pragma unroll 16
;     for (int kk = 0; kk < 64; ++kk) {
;       const float wv = wp[(size_t)kk * ldw];
;       const float* sp = sc + kp * 64 + kk;
; #pragma unroll
;       for (int j = 0; j < 17; ++j) acc[j] += sp[j * 512] * wv;
;     }
;   }
	v_fmac_f32_e32 v68, v90, v58
	v_fmac_f32_e32 v68, v91, v59
	v_fmac_f32_e32 v68, v92, v60
	v_fmac_f32_e32 v68, v93, v61
	ds_read_b128 v[90:93], v113 offset:12512
	s_waitcnt lgkmcnt(3)
	v_fmac_f32_e32 v69, v94, v58
	v_fmac_f32_e32 v69, v95, v59
	v_fmac_f32_e32 v69, v96, v60
	v_fmac_f32_e32 v69, v97, v61
	ds_read_b128 v[94:97], v113 offset:14560
	s_waitcnt lgkmcnt(3)
	v_fmac_f32_e32 v70, v98, v58
	v_fmac_f32_e32 v70, v99, v59
	v_fmac_f32_e32 v70, v100, v60
	v_fmac_f32_e32 v70, v101, v61
	ds_read_b128 v[98:101], v113 offset:16608
	s_waitcnt lgkmcnt(3)
	v_fmac_f32_e32 v71, v108, v58
	v_fmac_f32_e32 v71, v109, v59
	v_fmac_f32_e32 v71, v110, v60
	v_fmac_f32_e32 v71, v111, v61
	ds_read_b128 v[108:111], v113 offset:18656
	s_waitcnt lgkmcnt(3)
	v_fmac_f32_e32 v72, v90, v58
	v_fmac_f32_e32 v72, v91, v59
	v_fmac_f32_e32 v72, v92, v60
	v_fmac_f32_e32 v72, v93, v61
	ds_read_b128 v[90:93], v113 offset:20704
	s_waitcnt lgkmcnt(3)
	v_fmac_f32_e32 v73, v94, v58
	v_fmac_f32_e32 v73, v95, v59
	v_fmac_f32_e32 v73, v96, v60
	v_fmac_f32_e32 v73, v97, v61
	ds_read_b128 v[94:97], v113 offset:22752
	s_waitcnt lgkmcnt(3)
	v_fmac_f32_e32 v74, v98, v58
	v_fmac_f32_e32 v74, v99, v59
	v_fmac_f32_e32 v74, v100, v60
	v_fmac_f32_e32 v74, v101, v61
	ds_read_b128 v[98:101], v113 offset:24800
	s_waitcnt lgkmcnt(3)
	v_fmac_f32_e32 v75, v108, v58
	v_fmac_f32_e32 v75, v109, v59
	v_fmac_f32_e32 v75, v110, v60
	v_fmac_f32_e32 v75, v111, v61
	ds_read_b128 v[108:111], v113 offset:26848
	s_waitcnt lgkmcnt(3)
	v_fmac_f32_e32 v76, v90, v58
	v_fmac_f32_e32 v76, v91, v59
	v_fmac_f32_e32 v76, v92, v60
	v_fmac_f32_e32 v76, v93, v61
	ds_read_b128 v[90:93], v113 offset:28896
	s_waitcnt lgkmcnt(3)
	v_fmac_f32_e32 v77, v94, v58
	v_fmac_f32_e32 v77, v95, v59
	v_fmac_f32_e32 v77, v96, v60
	v_fmac_f32_e32 v77, v97, v61
	ds_read_b128 v[94:97], v113 offset:30944
	s_waitcnt lgkmcnt(3)
	v_fmac_f32_e32 v78, v98, v58
	v_fmac_f32_e32 v78, v99, v59
	v_fmac_f32_e32 v78, v100, v60
	v_fmac_f32_e32 v78, v101, v61
	ds_read_b128 v[98:101], v113 offset:32992
	s_waitcnt lgkmcnt(3)
	v_fmac_f32_e32 v79, v108, v58
	v_fmac_f32_e32 v79, v109, v59
	v_fmac_f32_e32 v79, v110, v60
	v_fmac_f32_e32 v79, v111, v61
	ds_read_b128 v[108:111], v113 offset:240
	s_waitcnt lgkmcnt(3)
	v_fmac_f32_e32 v80, v90, v58
	v_fmac_f32_e32 v80, v91, v59
	v_fmac_f32_e32 v80, v92, v60
	v_fmac_f32_e32 v80, v93, v61
	ds_read_b128 v[90:93], v113 offset:2288
	s_waitcnt lgkmcnt(3)
	v_fmac_f32_e32 v81, v94, v58
	v_fmac_f32_e32 v81, v95, v59
	v_fmac_f32_e32 v81, v96, v60
	v_fmac_f32_e32 v81, v97, v61
	ds_read_b128 v[94:97], v113 offset:4336
	s_waitcnt lgkmcnt(3)
	v_fmac_f32_e32 v89, v98, v58
	v_fmac_f32_e32 v89, v99, v59
	v_fmac_f32_e32 v89, v100, v60
	v_fmac_f32_e32 v89, v101, v61
	ds_read_b128 v[98:101], v113 offset:6384
	s_waitcnt vmcnt(0)
	s_waitcnt lgkmcnt(3)
	v_fmac_f32_e32 v66, v108, v62
	v_fmac_f32_e32 v66, v109, v63
	v_fmac_f32_e32 v66, v110, v64
	v_fmac_f32_e32 v66, v111, v65
	ds_read_b128 v[108:111], v113 offset:8432
	s_waitcnt lgkmcnt(3)
	v_fmac_f32_e32 v67, v90, v62
	v_fmac_f32_e32 v67, v91, v63
	v_fmac_f32_e32 v67, v92, v64
	v_fmac_f32_e32 v67, v93, v65
	ds_read_b128 v[90:93], v113 offset:10480
	s_waitcnt lgkmcnt(3)
	v_fmac_f32_e32 v68, v94, v62
	v_fmac_f32_e32 v68, v95, v63
	v_fmac_f32_e32 v68, v96, v64
	v_fmac_f32_e32 v68, v97, v65
	ds_read_b128 v[94:97], v113 offset:12528
	s_waitcnt lgkmcnt(3)
	v_fmac_f32_e32 v69, v98, v62
	v_fmac_f32_e32 v69, v99, v63
	v_fmac_f32_e32 v69, v100, v64
	v_fmac_f32_e32 v69, v101, v65
	ds_read_b128 v[98:101], v113 offset:14576
	s_waitcnt lgkmcnt(3)
	v_fmac_f32_e32 v70, v108, v62
	v_fmac_f32_e32 v70, v109, v63
	v_fmac_f32_e32 v70, v110, v64
	v_fmac_f32_e32 v70, v111, v65
	ds_read_b128 v[108:111], v113 offset:16624
	s_waitcnt lgkmcnt(3)
	v_fmac_f32_e32 v71, v90, v62
	v_fmac_f32_e32 v71, v91, v63
	v_fmac_f32_e32 v71, v92, v64
	v_fmac_f32_e32 v71, v93, v65
	ds_read_b128 v[90:93], v113 offset:18672
	s_waitcnt lgkmcnt(3)
	v_fmac_f32_e32 v72, v94, v62
	v_fmac_f32_e32 v72, v95, v63
	v_fmac_f32_e32 v72, v96, v64
	v_fmac_f32_e32 v72, v97, v65
	ds_read_b128 v[94:97], v113 offset:20720
	s_waitcnt lgkmcnt(3)
	v_fmac_f32_e32 v73, v98, v62
	v_fmac_f32_e32 v73, v99, v63
	v_fmac_f32_e32 v73, v100, v64
	v_fmac_f32_e32 v73, v101, v65
	ds_read_b128 v[98:101], v113 offset:22768
	s_waitcnt lgkmcnt(3)
	v_fmac_f32_e32 v74, v108, v62
	v_fmac_f32_e32 v74, v109, v63
	v_fmac_f32_e32 v74, v110, v64
	v_fmac_f32_e32 v74, v111, v65
	ds_read_b128 v[108:111], v113 offset:24816
	s_waitcnt lgkmcnt(3)
	v_fmac_f32_e32 v75, v90, v62
	v_fmac_f32_e32 v75, v91, v63
	v_fmac_f32_e32 v75, v92, v64
	v_fmac_f32_e32 v75, v93, v65
	ds_read_b128 v[90:93], v113 offset:26864
	s_waitcnt lgkmcnt(3)
	v_fmac_f32_e32 v76, v94, v62
	v_fmac_f32_e32 v76, v95, v63
	v_fmac_f32_e32 v76, v96, v64
	v_fmac_f32_e32 v76, v97, v65
	ds_read_b128 v[94:97], v113 offset:28912
	s_waitcnt lgkmcnt(3)
	v_fmac_f32_e32 v77, v98, v62
	v_fmac_f32_e32 v77, v99, v63
	v_fmac_f32_e32 v77, v100, v64
	v_fmac_f32_e32 v77, v101, v65
	ds_read_b128 v[98:101], v113 offset:30960
	s_waitcnt lgkmcnt(3)
	v_fmac_f32_e32 v78, v108, v62
	v_fmac_f32_e32 v78, v109, v63
	v_fmac_f32_e32 v78, v110, v64
	v_fmac_f32_e32 v78, v111, v65
	ds_read_b128 v[108:111], v113 offset:33008
	s_waitcnt lgkmcnt(3)
	v_fmac_f32_e32 v79, v90, v62
	v_fmac_f32_e32 v79, v91, v63
	v_fmac_f32_e32 v79, v92, v64
	v_fmac_f32_e32 v79, v93, v65
	s_waitcnt lgkmcnt(2)
	v_fmac_f32_e32 v80, v94, v62
	v_fmac_f32_e32 v80, v95, v63
	v_fmac_f32_e32 v80, v96, v64
	v_fmac_f32_e32 v80, v97, v65
	s_waitcnt lgkmcnt(1)
	v_fmac_f32_e32 v81, v98, v62
	v_fmac_f32_e32 v81, v99, v63
	v_fmac_f32_e32 v81, v100, v64
	v_fmac_f32_e32 v81, v101, v65
	s_waitcnt lgkmcnt(0)
	v_fmac_f32_e32 v89, v108, v62
	v_fmac_f32_e32 v89, v109, v63
	v_fmac_f32_e32 v89, v110, v64
	v_fmac_f32_e32 v89, v111, v65
	s_add_u32 s36, s36, 0x800
	s_addc_u32 s37, s37, 0
	s_add_u32 s38, s38, 0x800
	s_addc_u32 s39, s39, 0
	s_add_u32 s40, s40, 6291456
	s_addc_u32 s41, s41, 0
	s_add_i32 s47, s47, 1
	s_cmp_lt_u32 s47, 2
	s_cbranch_scc1 .Lgv_mod_kh
; DI void gemv17(const float* in16, int istride, const float* in1, bool do_silu, const float* W, int ldw, int n0,
;                const float* bvec, float* out, int ostride, char* lds) {
;     ...
; #pragma unroll
;   for (int j = 0; j < 17; ++j) red[(kp * 17 + j) * 64 + col] = acc[j];
;   __syncthreads();
;   for (int e = tid; e < 17 * 64; e += NTHREADS) {
;     const int j = e >> 6, cc = e & 63;
;     float v = ((red[(0 * 17 + j) * 64 + cc] + red[(1 * 17 + j) * 64 + cc]) +
;                (red[(2 * 17 + j) * 64 + cc] + red[(3 * 17 + j) * 64 + cc])) +
;               ((red[(4 * 17 + j) * 64 + cc] + red[(5 * 17 + j) * 64 + cc]) +
;                (red[(6 * 17 + j) * 64 + cc] + red[(7 * 17 + j) * 64 + cc]));
;     if (bvec) v += bvec[n0 + cc];
;     out[(size_t)j * ostride + n0 + cc] = v;
;   }
;   __syncthreads();
	v_lshrrev_b32_e32 v0, 6, v251
	v_mul_u32_u24_e32 v90, 0x1100, v0
	v_and_b32_e32 v91, 63, v251
	v_lshlrev_b32_e32 v91, 2, v91
	v_add_u32_e32 v90, v90, v91
	v_add_u32_e32 v90, 0x8800, v90
	ds_write_b32 v90, v66
	ds_write_b32 v90, v67 offset:256
	ds_write_b32 v90, v68 offset:512
	ds_write_b32 v90, v69 offset:768
	ds_write_b32 v90, v70 offset:1024
	ds_write_b32 v90, v71 offset:1280
	ds_write_b32 v90, v72 offset:1536
	ds_write_b32 v90, v73 offset:1792
	ds_write_b32 v90, v74 offset:2048
	ds_write_b32 v90, v75 offset:2304
	ds_write_b32 v90, v76 offset:2560
	ds_write_b32 v90, v77 offset:2816
	ds_write_b32 v90, v78 offset:3072
	ds_write_b32 v90, v79 offset:3328
	ds_write_b32 v90, v80 offset:3584
	ds_write_b32 v90, v81 offset:3840
	ds_write_b32 v90, v89 offset:4096
	s_waitcnt lgkmcnt(0)
	s_barrier
	v_lshlrev_b32_e32 v90, 8, v0
	v_add_u32_e32 v90, v90, v91
	v_add_u32_e32 v90, 0x8800, v90
	s_mul_i32 s3, s46, 12288
	s_add_u32 s44, s44, s3
	s_addc_u32 s45, s45, 0
	ds_read_b32 v92, v90 offset:0
	ds_read_b32 v93, v90 offset:4352
	ds_read_b32 v94, v90 offset:8704
	ds_read_b32 v95, v90 offset:13056
	ds_read_b32 v96, v90 offset:17408
	ds_read_b32 v97, v90 offset:21760
	ds_read_b32 v98, v90 offset:26112
	ds_read_b32 v99, v90 offset:30464
	global_load_dword v100, v91, s[42:43]
	s_waitcnt lgkmcnt(0)
	v_add_f32_e32 v92, v92, v93
	v_add_f32_e32 v94, v94, v95
	v_add_f32_e32 v96, v96, v97
	v_add_f32_e32 v98, v98, v99
	v_add_f32_e32 v92, v92, v94
	v_add_f32_e32 v96, v96, v98
	v_add_f32_e32 v92, v92, v96
	s_waitcnt vmcnt(0)
	v_add_f32_e32 v92, v92, v100
	global_store_dword v91, v92, s[44:45]
	s_add_u32 s44, s44, 98304
	s_addc_u32 s45, s45, 0
	ds_read_b32 v92, v90 offset:2048
	ds_read_b32 v93, v90 offset:6400
	ds_read_b32 v94, v90 offset:10752
	ds_read_b32 v95, v90 offset:15104
	ds_read_b32 v96, v90 offset:19456
	ds_read_b32 v97, v90 offset:23808
	ds_read_b32 v98, v90 offset:28160
	ds_read_b32 v99, v90 offset:32512
	global_load_dword v100, v91, s[42:43]
	s_waitcnt lgkmcnt(0)
	v_add_f32_e32 v92, v92, v93
	v_add_f32_e32 v94, v94, v95
	v_add_f32_e32 v96, v96, v97
	v_add_f32_e32 v98, v98, v99
	v_add_f32_e32 v92, v92, v94
	v_add_f32_e32 v96, v96, v98
	v_add_f32_e32 v92, v92, v96
	s_waitcnt vmcnt(0)
	v_add_f32_e32 v92, v92, v100
	global_store_dword v91, v92, s[44:45]
	s_add_u32 s44, s44, 98304
	s_addc_u32 s45, s45, 0
	s_cmp_lg_u32 s46, 0
	s_cbranch_scc1 .Lgv_mod_done
	ds_read_b32 v92, v90 offset:4096
	ds_read_b32 v93, v90 offset:8448
	ds_read_b32 v94, v90 offset:12800
	ds_read_b32 v95, v90 offset:17152
	ds_read_b32 v96, v90 offset:21504
	ds_read_b32 v97, v90 offset:25856
	ds_read_b32 v98, v90 offset:30208
	ds_read_b32 v99, v90 offset:34560
	global_load_dword v100, v91, s[42:43]
	s_waitcnt lgkmcnt(0)
	v_add_f32_e32 v92, v92, v93
	v_add_f32_e32 v94, v94, v95
	v_add_f32_e32 v96, v96, v97
	v_add_f32_e32 v98, v98, v99
	v_add_f32_e32 v92, v92, v94
	v_add_f32_e32 v96, v96, v98
	v_add_f32_e32 v92, v92, v96
	s_waitcnt vmcnt(0)
	v_add_f32_e32 v92, v92, v100
	global_store_dword v91, v92, s[44:45]
.Lgv_mod_done:
	s_barrier
	s_branch .LBB0_488
